# v043 + softmax row sums with packed adds in all four attention tile bodies (3 v_pk_add_f32 + 2 adds per unit instead of 8 adds; f32, association order only)
# baseline (speedup 1.0000x reference)
; __device__ __forceinline__ void drain_wait() { asm volatile("s_waitcnt vmcnt(0)" ::: "memory"); __syncthreads(); }
; __device__ __forceinline__ void swa_phase(LAS unsigned char* lds, const bf16_t* Q, const bf16_t* K, const bf16_t* V, bf16_t* Ob, const float* sink, float negb) {
;     ...
;     for (int it = 0;; ++it) {
;         const int item = item_of(it, SW_ITEMS, SW_ITEMS); if (item < 0) break;
;         const int b = item >> 8, kvh = (item >> 6) & 3, tb = item & 63;
;         const size_t ctx0 = (size_t)(MLAT + b * NCTX), lat0 = (size_t)(b * SEQ);
;         const int i_lo = tb == 0 ? 2 : 0, i_hi = tb == 63 ? 4 : 6;
;         const int NT = 4 + (i_hi - i_lo);
;         const DmaLane dl = dma_lane(256, kvh * 64, w, lane);
;     ...
;         dma_tile<1>(lds, K, V, SW_ROW0(0), 256, dl, w);
;         dma_tile<1>(lds + SW_BUF, K, V, SW_ROW0(1), 256, dl, w);
;         dma_tile<1>(lds + 2 * SW_BUF, K, V, SW_ROW0(2), 256, dl, w);
;         const int tq = 128 * tb + 16 * w;
;         const size_t qrow = (size_t)(b * SEQ + tq + l15);
;         bf16x8 qf[4][2];
; #pragma unroll
;         for (int grp = 0; grp < 4; ++grp)
; #pragma unroll
;             for (int ds = 0; ds < 2; ++ds) qf[grp][ds] = *(const bf16x8*)(Q + qrow * DM + (4 * kvh + grp) * 64 + 32 * ds + 8 * g);
;         f32x4 O[4][4]; float ls[4];
; #pragma unroll
;         for (int grp = 0; grp < 4; ++grp) { ls[grp] = 0.f;
; #pragma unroll
;             for (int db = 0; db < 4; ++db) O[grp][db] = (f32x4){0.f, 0.f, 0.f, 0.f}; }
;         drain_wait();
;         for (int t = 0; t < 4; ++t) {
;             dma_tile<1>(lds + ((t + 3) & 3) * SW_BUF, K, V, SW_ROW0(t + 3), 256, dl, w);
.LBB0_350:
	s_cmp_lt_i32 s6, 0
	s_cbranch_scc1 .LBB0_357
	s_and_b32 s0, s6, 0x7fffff00
	s_add_i32 s82, s0, 0x8000
	s_lshl_b32 s0, s6, 5
	s_bfe_u32 s42, s6, 0x20006
	s_and_b32 s12, s6, 63
	s_and_b32 s43, s0, 0x7fffe000
	s_cmp_eq_u32 s12, 0
	s_cselect_b32 s7, 2, 0
	s_cmp_eq_u32 s12, 63
	s_cselect_b32 s0, 4, 6
	s_sub_i32 s44, s0, s7
	s_lshl_b64 s[8:9], s[82:83], 9
	s_add_u32 s0, s67, s8
	s_addc_u32 s1, s4, s9
	v_lshl_or_b32 v4, s42, 7, v188
	s_add_u32 s10, s5, s8
	v_or_b32_e32 v212, v4, v189
	s_addc_u32 s11, s58, s9
	s_add_i32 s6, s40, 0x2000
	s_mov_b32 s13, m0
	s_mov_b32 m0, s40
	s_nop 0
	global_load_lds_dwordx4 v212, s[0:1]
	s_mov_b32 m0, s13
	v_or_b32_e32 v213, v4, v190
	s_mov_b32 s0, m0
	s_mov_b32 m0, s6
	s_nop 0
	global_load_lds_dwordx4 v213, s[10:11]
	s_mov_b32 m0, s0
	s_or_b32 s6, s8, 0x8000
	s_add_u32 s0, s67, s6
	s_addc_u32 s1, s4, s9
	s_add_u32 s10, s5, s6
	s_addc_u32 s11, s58, s9
	s_add_i32 s6, s40, 0x4000
	s_mov_b32 s14, m0
	s_mov_b32 m0, s6
	s_nop 0
	global_load_lds_dwordx4 v212, s[0:1]
	s_mov_b32 m0, s14
	s_add_i32 s13, s40, 0x6000
	s_mov_b32 s0, m0
	s_mov_b32 m0, s13
	s_nop 0
	global_load_lds_dwordx4 v213, s[10:11]
	s_mov_b32 m0, s0
	s_or_b32 s6, s8, 0x10000
	s_add_u32 s0, s67, s6
	s_addc_u32 s1, s4, s9
	s_add_u32 s10, s5, s6
	s_addc_u32 s11, s58, s9
	s_add_i32 s6, s40, 0x8000
	s_mov_b32 s14, m0
	s_mov_b32 m0, s6
	s_nop 0
	global_load_lds_dwordx4 v212, s[0:1]
	s_mov_b32 m0, s14
	s_add_i32 s13, s40, 0xa000
	s_mov_b32 s0, m0
	s_mov_b32 m0, s13
	s_nop 0
	global_load_lds_dwordx4 v213, s[10:11]
	s_mov_b32 m0, s0
	s_lshl_b32 s45, s12, 7
	s_add_i32 s0, s45, s39
	s_add_i32 s1, s0, s43
	v_or_b32_e32 v4, s1, v187
	v_ashrrev_i32_e32 v5, 31, v4
	v_lshlrev_b64 v[126:127], 11, v[4:5]
	v_lshl_add_u64 v[4:5], v[122:123], 0, v[126:127]
	s_lshl_b32 s36, s42, 9
	s_mov_b32 s37, s83
	v_lshl_add_u64 v[32:33], v[4:5], 0, s[36:37]
	global_load_dwordx4 v[4:7], v[32:33], off
	global_load_dwordx4 v[8:11], v[32:33], off offset:128
	global_load_dwordx4 v[12:15], v[32:33], off offset:64
	global_load_dwordx4 v[16:19], v[32:33], off offset:192
	global_load_dwordx4 v[20:23], v[32:33], off offset:256
	global_load_dwordx4 v[24:27], v[32:33], off offset:320
	global_load_dwordx4 v[28:31], v[32:33], off offset:384
	s_nop 0
	global_load_dwordx4 v[32:35], v[32:33], off offset:448
	s_lshl_b32 s60, s42, 4
	s_mov_b32 s61, 0
	v_lshl_add_u64 v[214:215], v[120:121], 0, s[60:61]
	global_load_dword v158, v[214:215], off
	global_load_dword v159, v[214:215], off offset:4
	global_load_dword v184, v[214:215], off offset:8
	global_load_dword v185, v[214:215], off offset:12
	s_lshl_b32 s37, s42, 8
	s_add_i32 s46, s44, 4
	s_or_b32 s1, s8, 0x18000
	s_add_u32 s10, s67, s1
	s_addc_u32 s11, s4, s9
	s_add_u32 s8, s5, s1
	s_addc_u32 s9, s58, s9
	s_add_i32 s1, s40, 0xc000
	s_waitcnt vmcnt(0)
	s_barrier
	s_mov_b32 s12, m0
	s_mov_b32 m0, s1
	s_nop 0
	global_load_lds_dwordx4 v212, s[10:11]
	s_mov_b32 m0, s12
	v_add_u32_e32 v91, v154, v192
	s_add_i32 s6, s40, 0xe000
	s_mov_b32 s1, m0
	s_mov_b32 m0, s6
	s_nop 0
	global_load_lds_dwordx4 v213, s[8:9]
	s_mov_b32 m0, s1
	v_mov_b32_e32 v64, 0
	v_mov_b32_e32 v65, 0
	v_mov_b32_e32 v66, 0
	v_mov_b32_e32 v67, 0
	v_mov_b32_e32 v60, 0
	v_mov_b32_e32 v61, 0
	v_mov_b32_e32 v62, 0
	v_mov_b32_e32 v63, 0
	v_mov_b32_e32 v56, 0
	v_mov_b32_e32 v57, 0
	v_mov_b32_e32 v58, 0
	v_mov_b32_e32 v59, 0
	v_mov_b32_e32 v52, 0
	v_mov_b32_e32 v53, 0
	v_mov_b32_e32 v54, 0
	v_mov_b32_e32 v55, 0
	v_mov_b32_e32 v131, 0
	v_mov_b32_e32 v48, 0
	v_mov_b32_e32 v49, 0
	v_mov_b32_e32 v50, 0
	v_mov_b32_e32 v51, 0
	v_mov_b32_e32 v44, 0
	v_mov_b32_e32 v45, 0
	v_mov_b32_e32 v46, 0
	v_mov_b32_e32 v47, 0
	v_mov_b32_e32 v40, 0
	v_mov_b32_e32 v41, 0
	v_mov_b32_e32 v42, 0
	v_mov_b32_e32 v43, 0
	v_mov_b32_e32 v36, 0
	v_mov_b32_e32 v37, 0
	v_mov_b32_e32 v38, 0
	v_mov_b32_e32 v39, 0
	v_mov_b32_e32 v130, 0
	v_mov_b32_e32 v72, 0
	v_mov_b32_e32 v73, 0
	v_mov_b32_e32 v74, 0
	v_mov_b32_e32 v75, 0
	v_mov_b32_e32 v84, 0
	v_mov_b32_e32 v85, 0
	v_mov_b32_e32 v86, 0
	v_mov_b32_e32 v87, 0
	v_mov_b32_e32 v88, 0
	v_mov_b32_e32 v89, 0
	v_mov_b32_e32 v90, 0
	v_mov_b32_e32 v91, 0
	v_mov_b32_e32 v96, 0
	v_mov_b32_e32 v97, 0
	v_mov_b32_e32 v98, 0
	v_mov_b32_e32 v99, 0
	v_mov_b32_e32 v129, 0
	v_mov_b32_e32 v68, 0
	v_mov_b32_e32 v69, 0
	v_mov_b32_e32 v70, 0
	v_mov_b32_e32 v71, 0
	v_mov_b32_e32 v76, 0
	v_mov_b32_e32 v77, 0
	v_mov_b32_e32 v78, 0
	v_mov_b32_e32 v79, 0
	v_mov_b32_e32 v80, 0
	v_mov_b32_e32 v81, 0
	v_mov_b32_e32 v82, 0
	v_mov_b32_e32 v83, 0
	v_mov_b32_e32 v92, 0
	v_mov_b32_e32 v93, 0
	v_mov_b32_e32 v94, 0
	v_mov_b32_e32 v95, 0
	v_mov_b32_e32 v128, 0
	s_lshl_b32 s47, s7, 6
	s_add_i32 s7, s45, s47
	s_addk_i32 s7, 0xff80
	s_ashr_i32 s8, s7, 31
	s_add_u32 s7, s43, s7
	s_addc_u32 s8, 0, s8
	s_mov_b32 s1, 0
	s_mov_b32 s6, 4
	s_mov_b32 s34, 0
	v_add_u32_e32 v100, s34, v191
	v_add3_u32 v135, s34, v203, v198
	v_add_u32_e32 v102, v100, v193
	v_add_u32_e32 v100, v100, v192
	ds_read_b128 v[160:163], v100
	ds_read_b128 v[164:167], v102
	ds_read_b128 v[168:171], v100 offset:2048
	ds_read_b128 v[172:175], v102 offset:2048
	ds_read_b128 v[104:107], v100 offset:4096
	ds_read_b128 v[108:111], v102 offset:4096
	ds_read_b128 v[112:115], v100 offset:6144
	ds_read_b128 v[116:119], v102 offset:6144
	v_add_u32_e32 v103, v135, v199
	v_add_u32_e32 v133, v135, v200
	v_add_u32_e32 v134, v135, v201
	v_add_u32_e32 v135, v135, v202
	s_waitcnt lgkmcnt(4)
; #define LAS __attribute__((address_space(3)))
; template <int NB16> __device__ __forceinline__ float exp_step(f32x4 (&S)[NB16]) {
;     float sum = 0.f;
; #pragma unroll
;     for (int k = 0; k < NB16; ++k)
; #pragma unroll
;         for (int i = 0; i < 4; ++i) { S[k][i] = __builtin_amdgcn_exp2f(S[k][i]); sum += S[k][i]; }
;     return sum;
; }
;     const int l15 = lane & 15, g = lane >> 4, q4 = l15 >> 2;
;     const LAS unsigned char* kb0 = Kt + l15 * 128;
;     const int kx0 = ((g) ^ (l15 & 7)) << 4, kx1 = ((4 + g) ^ (l15 & 7)) << 4;
;     const LAS unsigned char* vrow = Vt + (4 * g + q4) * 128 + (lane & 3) * 8;
;     const int swz = (2 * (g & 1) + (q4 >> 1)) & 3;
;     const f32x4 cinit = (f32x4){negb, negb, negb, negb};
; #pragma unroll
;     for (int gh = 0; gh < 4 / GPB; ++gh) {
;         f32x4 S[GPB][4];
; #pragma unroll
;         for (int kb = 0; kb < 4; ++kb) {
;             const bf16x8 kf0 = *(const LAS bf16x8*)(kb0 + (16 * kb) * 128 + kx0), kf1 = *(const LAS bf16x8*)(kb0 + (16 * kb) * 128 + kx1);
; #pragma unroll
;             for (int gi = 0; gi < GPB; ++gi) { S[gi][kb] = __builtin_amdgcn_mfma_f32_16x16x32_bf16(kf0, qf[GPB * gh + gi][0], cinit, 0, 0, 0);
;                 S[gi][kb] = __builtin_amdgcn_mfma_f32_16x16x32_bf16(kf1, qf[GPB * gh + gi][1], S[gi][kb], 0, 0, 0); } }
;         bf16x8 pf[GPB][2];
; #pragma unroll
;         for (int gi = 0; gi < GPB; ++gi) {
;             if (MASK) {
; #pragma unroll
;                 for (int kb = 0; kb < 4; ++kb)
; #pragma unroll
;                     for (int i = 0; i < 4; ++i) { const int rel = rel0 + 16 * kb + 4 * g + i; S[gi][kb][i] = ((unsigned)(rel + 128) > 256u) ? NEGBIG : S[gi][kb][i]; }
;             }
;             ls[GPB * gh + gi] += exp_step<4>(S[gi]);
;             pf[gi][0] = pack8(S[gi][0], S[gi][1]); pf[gi][1] = pack8(S[gi][2], S[gi][3]);
;         }
; #pragma unroll
;         for (int kc = 0; kc < 2; ++kc)
; #pragma unroll
;             for (int db = 0; db < 4; ++db) {
;                 const LAS unsigned char* va = vrow + ((db ^ swz) << 5) + (32 * kc) * 128;
;                 const bf16x8 vf = cat8(vtr(va), vtr(va + 16 * 128));
; #pragma unroll
;                 for (int gi = 0; gi < GPB; ++gi) O[GPB * gh + gi][db] = __builtin_amdgcn_mfma_f32_16x16x32_bf16(vf, pf[gi][kc], O[GPB * gh + gi][db], 0, 0, 0);
;             }
	v_mfma_f32_16x16x32_bf16 v[136:139], v[160:163], v[4:7], v[0:3]
	v_mfma_f32_16x16x32_bf16 v[140:143], v[168:171], v[4:7], v[0:3]
	v_mfma_f32_16x16x32_bf16 v[136:139], v[164:167], v[12:15], v[136:139]
	v_mfma_f32_16x16x32_bf16 v[140:143], v[172:175], v[12:15], v[140:143]
	ds_read_b64_tr_b16 v[216:217], v103 offset:8192
	ds_read_b64_tr_b16 v[218:219], v103 offset:10240
	ds_read_b64_tr_b16 v[220:221], v133 offset:8192
	ds_read_b64_tr_b16 v[222:223], v133 offset:10240
	ds_read_b64_tr_b16 v[224:225], v134 offset:8192
	ds_read_b64_tr_b16 v[226:227], v134 offset:10240
	ds_read_b64_tr_b16 v[228:229], v135 offset:8192
	ds_read_b64_tr_b16 v[230:231], v135 offset:10240
	v_mfma_f32_16x16x32_bf16 v[176:179], v[160:163], v[8:11], v[0:3]
	v_exp_f32_e32 v136, v136
	v_exp_f32_e32 v137, v137
	v_exp_f32_e32 v138, v138
	v_mfma_f32_16x16x32_bf16 v[232:235], v[168:171], v[8:11], v[0:3]
	v_exp_f32_e32 v139, v139
	v_exp_f32_e32 v140, v140
	v_pk_add_f32 v[242:243], v[136:137], v[138:139]
	v_mfma_f32_16x16x32_bf16 v[176:179], v[164:167], v[16:19], v[176:179]
	v_exp_f32_e32 v141, v141
	v_exp_f32_e32 v142, v142
	v_pk_add_f32 v[242:243], v[242:243], v[140:141]
	v_cvt_pk_bf16_f32 v136, v136, v137
	v_mfma_f32_16x16x32_bf16 v[232:235], v[172:175], v[16:19], v[232:235]
	v_exp_f32_e32 v143, v143
	v_cvt_pk_bf16_f32 v137, v138, v139
	v_cvt_pk_bf16_f32 v138, v140, v141
	v_cvt_pk_bf16_f32 v139, v142, v143
	v_pk_add_f32 v[242:243], v[242:243], v[142:143]
	v_add_f32_e32 v131, v131, v242
	v_add_f32_e32 v131, v131, v243
	s_waitcnt lgkmcnt(0)
	v_mfma_f32_16x16x32_bf16 v[244:247], v[160:163], v[20:23], v[0:3]
	v_exp_f32_e32 v176, v176
	v_exp_f32_e32 v177, v177
	v_mfma_f32_16x16x32_bf16 v[248:251], v[168:171], v[20:23], v[0:3]
	v_exp_f32_e32 v178, v178
	v_mfma_f32_16x16x32_bf16 v[244:247], v[164:167], v[24:27], v[244:247]
	v_exp_f32_e32 v179, v179
	v_mfma_f32_16x16x32_bf16 v[248:251], v[172:175], v[24:27], v[248:251]
	v_exp_f32_e32 v232, v232
	v_pk_add_f32 v[242:243], v[176:177], v[178:179]
	v_mfma_f32_16x16x32_bf16 v[64:67], v[216:219], v[136:139], v[64:67]
	v_exp_f32_e32 v233, v233
	v_mfma_f32_16x16x32_bf16 v[60:63], v[220:223], v[136:139], v[60:63]
	v_exp_f32_e32 v234, v234
	v_pk_add_f32 v[242:243], v[242:243], v[232:233]
	v_cvt_pk_bf16_f32 v176, v176, v177
	v_mfma_f32_16x16x32_bf16 v[56:59], v[224:227], v[136:139], v[56:59]
	v_exp_f32_e32 v235, v235
	v_cvt_pk_bf16_f32 v177, v178, v179
	v_mfma_f32_16x16x32_bf16 v[52:55], v[228:231], v[136:139], v[52:55]
	v_cvt_pk_bf16_f32 v178, v232, v233
	v_cvt_pk_bf16_f32 v179, v234, v235
	v_pk_add_f32 v[242:243], v[242:243], v[234:235]
	v_add_f32_e32 v130, v130, v242
	v_add_f32_e32 v130, v130, v243
	v_mfma_f32_16x16x32_bf16 v[136:139], v[160:163], v[28:31], v[0:3]
	v_exp_f32_e32 v244, v244
	v_exp_f32_e32 v245, v245
	v_mfma_f32_16x16x32_bf16 v[140:143], v[168:171], v[28:31], v[0:3]
	v_exp_f32_e32 v246, v246
	v_mfma_f32_16x16x32_bf16 v[136:139], v[164:167], v[32:35], v[136:139]
	v_exp_f32_e32 v247, v247
	v_mfma_f32_16x16x32_bf16 v[140:143], v[172:175], v[32:35], v[140:143]
	v_exp_f32_e32 v248, v248
	v_pk_add_f32 v[242:243], v[244:245], v[246:247]
	v_mfma_f32_16x16x32_bf16 v[48:51], v[216:219], v[176:179], v[48:51]
	v_exp_f32_e32 v249, v249
	v_mfma_f32_16x16x32_bf16 v[44:47], v[220:223], v[176:179], v[44:47]
	v_exp_f32_e32 v250, v250
	v_pk_add_f32 v[242:243], v[242:243], v[248:249]
	v_cvt_pk_bf16_f32 v244, v244, v245
	v_mfma_f32_16x16x32_bf16 v[40:43], v[224:227], v[176:179], v[40:43]
	v_exp_f32_e32 v251, v251
	v_cvt_pk_bf16_f32 v245, v246, v247
	v_mfma_f32_16x16x32_bf16 v[36:39], v[228:231], v[176:179], v[36:39]
	v_cvt_pk_bf16_f32 v246, v248, v249
	v_cvt_pk_bf16_f32 v247, v250, v251
	v_pk_add_f32 v[242:243], v[242:243], v[250:251]
	v_add_f32_e32 v129, v129, v242
	v_add_f32_e32 v129, v129, v243
	ds_read_b64_tr_b16 v[160:161], v103 offset:12288
	ds_read_b64_tr_b16 v[162:163], v103 offset:14336
	ds_read_b64_tr_b16 v[164:165], v133 offset:12288
	ds_read_b64_tr_b16 v[166:167], v133 offset:14336
	ds_read_b64_tr_b16 v[168:169], v134 offset:12288
	ds_read_b64_tr_b16 v[170:171], v134 offset:14336
	ds_read_b64_tr_b16 v[172:173], v135 offset:12288
	ds_read_b64_tr_b16 v[174:175], v135 offset:14336
	v_mfma_f32_16x16x32_bf16 v[176:179], v[104:107], v[4:7], v[0:3]
	v_exp_f32_e32 v136, v136
	v_exp_f32_e32 v137, v137
	v_mfma_f32_16x16x32_bf16 v[232:235], v[112:115], v[4:7], v[0:3]
	v_exp_f32_e32 v138, v138
	v_mfma_f32_16x16x32_bf16 v[176:179], v[108:111], v[12:15], v[176:179]
	v_exp_f32_e32 v139, v139
	v_mfma_f32_16x16x32_bf16 v[232:235], v[116:119], v[12:15], v[232:235]
	v_exp_f32_e32 v140, v140
	v_pk_add_f32 v[242:243], v[136:137], v[138:139]
	v_mfma_f32_16x16x32_bf16 v[72:75], v[216:219], v[244:247], v[72:75]
	v_exp_f32_e32 v141, v141
	v_mfma_f32_16x16x32_bf16 v[84:87], v[220:223], v[244:247], v[84:87]
	v_exp_f32_e32 v142, v142
	v_pk_add_f32 v[242:243], v[242:243], v[140:141]
	v_cvt_pk_bf16_f32 v136, v136, v137
	v_mfma_f32_16x16x32_bf16 v[88:91], v[224:227], v[244:247], v[88:91]
	v_exp_f32_e32 v143, v143
	v_cvt_pk_bf16_f32 v137, v138, v139
	v_mfma_f32_16x16x32_bf16 v[96:99], v[228:231], v[244:247], v[96:99]
	v_cvt_pk_bf16_f32 v138, v140, v141
	v_cvt_pk_bf16_f32 v139, v142, v143
	v_pk_add_f32 v[242:243], v[242:243], v[142:143]
	v_add_f32_e32 v128, v128, v242
	v_add_f32_e32 v128, v128, v243
	v_mfma_f32_16x16x32_bf16 v[244:247], v[104:107], v[8:11], v[0:3]
	v_exp_f32_e32 v176, v176
	v_exp_f32_e32 v177, v177
	v_mfma_f32_16x16x32_bf16 v[248:251], v[112:115], v[8:11], v[0:3]
	v_exp_f32_e32 v178, v178
	v_mfma_f32_16x16x32_bf16 v[244:247], v[108:111], v[16:19], v[244:247]
	v_exp_f32_e32 v179, v179
	v_mfma_f32_16x16x32_bf16 v[248:251], v[116:119], v[16:19], v[248:251]
	v_exp_f32_e32 v232, v232
	v_pk_add_f32 v[242:243], v[176:177], v[178:179]
	v_mfma_f32_16x16x32_bf16 v[68:71], v[216:219], v[136:139], v[68:71]
	v_exp_f32_e32 v233, v233
	v_mfma_f32_16x16x32_bf16 v[76:79], v[220:223], v[136:139], v[76:79]
	v_exp_f32_e32 v234, v234
	v_pk_add_f32 v[242:243], v[242:243], v[232:233]
	v_cvt_pk_bf16_f32 v176, v176, v177
	v_mfma_f32_16x16x32_bf16 v[80:83], v[224:227], v[136:139], v[80:83]
	v_exp_f32_e32 v235, v235
	v_cvt_pk_bf16_f32 v177, v178, v179
	v_mfma_f32_16x16x32_bf16 v[92:95], v[228:231], v[136:139], v[92:95]
	v_cvt_pk_bf16_f32 v178, v232, v233
	v_cvt_pk_bf16_f32 v179, v234, v235
	v_pk_add_f32 v[242:243], v[242:243], v[234:235]
	v_add_f32_e32 v131, v131, v242
	v_add_f32_e32 v131, v131, v243
	s_waitcnt lgkmcnt(0)
; #define LAS __attribute__((address_space(3)))
; template <int NB16> __device__ __forceinline__ float exp_step(f32x4 (&S)[NB16]) {
;     float sum = 0.f;
; #pragma unroll
;     for (int k = 0; k < NB16; ++k)
; #pragma unroll
;         for (int i = 0; i < 4; ++i) { S[k][i] = __builtin_amdgcn_exp2f(S[k][i]); sum += S[k][i]; }
;     return sum;
; }
;     const int l15 = lane & 15, g = lane >> 4, q4 = l15 >> 2;
;     const LAS unsigned char* kb0 = Kt + l15 * 128;
;     const int kx0 = ((g) ^ (l15 & 7)) << 4, kx1 = ((4 + g) ^ (l15 & 7)) << 4;
;     const LAS unsigned char* vrow = Vt + (4 * g + q4) * 128 + (lane & 3) * 8;
;     const int swz = (2 * (g & 1) + (q4 >> 1)) & 3;
;     const f32x4 cinit = (f32x4){negb, negb, negb, negb};
; #pragma unroll
;     for (int gh = 0; gh < 4 / GPB; ++gh) {
;         f32x4 S[GPB][4];
; #pragma unroll
;         for (int kb = 0; kb < 4; ++kb) {
;             const bf16x8 kf0 = *(const LAS bf16x8*)(kb0 + (16 * kb) * 128 + kx0), kf1 = *(const LAS bf16x8*)(kb0 + (16 * kb) * 128 + kx1);
; #pragma unroll
;             for (int gi = 0; gi < GPB; ++gi) { S[gi][kb] = __builtin_amdgcn_mfma_f32_16x16x32_bf16(kf0, qf[GPB * gh + gi][0], cinit, 0, 0, 0);
;                 S[gi][kb] = __builtin_amdgcn_mfma_f32_16x16x32_bf16(kf1, qf[GPB * gh + gi][1], S[gi][kb], 0, 0, 0); } }
;         bf16x8 pf[GPB][2];
; #pragma unroll
;         for (int gi = 0; gi < GPB; ++gi) {
;             if (MASK) {
; #pragma unroll
;                 for (int kb = 0; kb < 4; ++kb)
; #pragma unroll
;                     for (int i = 0; i < 4; ++i) { const int rel = rel0 + 16 * kb + 4 * g + i; S[gi][kb][i] = ((unsigned)(rel + 128) > 256u) ? NEGBIG : S[gi][kb][i]; }
;             }
;             ls[GPB * gh + gi] += exp_step<4>(S[gi]);
;             pf[gi][0] = pack8(S[gi][0], S[gi][1]); pf[gi][1] = pack8(S[gi][2], S[gi][3]);
;         }
; #pragma unroll
;         for (int kc = 0; kc < 2; ++kc)
; #pragma unroll
;             for (int db = 0; db < 4; ++db) {
;                 const LAS unsigned char* va = vrow + ((db ^ swz) << 5) + (32 * kc) * 128;
;                 const bf16x8 vf = cat8(vtr(va), vtr(va + 16 * 128));
; #pragma unroll
;                 for (int gi = 0; gi < GPB; ++gi) O[GPB * gh + gi][db] = __builtin_amdgcn_mfma_f32_16x16x32_bf16(vf, pf[gi][kc], O[GPB * gh + gi][db], 0, 0, 0);
;             }
	v_mfma_f32_16x16x32_bf16 v[136:139], v[104:107], v[20:23], v[0:3]
	v_exp_f32_e32 v244, v244
	v_exp_f32_e32 v245, v245
	v_mfma_f32_16x16x32_bf16 v[140:143], v[112:115], v[20:23], v[0:3]
	v_exp_f32_e32 v246, v246
	v_mfma_f32_16x16x32_bf16 v[136:139], v[108:111], v[24:27], v[136:139]
	v_exp_f32_e32 v247, v247
	v_mfma_f32_16x16x32_bf16 v[140:143], v[116:119], v[24:27], v[140:143]
	v_exp_f32_e32 v248, v248
	v_pk_add_f32 v[242:243], v[244:245], v[246:247]
	v_mfma_f32_16x16x32_bf16 v[64:67], v[160:163], v[176:179], v[64:67]
	v_exp_f32_e32 v249, v249
	v_mfma_f32_16x16x32_bf16 v[60:63], v[164:167], v[176:179], v[60:63]
	v_exp_f32_e32 v250, v250
	v_pk_add_f32 v[242:243], v[242:243], v[248:249]
	v_cvt_pk_bf16_f32 v244, v244, v245
	v_mfma_f32_16x16x32_bf16 v[56:59], v[168:171], v[176:179], v[56:59]
	v_exp_f32_e32 v251, v251
	v_cvt_pk_bf16_f32 v245, v246, v247
	v_mfma_f32_16x16x32_bf16 v[52:55], v[172:175], v[176:179], v[52:55]
	v_cvt_pk_bf16_f32 v246, v248, v249
	v_cvt_pk_bf16_f32 v247, v250, v251
	v_pk_add_f32 v[242:243], v[242:243], v[250:251]
	v_add_f32_e32 v130, v130, v242
	v_add_f32_e32 v130, v130, v243
	v_mfma_f32_16x16x32_bf16 v[176:179], v[104:107], v[28:31], v[0:3]
	v_exp_f32_e32 v136, v136
	v_exp_f32_e32 v137, v137
	v_mfma_f32_16x16x32_bf16 v[232:235], v[112:115], v[28:31], v[0:3]
	v_exp_f32_e32 v138, v138
	v_mfma_f32_16x16x32_bf16 v[176:179], v[108:111], v[32:35], v[176:179]
	v_exp_f32_e32 v139, v139
	v_mfma_f32_16x16x32_bf16 v[232:235], v[116:119], v[32:35], v[232:235]
	v_exp_f32_e32 v140, v140
	v_pk_add_f32 v[242:243], v[136:137], v[138:139]
	v_mfma_f32_16x16x32_bf16 v[48:51], v[160:163], v[244:247], v[48:51]
	v_exp_f32_e32 v141, v141
	v_mfma_f32_16x16x32_bf16 v[44:47], v[164:167], v[244:247], v[44:47]
	v_exp_f32_e32 v142, v142
	v_pk_add_f32 v[242:243], v[242:243], v[140:141]
	v_cvt_pk_bf16_f32 v136, v136, v137
	v_mfma_f32_16x16x32_bf16 v[40:43], v[168:171], v[244:247], v[40:43]
	v_exp_f32_e32 v143, v143
	v_cvt_pk_bf16_f32 v137, v138, v139
	v_mfma_f32_16x16x32_bf16 v[36:39], v[172:175], v[244:247], v[36:39]
	v_cvt_pk_bf16_f32 v138, v140, v141
	v_cvt_pk_bf16_f32 v139, v142, v143
	v_pk_add_f32 v[242:243], v[242:243], v[142:143]
	v_add_f32_e32 v129, v129, v242
	v_add_f32_e32 v129, v129, v243
	v_mfma_f32_16x16x32_bf16 v[72:75], v[160:163], v[136:139], v[72:75]
	v_exp_f32_e32 v176, v176
	v_exp_f32_e32 v177, v177
	v_exp_f32_e32 v178, v178
	v_mfma_f32_16x16x32_bf16 v[84:87], v[164:167], v[136:139], v[84:87]
	v_exp_f32_e32 v179, v179
	v_exp_f32_e32 v232, v232
	v_pk_add_f32 v[242:243], v[176:177], v[178:179]
	v_mfma_f32_16x16x32_bf16 v[88:91], v[168:171], v[136:139], v[88:91]
	v_exp_f32_e32 v233, v233
	v_exp_f32_e32 v234, v234
	v_pk_add_f32 v[242:243], v[242:243], v[232:233]
	v_cvt_pk_bf16_f32 v176, v176, v177
	v_mfma_f32_16x16x32_bf16 v[96:99], v[172:175], v[136:139], v[96:99]
	v_exp_f32_e32 v235, v235
	v_cvt_pk_bf16_f32 v177, v178, v179
	v_cvt_pk_bf16_f32 v178, v232, v233
	v_cvt_pk_bf16_f32 v179, v234, v235
	v_pk_add_f32 v[242:243], v[242:243], v[234:235]
	v_add_f32_e32 v128, v128, v242
	v_add_f32_e32 v128, v128, v243
	v_mfma_f32_16x16x32_bf16 v[68:71], v[160:163], v[176:179], v[68:71]
	v_mfma_f32_16x16x32_bf16 v[76:79], v[164:167], v[176:179], v[76:79]
	v_mfma_f32_16x16x32_bf16 v[80:83], v[168:171], v[176:179], v[80:83]
	v_mfma_f32_16x16x32_bf16 v[92:95], v[172:175], v[176:179], v[92:95]
	s_waitcnt vmcnt(4)
	s_barrier
	s_cmp_lt_u32 s6, s46
	s_cselect_b32 s11, s8, 0
	s_cselect_b32 s10, s7, s82
	s_lshl_b64 s[10:11], s[10:11], 9
	s_add_u32 s12, s67, s10
	s_addc_u32 s13, s4, s11
	s_add_u32 s10, s5, s10
	s_addc_u32 s11, s58, s11
	s_add_i32 s9, s40, s1
	s_mov_b32 s15, m0
	s_mov_b32 m0, s9
	s_nop 0
	global_load_lds_dwordx4 v212, s[12:13]
	s_mov_b32 m0, s15
	s_add_i32 s14, s9, 0x2000
	s_mov_b32 s9, m0
	s_mov_b32 m0, s14
	s_nop 0
	global_load_lds_dwordx4 v213, s[10:11]
	s_mov_b32 m0, s9
	s_add_i32 s34, s1, 0x4000
	v_add_u32_e32 v100, s34, v191
	v_add3_u32 v135, s34, v203, v198
	v_add_u32_e32 v102, v100, v193
	v_add_u32_e32 v100, v100, v192
	ds_read_b128 v[160:163], v100
	ds_read_b128 v[164:167], v102
	ds_read_b128 v[168:171], v100 offset:2048
	ds_read_b128 v[172:175], v102 offset:2048
	ds_read_b128 v[104:107], v100 offset:4096
	ds_read_b128 v[108:111], v102 offset:4096
	ds_read_b128 v[112:115], v100 offset:6144
	ds_read_b128 v[116:119], v102 offset:6144
	v_add_u32_e32 v103, v135, v199
	v_add_u32_e32 v133, v135, v200
	v_add_u32_e32 v134, v135, v201
	v_add_u32_e32 v135, v135, v202
	s_waitcnt lgkmcnt(4)
	v_mfma_f32_16x16x32_bf16 v[136:139], v[160:163], v[4:7], v[0:3]
	v_mfma_f32_16x16x32_bf16 v[140:143], v[168:171], v[4:7], v[0:3]
	v_mfma_f32_16x16x32_bf16 v[136:139], v[164:167], v[12:15], v[136:139]
	v_mfma_f32_16x16x32_bf16 v[140:143], v[172:175], v[12:15], v[140:143]
	ds_read_b64_tr_b16 v[216:217], v103 offset:8192
	ds_read_b64_tr_b16 v[218:219], v103 offset:10240
	ds_read_b64_tr_b16 v[220:221], v133 offset:8192
	ds_read_b64_tr_b16 v[222:223], v133 offset:10240
	ds_read_b64_tr_b16 v[224:225], v134 offset:8192
	ds_read_b64_tr_b16 v[226:227], v134 offset:10240
	ds_read_b64_tr_b16 v[228:229], v135 offset:8192
	ds_read_b64_tr_b16 v[230:231], v135 offset:10240
	v_mfma_f32_16x16x32_bf16 v[176:179], v[160:163], v[8:11], v[0:3]
	v_exp_f32_e32 v136, v136
	v_exp_f32_e32 v137, v137
	v_exp_f32_e32 v138, v138
	v_mfma_f32_16x16x32_bf16 v[232:235], v[168:171], v[8:11], v[0:3]
	v_exp_f32_e32 v139, v139
	v_exp_f32_e32 v140, v140
	v_pk_add_f32 v[242:243], v[136:137], v[138:139]
	v_mfma_f32_16x16x32_bf16 v[176:179], v[164:167], v[16:19], v[176:179]
	v_exp_f32_e32 v141, v141
	v_exp_f32_e32 v142, v142
	v_pk_add_f32 v[242:243], v[242:243], v[140:141]
	v_cvt_pk_bf16_f32 v136, v136, v137
	v_mfma_f32_16x16x32_bf16 v[232:235], v[172:175], v[16:19], v[232:235]
	v_exp_f32_e32 v143, v143
	v_cvt_pk_bf16_f32 v137, v138, v139
	v_cvt_pk_bf16_f32 v138, v140, v141
	v_cvt_pk_bf16_f32 v139, v142, v143
	v_pk_add_f32 v[242:243], v[242:243], v[142:143]
	v_add_f32_e32 v131, v131, v242
	v_add_f32_e32 v131, v131, v243
	s_waitcnt lgkmcnt(0)
; #define LAS __attribute__((address_space(3)))
; template <int NB16> __device__ __forceinline__ float exp_step(f32x4 (&S)[NB16]) {
;     float sum = 0.f;
; #pragma unroll
;     for (int k = 0; k < NB16; ++k)
; #pragma unroll
;         for (int i = 0; i < 4; ++i) { S[k][i] = __builtin_amdgcn_exp2f(S[k][i]); sum += S[k][i]; }
;     return sum;
; }
;     const int l15 = lane & 15, g = lane >> 4, q4 = l15 >> 2;
;     const LAS unsigned char* kb0 = Kt + l15 * 128;
;     const int kx0 = ((g) ^ (l15 & 7)) << 4, kx1 = ((4 + g) ^ (l15 & 7)) << 4;
;     const LAS unsigned char* vrow = Vt + (4 * g + q4) * 128 + (lane & 3) * 8;
;     const int swz = (2 * (g & 1) + (q4 >> 1)) & 3;
;     const f32x4 cinit = (f32x4){negb, negb, negb, negb};
; #pragma unroll
;     for (int gh = 0; gh < 4 / GPB; ++gh) {
;         f32x4 S[GPB][4];
; #pragma unroll
;         for (int kb = 0; kb < 4; ++kb) {
;             const bf16x8 kf0 = *(const LAS bf16x8*)(kb0 + (16 * kb) * 128 + kx0), kf1 = *(const LAS bf16x8*)(kb0 + (16 * kb) * 128 + kx1);
; #pragma unroll
;             for (int gi = 0; gi < GPB; ++gi) { S[gi][kb] = __builtin_amdgcn_mfma_f32_16x16x32_bf16(kf0, qf[GPB * gh + gi][0], cinit, 0, 0, 0);
;                 S[gi][kb] = __builtin_amdgcn_mfma_f32_16x16x32_bf16(kf1, qf[GPB * gh + gi][1], S[gi][kb], 0, 0, 0); } }
;         bf16x8 pf[GPB][2];
; #pragma unroll
;         for (int gi = 0; gi < GPB; ++gi) {
;             if (MASK) {
; #pragma unroll
;                 for (int kb = 0; kb < 4; ++kb)
; #pragma unroll
;                     for (int i = 0; i < 4; ++i) { const int rel = rel0 + 16 * kb + 4 * g + i; S[gi][kb][i] = ((unsigned)(rel + 128) > 256u) ? NEGBIG : S[gi][kb][i]; }
;             }
;             ls[GPB * gh + gi] += exp_step<4>(S[gi]);
;             pf[gi][0] = pack8(S[gi][0], S[gi][1]); pf[gi][1] = pack8(S[gi][2], S[gi][3]);
;         }
; #pragma unroll
;         for (int kc = 0; kc < 2; ++kc)
; #pragma unroll
;             for (int db = 0; db < 4; ++db) {
;                 const LAS unsigned char* va = vrow + ((db ^ swz) << 5) + (32 * kc) * 128;
;                 const bf16x8 vf = cat8(vtr(va), vtr(va + 16 * 128));
; #pragma unroll
;                 for (int gi = 0; gi < GPB; ++gi) O[GPB * gh + gi][db] = __builtin_amdgcn_mfma_f32_16x16x32_bf16(vf, pf[gi][kc], O[GPB * gh + gi][db], 0, 0, 0);
;             }
	v_mfma_f32_16x16x32_bf16 v[244:247], v[160:163], v[20:23], v[0:3]
	v_exp_f32_e32 v176, v176
	v_exp_f32_e32 v177, v177
	v_mfma_f32_16x16x32_bf16 v[248:251], v[168:171], v[20:23], v[0:3]
	v_exp_f32_e32 v178, v178
	v_mfma_f32_16x16x32_bf16 v[244:247], v[164:167], v[24:27], v[244:247]
	v_exp_f32_e32 v179, v179
	v_mfma_f32_16x16x32_bf16 v[248:251], v[172:175], v[24:27], v[248:251]
	v_exp_f32_e32 v232, v232
	v_pk_add_f32 v[242:243], v[176:177], v[178:179]
	v_mfma_f32_16x16x32_bf16 v[64:67], v[216:219], v[136:139], v[64:67]
	v_exp_f32_e32 v233, v233
	v_mfma_f32_16x16x32_bf16 v[60:63], v[220:223], v[136:139], v[60:63]
	v_exp_f32_e32 v234, v234
	v_pk_add_f32 v[242:243], v[242:243], v[232:233]
	v_cvt_pk_bf16_f32 v176, v176, v177
	v_mfma_f32_16x16x32_bf16 v[56:59], v[224:227], v[136:139], v[56:59]
	v_exp_f32_e32 v235, v235
	v_cvt_pk_bf16_f32 v177, v178, v179
	v_mfma_f32_16x16x32_bf16 v[52:55], v[228:231], v[136:139], v[52:55]
	v_cvt_pk_bf16_f32 v178, v232, v233
	v_cvt_pk_bf16_f32 v179, v234, v235
	v_pk_add_f32 v[242:243], v[242:243], v[234:235]
	v_add_f32_e32 v130, v130, v242
	v_add_f32_e32 v130, v130, v243
	v_mfma_f32_16x16x32_bf16 v[136:139], v[160:163], v[28:31], v[0:3]
	v_exp_f32_e32 v244, v244
	v_exp_f32_e32 v245, v245
	v_mfma_f32_16x16x32_bf16 v[140:143], v[168:171], v[28:31], v[0:3]
	v_exp_f32_e32 v246, v246
	v_mfma_f32_16x16x32_bf16 v[136:139], v[164:167], v[32:35], v[136:139]
	v_exp_f32_e32 v247, v247
	v_mfma_f32_16x16x32_bf16 v[140:143], v[172:175], v[32:35], v[140:143]
	v_exp_f32_e32 v248, v248
	v_pk_add_f32 v[242:243], v[244:245], v[246:247]
	v_mfma_f32_16x16x32_bf16 v[48:51], v[216:219], v[176:179], v[48:51]
	v_exp_f32_e32 v249, v249
	v_mfma_f32_16x16x32_bf16 v[44:47], v[220:223], v[176:179], v[44:47]
	v_exp_f32_e32 v250, v250
	v_pk_add_f32 v[242:243], v[242:243], v[248:249]
	v_cvt_pk_bf16_f32 v244, v244, v245
	v_mfma_f32_16x16x32_bf16 v[40:43], v[224:227], v[176:179], v[40:43]
	v_exp_f32_e32 v251, v251
	v_cvt_pk_bf16_f32 v245, v246, v247
	v_mfma_f32_16x16x32_bf16 v[36:39], v[228:231], v[176:179], v[36:39]
	v_cvt_pk_bf16_f32 v246, v248, v249
	v_cvt_pk_bf16_f32 v247, v250, v251
	v_pk_add_f32 v[242:243], v[242:243], v[250:251]
	v_add_f32_e32 v129, v129, v242
	v_add_f32_e32 v129, v129, v243
	ds_read_b64_tr_b16 v[160:161], v103 offset:12288
	ds_read_b64_tr_b16 v[162:163], v103 offset:14336
	ds_read_b64_tr_b16 v[164:165], v133 offset:12288
	ds_read_b64_tr_b16 v[166:167], v133 offset:14336
	ds_read_b64_tr_b16 v[168:169], v134 offset:12288
	ds_read_b64_tr_b16 v[170:171], v134 offset:14336
	ds_read_b64_tr_b16 v[172:173], v135 offset:12288
	ds_read_b64_tr_b16 v[174:175], v135 offset:14336
	v_mfma_f32_16x16x32_bf16 v[176:179], v[104:107], v[4:7], v[0:3]
	v_exp_f32_e32 v136, v136
	v_exp_f32_e32 v137, v137
	v_mfma_f32_16x16x32_bf16 v[232:235], v[112:115], v[4:7], v[0:3]
	v_exp_f32_e32 v138, v138
	v_mfma_f32_16x16x32_bf16 v[176:179], v[108:111], v[12:15], v[176:179]
	v_exp_f32_e32 v139, v139
	v_mfma_f32_16x16x32_bf16 v[232:235], v[116:119], v[12:15], v[232:235]
	v_exp_f32_e32 v140, v140
	v_pk_add_f32 v[242:243], v[136:137], v[138:139]
	v_mfma_f32_16x16x32_bf16 v[72:75], v[216:219], v[244:247], v[72:75]
	v_exp_f32_e32 v141, v141
	v_mfma_f32_16x16x32_bf16 v[84:87], v[220:223], v[244:247], v[84:87]
	v_exp_f32_e32 v142, v142
	v_pk_add_f32 v[242:243], v[242:243], v[140:141]
	v_cvt_pk_bf16_f32 v136, v136, v137
	v_mfma_f32_16x16x32_bf16 v[88:91], v[224:227], v[244:247], v[88:91]
	v_exp_f32_e32 v143, v143
	v_cvt_pk_bf16_f32 v137, v138, v139
	v_mfma_f32_16x16x32_bf16 v[96:99], v[228:231], v[244:247], v[96:99]
	v_cvt_pk_bf16_f32 v138, v140, v141
	v_cvt_pk_bf16_f32 v139, v142, v143
	v_pk_add_f32 v[242:243], v[242:243], v[142:143]
	v_add_f32_e32 v128, v128, v242
	v_add_f32_e32 v128, v128, v243
	v_mfma_f32_16x16x32_bf16 v[244:247], v[104:107], v[8:11], v[0:3]
	v_exp_f32_e32 v176, v176
	v_exp_f32_e32 v177, v177
	v_mfma_f32_16x16x32_bf16 v[248:251], v[112:115], v[8:11], v[0:3]
	v_exp_f32_e32 v178, v178
	v_mfma_f32_16x16x32_bf16 v[244:247], v[108:111], v[16:19], v[244:247]
	v_exp_f32_e32 v179, v179
	v_mfma_f32_16x16x32_bf16 v[248:251], v[116:119], v[16:19], v[248:251]
	v_exp_f32_e32 v232, v232
	v_pk_add_f32 v[242:243], v[176:177], v[178:179]
	v_mfma_f32_16x16x32_bf16 v[68:71], v[216:219], v[136:139], v[68:71]
	v_exp_f32_e32 v233, v233
	v_mfma_f32_16x16x32_bf16 v[76:79], v[220:223], v[136:139], v[76:79]
	v_exp_f32_e32 v234, v234
	v_pk_add_f32 v[242:243], v[242:243], v[232:233]
	v_cvt_pk_bf16_f32 v176, v176, v177
	v_mfma_f32_16x16x32_bf16 v[80:83], v[224:227], v[136:139], v[80:83]
	v_exp_f32_e32 v235, v235
	v_cvt_pk_bf16_f32 v177, v178, v179
	v_mfma_f32_16x16x32_bf16 v[92:95], v[228:231], v[136:139], v[92:95]
	v_cvt_pk_bf16_f32 v178, v232, v233
	v_cvt_pk_bf16_f32 v179, v234, v235
	v_pk_add_f32 v[242:243], v[242:243], v[234:235]
	v_add_f32_e32 v131, v131, v242
	v_add_f32_e32 v131, v131, v243
	s_waitcnt lgkmcnt(0)
; #define LAS __attribute__((address_space(3)))
; template <int NB16> __device__ __forceinline__ float exp_step(f32x4 (&S)[NB16]) {
;     float sum = 0.f;
; #pragma unroll
;     for (int k = 0; k < NB16; ++k)
; #pragma unroll
;         for (int i = 0; i < 4; ++i) { S[k][i] = __builtin_amdgcn_exp2f(S[k][i]); sum += S[k][i]; }
;     return sum;
; }
;     const int l15 = lane & 15, g = lane >> 4, q4 = l15 >> 2;
;     const LAS unsigned char* kb0 = Kt + l15 * 128;
;     const int kx0 = ((g) ^ (l15 & 7)) << 4, kx1 = ((4 + g) ^ (l15 & 7)) << 4;
;     const LAS unsigned char* vrow = Vt + (4 * g + q4) * 128 + (lane & 3) * 8;
;     const int swz = (2 * (g & 1) + (q4 >> 1)) & 3;
;     const f32x4 cinit = (f32x4){negb, negb, negb, negb};
; #pragma unroll
;     for (int gh = 0; gh < 4 / GPB; ++gh) {
;         f32x4 S[GPB][4];
; #pragma unroll
;         for (int kb = 0; kb < 4; ++kb) {
;             const bf16x8 kf0 = *(const LAS bf16x8*)(kb0 + (16 * kb) * 128 + kx0), kf1 = *(const LAS bf16x8*)(kb0 + (16 * kb) * 128 + kx1);
; #pragma unroll
;             for (int gi = 0; gi < GPB; ++gi) { S[gi][kb] = __builtin_amdgcn_mfma_f32_16x16x32_bf16(kf0, qf[GPB * gh + gi][0], cinit, 0, 0, 0);
;                 S[gi][kb] = __builtin_amdgcn_mfma_f32_16x16x32_bf16(kf1, qf[GPB * gh + gi][1], S[gi][kb], 0, 0, 0); } }
;         bf16x8 pf[GPB][2];
; #pragma unroll
;         for (int gi = 0; gi < GPB; ++gi) {
;             if (MASK) {
; #pragma unroll
;                 for (int kb = 0; kb < 4; ++kb)
; #pragma unroll
;                     for (int i = 0; i < 4; ++i) { const int rel = rel0 + 16 * kb + 4 * g + i; S[gi][kb][i] = ((unsigned)(rel + 128) > 256u) ? NEGBIG : S[gi][kb][i]; }
;             }
;             ls[GPB * gh + gi] += exp_step<4>(S[gi]);
;             pf[gi][0] = pack8(S[gi][0], S[gi][1]); pf[gi][1] = pack8(S[gi][2], S[gi][3]);
;         }
; #pragma unroll
;         for (int kc = 0; kc < 2; ++kc)
; #pragma unroll
;             for (int db = 0; db < 4; ++db) {
;                 const LAS unsigned char* va = vrow + ((db ^ swz) << 5) + (32 * kc) * 128;
;                 const bf16x8 vf = cat8(vtr(va), vtr(va + 16 * 128));
; #pragma unroll
;                 for (int gi = 0; gi < GPB; ++gi) O[GPB * gh + gi][db] = __builtin_amdgcn_mfma_f32_16x16x32_bf16(vf, pf[gi][kc], O[GPB * gh + gi][db], 0, 0, 0);
;             }
	v_mfma_f32_16x16x32_bf16 v[136:139], v[104:107], v[20:23], v[0:3]
	v_exp_f32_e32 v244, v244
	v_exp_f32_e32 v245, v245
	v_mfma_f32_16x16x32_bf16 v[140:143], v[112:115], v[20:23], v[0:3]
	v_exp_f32_e32 v246, v246
	v_mfma_f32_16x16x32_bf16 v[136:139], v[108:111], v[24:27], v[136:139]
	v_exp_f32_e32 v247, v247
	v_mfma_f32_16x16x32_bf16 v[140:143], v[116:119], v[24:27], v[140:143]
	v_exp_f32_e32 v248, v248
	v_pk_add_f32 v[242:243], v[244:245], v[246:247]
	v_mfma_f32_16x16x32_bf16 v[64:67], v[160:163], v[176:179], v[64:67]
	v_exp_f32_e32 v249, v249
	v_mfma_f32_16x16x32_bf16 v[60:63], v[164:167], v[176:179], v[60:63]
	v_exp_f32_e32 v250, v250
	v_pk_add_f32 v[242:243], v[242:243], v[248:249]
	v_cvt_pk_bf16_f32 v244, v244, v245
	v_mfma_f32_16x16x32_bf16 v[56:59], v[168:171], v[176:179], v[56:59]
	v_exp_f32_e32 v251, v251
	v_cvt_pk_bf16_f32 v245, v246, v247
	v_mfma_f32_16x16x32_bf16 v[52:55], v[172:175], v[176:179], v[52:55]
	v_cvt_pk_bf16_f32 v246, v248, v249
	v_cvt_pk_bf16_f32 v247, v250, v251
	v_pk_add_f32 v[242:243], v[242:243], v[250:251]
	v_add_f32_e32 v130, v130, v242
	v_add_f32_e32 v130, v130, v243
	v_mfma_f32_16x16x32_bf16 v[176:179], v[104:107], v[28:31], v[0:3]
	v_exp_f32_e32 v136, v136
	v_exp_f32_e32 v137, v137
	v_mfma_f32_16x16x32_bf16 v[232:235], v[112:115], v[28:31], v[0:3]
	v_exp_f32_e32 v138, v138
	v_mfma_f32_16x16x32_bf16 v[176:179], v[108:111], v[32:35], v[176:179]
	v_exp_f32_e32 v139, v139
	v_mfma_f32_16x16x32_bf16 v[232:235], v[116:119], v[32:35], v[232:235]
	v_exp_f32_e32 v140, v140
	v_pk_add_f32 v[242:243], v[136:137], v[138:139]
	v_mfma_f32_16x16x32_bf16 v[48:51], v[160:163], v[244:247], v[48:51]
	v_exp_f32_e32 v141, v141
	v_mfma_f32_16x16x32_bf16 v[44:47], v[164:167], v[244:247], v[44:47]
	v_exp_f32_e32 v142, v142
	v_pk_add_f32 v[242:243], v[242:243], v[140:141]
	v_cvt_pk_bf16_f32 v136, v136, v137
	v_mfma_f32_16x16x32_bf16 v[40:43], v[168:171], v[244:247], v[40:43]
	v_exp_f32_e32 v143, v143
	v_cvt_pk_bf16_f32 v137, v138, v139
	v_mfma_f32_16x16x32_bf16 v[36:39], v[172:175], v[244:247], v[36:39]
	v_cvt_pk_bf16_f32 v138, v140, v141
	v_cvt_pk_bf16_f32 v139, v142, v143
	v_pk_add_f32 v[242:243], v[242:243], v[142:143]
	v_add_f32_e32 v129, v129, v242
	v_add_f32_e32 v129, v129, v243
	v_mfma_f32_16x16x32_bf16 v[72:75], v[160:163], v[136:139], v[72:75]
	v_exp_f32_e32 v176, v176
	v_exp_f32_e32 v177, v177
	v_exp_f32_e32 v178, v178
	v_mfma_f32_16x16x32_bf16 v[84:87], v[164:167], v[136:139], v[84:87]
	v_exp_f32_e32 v179, v179
	v_exp_f32_e32 v232, v232
	v_pk_add_f32 v[242:243], v[176:177], v[178:179]
	v_mfma_f32_16x16x32_bf16 v[88:91], v[168:171], v[136:139], v[88:91]
	v_exp_f32_e32 v233, v233
	v_exp_f32_e32 v234, v234
	v_pk_add_f32 v[242:243], v[242:243], v[232:233]
	v_cvt_pk_bf16_f32 v176, v176, v177
	v_mfma_f32_16x16x32_bf16 v[96:99], v[172:175], v[136:139], v[96:99]
	v_exp_f32_e32 v235, v235
	v_cvt_pk_bf16_f32 v177, v178, v179
	v_cvt_pk_bf16_f32 v178, v232, v233
	v_cvt_pk_bf16_f32 v179, v234, v235
	v_pk_add_f32 v[242:243], v[242:243], v[234:235]
	v_add_f32_e32 v128, v128, v242
	v_add_f32_e32 v128, v128, v243
	v_mfma_f32_16x16x32_bf16 v[68:71], v[160:163], v[176:179], v[68:71]
	v_mfma_f32_16x16x32_bf16 v[76:79], v[164:167], v[176:179], v[76:79]
	v_mfma_f32_16x16x32_bf16 v[80:83], v[168:171], v[176:179], v[80:83]
	v_mfma_f32_16x16x32_bf16 v[92:95], v[172:175], v[176:179], v[92:95]
	s_addk_i32 s1, 0x4000
	s_add_u32 s7, s7, 64
	s_addc_u32 s8, s8, 0
	s_add_i32 s6, s6, 1
	s_waitcnt vmcnt(4)
	s_barrier
	s_cmp_lt_u32 s6, s46
	s_cselect_b32 s11, s8, 0
	s_cselect_b32 s10, s7, s82
	s_lshl_b64 s[10:11], s[10:11], 9
	s_add_u32 s12, s67, s10
	s_addc_u32 s13, s4, s11
	s_add_u32 s10, s5, s10
	s_addc_u32 s11, s58, s11
	s_add_i32 s9, s40, s1
	s_mov_b32 s15, m0
	s_mov_b32 m0, s9
	s_nop 0
	global_load_lds_dwordx4 v212, s[12:13]
	s_mov_b32 m0, s15
	s_add_i32 s14, s9, 0x2000
	s_mov_b32 s9, m0
	s_mov_b32 m0, s14
	s_nop 0
	global_load_lds_dwordx4 v213, s[10:11]
	s_mov_b32 m0, s9
	s_add_i32 s34, s1, 0x4000
	v_add_u32_e32 v100, s34, v191
	v_add3_u32 v135, s34, v203, v198
	v_add_u32_e32 v102, v100, v193
	v_add_u32_e32 v100, v100, v192
	ds_read_b128 v[160:163], v100
	ds_read_b128 v[164:167], v102
	ds_read_b128 v[168:171], v100 offset:2048
	ds_read_b128 v[172:175], v102 offset:2048
	ds_read_b128 v[104:107], v100 offset:4096
	ds_read_b128 v[108:111], v102 offset:4096
	ds_read_b128 v[112:115], v100 offset:6144
	ds_read_b128 v[116:119], v102 offset:6144
	v_add_u32_e32 v103, v135, v199
	v_add_u32_e32 v133, v135, v200
	v_add_u32_e32 v134, v135, v201
	v_add_u32_e32 v135, v135, v202
	s_waitcnt lgkmcnt(4)
	v_mfma_f32_16x16x32_bf16 v[136:139], v[160:163], v[4:7], v[0:3]
	v_mfma_f32_16x16x32_bf16 v[140:143], v[168:171], v[4:7], v[0:3]
	v_mfma_f32_16x16x32_bf16 v[136:139], v[164:167], v[12:15], v[136:139]
	v_mfma_f32_16x16x32_bf16 v[140:143], v[172:175], v[12:15], v[140:143]
	ds_read_b64_tr_b16 v[216:217], v103 offset:8192
	ds_read_b64_tr_b16 v[218:219], v103 offset:10240
	ds_read_b64_tr_b16 v[220:221], v133 offset:8192
	ds_read_b64_tr_b16 v[222:223], v133 offset:10240
	ds_read_b64_tr_b16 v[224:225], v134 offset:8192
	ds_read_b64_tr_b16 v[226:227], v134 offset:10240
	ds_read_b64_tr_b16 v[228:229], v135 offset:8192
	ds_read_b64_tr_b16 v[230:231], v135 offset:10240
	v_mfma_f32_16x16x32_bf16 v[176:179], v[160:163], v[8:11], v[0:3]
	v_exp_f32_e32 v136, v136
	v_exp_f32_e32 v137, v137
	v_exp_f32_e32 v138, v138
	v_mfma_f32_16x16x32_bf16 v[232:235], v[168:171], v[8:11], v[0:3]
	v_exp_f32_e32 v139, v139
	v_exp_f32_e32 v140, v140
	v_pk_add_f32 v[242:243], v[136:137], v[138:139]
	v_mfma_f32_16x16x32_bf16 v[176:179], v[164:167], v[16:19], v[176:179]
	v_exp_f32_e32 v141, v141
	v_exp_f32_e32 v142, v142
	v_pk_add_f32 v[242:243], v[242:243], v[140:141]
	v_cvt_pk_bf16_f32 v136, v136, v137
	v_mfma_f32_16x16x32_bf16 v[232:235], v[172:175], v[16:19], v[232:235]
	v_exp_f32_e32 v143, v143
	v_cvt_pk_bf16_f32 v137, v138, v139
	v_cvt_pk_bf16_f32 v138, v140, v141
	v_cvt_pk_bf16_f32 v139, v142, v143
	v_pk_add_f32 v[242:243], v[242:243], v[142:143]
	v_add_f32_e32 v131, v131, v242
	v_add_f32_e32 v131, v131, v243
	s_waitcnt lgkmcnt(0)
; #define LAS __attribute__((address_space(3)))
; template <int NB16> __device__ __forceinline__ float exp_step(f32x4 (&S)[NB16]) {
;     float sum = 0.f;
; #pragma unroll
;     for (int k = 0; k < NB16; ++k)
; #pragma unroll
;         for (int i = 0; i < 4; ++i) { S[k][i] = __builtin_amdgcn_exp2f(S[k][i]); sum += S[k][i]; }
;     return sum;
; }
;     const int l15 = lane & 15, g = lane >> 4, q4 = l15 >> 2;
;     const LAS unsigned char* kb0 = Kt + l15 * 128;
;     const int kx0 = ((g) ^ (l15 & 7)) << 4, kx1 = ((4 + g) ^ (l15 & 7)) << 4;
;     const LAS unsigned char* vrow = Vt + (4 * g + q4) * 128 + (lane & 3) * 8;
;     const int swz = (2 * (g & 1) + (q4 >> 1)) & 3;
;     const f32x4 cinit = (f32x4){negb, negb, negb, negb};
; #pragma unroll
;     for (int gh = 0; gh < 4 / GPB; ++gh) {
;         f32x4 S[GPB][4];
; #pragma unroll
;         for (int kb = 0; kb < 4; ++kb) {
;             const bf16x8 kf0 = *(const LAS bf16x8*)(kb0 + (16 * kb) * 128 + kx0), kf1 = *(const LAS bf16x8*)(kb0 + (16 * kb) * 128 + kx1);
; #pragma unroll
;             for (int gi = 0; gi < GPB; ++gi) { S[gi][kb] = __builtin_amdgcn_mfma_f32_16x16x32_bf16(kf0, qf[GPB * gh + gi][0], cinit, 0, 0, 0);
;                 S[gi][kb] = __builtin_amdgcn_mfma_f32_16x16x32_bf16(kf1, qf[GPB * gh + gi][1], S[gi][kb], 0, 0, 0); } }
;         bf16x8 pf[GPB][2];
; #pragma unroll
;         for (int gi = 0; gi < GPB; ++gi) {
;             if (MASK) {
; #pragma unroll
;                 for (int kb = 0; kb < 4; ++kb)
; #pragma unroll
;                     for (int i = 0; i < 4; ++i) { const int rel = rel0 + 16 * kb + 4 * g + i; S[gi][kb][i] = ((unsigned)(rel + 128) > 256u) ? NEGBIG : S[gi][kb][i]; }
;             }
;             ls[GPB * gh + gi] += exp_step<4>(S[gi]);
;             pf[gi][0] = pack8(S[gi][0], S[gi][1]); pf[gi][1] = pack8(S[gi][2], S[gi][3]);
;         }
; #pragma unroll
;         for (int kc = 0; kc < 2; ++kc)
; #pragma unroll
;             for (int db = 0; db < 4; ++db) {
;                 const LAS unsigned char* va = vrow + ((db ^ swz) << 5) + (32 * kc) * 128;
;                 const bf16x8 vf = cat8(vtr(va), vtr(va + 16 * 128));
; #pragma unroll
;                 for (int gi = 0; gi < GPB; ++gi) O[GPB * gh + gi][db] = __builtin_amdgcn_mfma_f32_16x16x32_bf16(vf, pf[gi][kc], O[GPB * gh + gi][db], 0, 0, 0);
;             }
	v_mfma_f32_16x16x32_bf16 v[244:247], v[160:163], v[20:23], v[0:3]
	v_exp_f32_e32 v176, v176
	v_exp_f32_e32 v177, v177
	v_mfma_f32_16x16x32_bf16 v[248:251], v[168:171], v[20:23], v[0:3]
	v_exp_f32_e32 v178, v178
	v_mfma_f32_16x16x32_bf16 v[244:247], v[164:167], v[24:27], v[244:247]
	v_exp_f32_e32 v179, v179
	v_mfma_f32_16x16x32_bf16 v[248:251], v[172:175], v[24:27], v[248:251]
	v_exp_f32_e32 v232, v232
	v_pk_add_f32 v[242:243], v[176:177], v[178:179]
	v_mfma_f32_16x16x32_bf16 v[64:67], v[216:219], v[136:139], v[64:67]
	v_exp_f32_e32 v233, v233
	v_mfma_f32_16x16x32_bf16 v[60:63], v[220:223], v[136:139], v[60:63]
	v_exp_f32_e32 v234, v234
	v_pk_add_f32 v[242:243], v[242:243], v[232:233]
	v_cvt_pk_bf16_f32 v176, v176, v177
	v_mfma_f32_16x16x32_bf16 v[56:59], v[224:227], v[136:139], v[56:59]
	v_exp_f32_e32 v235, v235
	v_cvt_pk_bf16_f32 v177, v178, v179
	v_mfma_f32_16x16x32_bf16 v[52:55], v[228:231], v[136:139], v[52:55]
	v_cvt_pk_bf16_f32 v178, v232, v233
	v_cvt_pk_bf16_f32 v179, v234, v235
	v_pk_add_f32 v[242:243], v[242:243], v[234:235]
	v_add_f32_e32 v130, v130, v242
	v_add_f32_e32 v130, v130, v243
	v_mfma_f32_16x16x32_bf16 v[136:139], v[160:163], v[28:31], v[0:3]
	v_exp_f32_e32 v244, v244
	v_exp_f32_e32 v245, v245
	v_mfma_f32_16x16x32_bf16 v[140:143], v[168:171], v[28:31], v[0:3]
	v_exp_f32_e32 v246, v246
	v_mfma_f32_16x16x32_bf16 v[136:139], v[164:167], v[32:35], v[136:139]
	v_exp_f32_e32 v247, v247
	v_mfma_f32_16x16x32_bf16 v[140:143], v[172:175], v[32:35], v[140:143]
	v_exp_f32_e32 v248, v248
	v_pk_add_f32 v[242:243], v[244:245], v[246:247]
	v_mfma_f32_16x16x32_bf16 v[48:51], v[216:219], v[176:179], v[48:51]
	v_exp_f32_e32 v249, v249
	v_mfma_f32_16x16x32_bf16 v[44:47], v[220:223], v[176:179], v[44:47]
	v_exp_f32_e32 v250, v250
	v_pk_add_f32 v[242:243], v[242:243], v[248:249]
	v_cvt_pk_bf16_f32 v244, v244, v245
	v_mfma_f32_16x16x32_bf16 v[40:43], v[224:227], v[176:179], v[40:43]
	v_exp_f32_e32 v251, v251
	v_cvt_pk_bf16_f32 v245, v246, v247
	v_mfma_f32_16x16x32_bf16 v[36:39], v[228:231], v[176:179], v[36:39]
	v_cvt_pk_bf16_f32 v246, v248, v249
	v_cvt_pk_bf16_f32 v247, v250, v251
	v_pk_add_f32 v[242:243], v[242:243], v[250:251]
	v_add_f32_e32 v129, v129, v242
	v_add_f32_e32 v129, v129, v243
	ds_read_b64_tr_b16 v[160:161], v103 offset:12288
	ds_read_b64_tr_b16 v[162:163], v103 offset:14336
	ds_read_b64_tr_b16 v[164:165], v133 offset:12288
	ds_read_b64_tr_b16 v[166:167], v133 offset:14336
	ds_read_b64_tr_b16 v[168:169], v134 offset:12288
	ds_read_b64_tr_b16 v[170:171], v134 offset:14336
	ds_read_b64_tr_b16 v[172:173], v135 offset:12288
	ds_read_b64_tr_b16 v[174:175], v135 offset:14336
	v_mfma_f32_16x16x32_bf16 v[176:179], v[104:107], v[4:7], v[0:3]
	v_exp_f32_e32 v136, v136
	v_exp_f32_e32 v137, v137
	v_mfma_f32_16x16x32_bf16 v[232:235], v[112:115], v[4:7], v[0:3]
	v_exp_f32_e32 v138, v138
	v_mfma_f32_16x16x32_bf16 v[176:179], v[108:111], v[12:15], v[176:179]
	v_exp_f32_e32 v139, v139
	v_mfma_f32_16x16x32_bf16 v[232:235], v[116:119], v[12:15], v[232:235]
	v_exp_f32_e32 v140, v140
	v_pk_add_f32 v[242:243], v[136:137], v[138:139]
	v_mfma_f32_16x16x32_bf16 v[72:75], v[216:219], v[244:247], v[72:75]
	v_exp_f32_e32 v141, v141
	v_mfma_f32_16x16x32_bf16 v[84:87], v[220:223], v[244:247], v[84:87]
	v_exp_f32_e32 v142, v142
	v_pk_add_f32 v[242:243], v[242:243], v[140:141]
	v_cvt_pk_bf16_f32 v136, v136, v137
	v_mfma_f32_16x16x32_bf16 v[88:91], v[224:227], v[244:247], v[88:91]
	v_exp_f32_e32 v143, v143
	v_cvt_pk_bf16_f32 v137, v138, v139
	v_mfma_f32_16x16x32_bf16 v[96:99], v[228:231], v[244:247], v[96:99]
	v_cvt_pk_bf16_f32 v138, v140, v141
	v_cvt_pk_bf16_f32 v139, v142, v143
	v_pk_add_f32 v[242:243], v[242:243], v[142:143]
	v_add_f32_e32 v128, v128, v242
	v_add_f32_e32 v128, v128, v243
	v_mfma_f32_16x16x32_bf16 v[244:247], v[104:107], v[8:11], v[0:3]
	v_exp_f32_e32 v176, v176
	v_exp_f32_e32 v177, v177
	v_mfma_f32_16x16x32_bf16 v[248:251], v[112:115], v[8:11], v[0:3]
	v_exp_f32_e32 v178, v178
	v_mfma_f32_16x16x32_bf16 v[244:247], v[108:111], v[16:19], v[244:247]
	v_exp_f32_e32 v179, v179
	v_mfma_f32_16x16x32_bf16 v[248:251], v[116:119], v[16:19], v[248:251]
	v_exp_f32_e32 v232, v232
	v_pk_add_f32 v[242:243], v[176:177], v[178:179]
	v_mfma_f32_16x16x32_bf16 v[68:71], v[216:219], v[136:139], v[68:71]
	v_exp_f32_e32 v233, v233
	v_mfma_f32_16x16x32_bf16 v[76:79], v[220:223], v[136:139], v[76:79]
	v_exp_f32_e32 v234, v234
	v_pk_add_f32 v[242:243], v[242:243], v[232:233]
	v_cvt_pk_bf16_f32 v176, v176, v177
	v_mfma_f32_16x16x32_bf16 v[80:83], v[224:227], v[136:139], v[80:83]
	v_exp_f32_e32 v235, v235
	v_cvt_pk_bf16_f32 v177, v178, v179
	v_mfma_f32_16x16x32_bf16 v[92:95], v[228:231], v[136:139], v[92:95]
	v_cvt_pk_bf16_f32 v178, v232, v233
	v_cvt_pk_bf16_f32 v179, v234, v235
	v_pk_add_f32 v[242:243], v[242:243], v[234:235]
	v_add_f32_e32 v131, v131, v242
	v_add_f32_e32 v131, v131, v243
	s_waitcnt lgkmcnt(0)
; #define LAS __attribute__((address_space(3)))
; template <int NB16> __device__ __forceinline__ float exp_step(f32x4 (&S)[NB16]) {
;     float sum = 0.f;
; #pragma unroll
;     for (int k = 0; k < NB16; ++k)
; #pragma unroll
;         for (int i = 0; i < 4; ++i) { S[k][i] = __builtin_amdgcn_exp2f(S[k][i]); sum += S[k][i]; }
;     return sum;
; }
;     const int l15 = lane & 15, g = lane >> 4, q4 = l15 >> 2;
;     const LAS unsigned char* kb0 = Kt + l15 * 128;
;     const int kx0 = ((g) ^ (l15 & 7)) << 4, kx1 = ((4 + g) ^ (l15 & 7)) << 4;
;     const LAS unsigned char* vrow = Vt + (4 * g + q4) * 128 + (lane & 3) * 8;
;     const int swz = (2 * (g & 1) + (q4 >> 1)) & 3;
;     const f32x4 cinit = (f32x4){negb, negb, negb, negb};
; #pragma unroll
;     for (int gh = 0; gh < 4 / GPB; ++gh) {
;         f32x4 S[GPB][4];
; #pragma unroll
;         for (int kb = 0; kb < 4; ++kb) {
;             const bf16x8 kf0 = *(const LAS bf16x8*)(kb0 + (16 * kb) * 128 + kx0), kf1 = *(const LAS bf16x8*)(kb0 + (16 * kb) * 128 + kx1);
; #pragma unroll
;             for (int gi = 0; gi < GPB; ++gi) { S[gi][kb] = __builtin_amdgcn_mfma_f32_16x16x32_bf16(kf0, qf[GPB * gh + gi][0], cinit, 0, 0, 0);
;                 S[gi][kb] = __builtin_amdgcn_mfma_f32_16x16x32_bf16(kf1, qf[GPB * gh + gi][1], S[gi][kb], 0, 0, 0); } }
;         bf16x8 pf[GPB][2];
; #pragma unroll
;         for (int gi = 0; gi < GPB; ++gi) {
;             if (MASK) {
; #pragma unroll
;                 for (int kb = 0; kb < 4; ++kb)
; #pragma unroll
;                     for (int i = 0; i < 4; ++i) { const int rel = rel0 + 16 * kb + 4 * g + i; S[gi][kb][i] = ((unsigned)(rel + 128) > 256u) ? NEGBIG : S[gi][kb][i]; }
;             }
;             ls[GPB * gh + gi] += exp_step<4>(S[gi]);
;             pf[gi][0] = pack8(S[gi][0], S[gi][1]); pf[gi][1] = pack8(S[gi][2], S[gi][3]);
;         }
; #pragma unroll
;         for (int kc = 0; kc < 2; ++kc)
; #pragma unroll
;             for (int db = 0; db < 4; ++db) {
;                 const LAS unsigned char* va = vrow + ((db ^ swz) << 5) + (32 * kc) * 128;
;                 const bf16x8 vf = cat8(vtr(va), vtr(va + 16 * 128));
; #pragma unroll
;                 for (int gi = 0; gi < GPB; ++gi) O[GPB * gh + gi][db] = __builtin_amdgcn_mfma_f32_16x16x32_bf16(vf, pf[gi][kc], O[GPB * gh + gi][db], 0, 0, 0);
;             }
	v_mfma_f32_16x16x32_bf16 v[136:139], v[104:107], v[20:23], v[0:3]
	v_exp_f32_e32 v244, v244
	v_exp_f32_e32 v245, v245
	v_mfma_f32_16x16x32_bf16 v[140:143], v[112:115], v[20:23], v[0:3]
	v_exp_f32_e32 v246, v246
	v_mfma_f32_16x16x32_bf16 v[136:139], v[108:111], v[24:27], v[136:139]
	v_exp_f32_e32 v247, v247
	v_mfma_f32_16x16x32_bf16 v[140:143], v[116:119], v[24:27], v[140:143]
	v_exp_f32_e32 v248, v248
	v_pk_add_f32 v[242:243], v[244:245], v[246:247]
	v_mfma_f32_16x16x32_bf16 v[64:67], v[160:163], v[176:179], v[64:67]
	v_exp_f32_e32 v249, v249
	v_mfma_f32_16x16x32_bf16 v[60:63], v[164:167], v[176:179], v[60:63]
	v_exp_f32_e32 v250, v250
	v_pk_add_f32 v[242:243], v[242:243], v[248:249]
	v_cvt_pk_bf16_f32 v244, v244, v245
	v_mfma_f32_16x16x32_bf16 v[56:59], v[168:171], v[176:179], v[56:59]
	v_exp_f32_e32 v251, v251
	v_cvt_pk_bf16_f32 v245, v246, v247
	v_mfma_f32_16x16x32_bf16 v[52:55], v[172:175], v[176:179], v[52:55]
	v_cvt_pk_bf16_f32 v246, v248, v249
	v_cvt_pk_bf16_f32 v247, v250, v251
	v_pk_add_f32 v[242:243], v[242:243], v[250:251]
	v_add_f32_e32 v130, v130, v242
	v_add_f32_e32 v130, v130, v243
	v_mfma_f32_16x16x32_bf16 v[176:179], v[104:107], v[28:31], v[0:3]
	v_exp_f32_e32 v136, v136
	v_exp_f32_e32 v137, v137
	v_mfma_f32_16x16x32_bf16 v[232:235], v[112:115], v[28:31], v[0:3]
	v_exp_f32_e32 v138, v138
	v_mfma_f32_16x16x32_bf16 v[176:179], v[108:111], v[32:35], v[176:179]
	v_exp_f32_e32 v139, v139
	v_mfma_f32_16x16x32_bf16 v[232:235], v[116:119], v[32:35], v[232:235]
	v_exp_f32_e32 v140, v140
	v_pk_add_f32 v[242:243], v[136:137], v[138:139]
	v_mfma_f32_16x16x32_bf16 v[48:51], v[160:163], v[244:247], v[48:51]
	v_exp_f32_e32 v141, v141
	v_mfma_f32_16x16x32_bf16 v[44:47], v[164:167], v[244:247], v[44:47]
	v_exp_f32_e32 v142, v142
	v_pk_add_f32 v[242:243], v[242:243], v[140:141]
	v_cvt_pk_bf16_f32 v136, v136, v137
	v_mfma_f32_16x16x32_bf16 v[40:43], v[168:171], v[244:247], v[40:43]
	v_exp_f32_e32 v143, v143
	v_cvt_pk_bf16_f32 v137, v138, v139
	v_mfma_f32_16x16x32_bf16 v[36:39], v[172:175], v[244:247], v[36:39]
	v_cvt_pk_bf16_f32 v138, v140, v141
	v_cvt_pk_bf16_f32 v139, v142, v143
	v_pk_add_f32 v[242:243], v[242:243], v[142:143]
	v_add_f32_e32 v129, v129, v242
	v_add_f32_e32 v129, v129, v243
	v_mfma_f32_16x16x32_bf16 v[72:75], v[160:163], v[136:139], v[72:75]
	v_exp_f32_e32 v176, v176
	v_exp_f32_e32 v177, v177
	v_exp_f32_e32 v178, v178
	v_mfma_f32_16x16x32_bf16 v[84:87], v[164:167], v[136:139], v[84:87]
	v_exp_f32_e32 v179, v179
	v_exp_f32_e32 v232, v232
	v_pk_add_f32 v[242:243], v[176:177], v[178:179]
	v_mfma_f32_16x16x32_bf16 v[88:91], v[168:171], v[136:139], v[88:91]
	v_exp_f32_e32 v233, v233
	v_exp_f32_e32 v234, v234
	v_pk_add_f32 v[242:243], v[242:243], v[232:233]
	v_cvt_pk_bf16_f32 v176, v176, v177
	v_mfma_f32_16x16x32_bf16 v[96:99], v[172:175], v[136:139], v[96:99]
	v_exp_f32_e32 v235, v235
	v_cvt_pk_bf16_f32 v177, v178, v179
	v_cvt_pk_bf16_f32 v178, v232, v233
	v_cvt_pk_bf16_f32 v179, v234, v235
	v_pk_add_f32 v[242:243], v[242:243], v[234:235]
	v_add_f32_e32 v128, v128, v242
	v_add_f32_e32 v128, v128, v243
	v_mfma_f32_16x16x32_bf16 v[68:71], v[160:163], v[176:179], v[68:71]
	v_mfma_f32_16x16x32_bf16 v[76:79], v[164:167], v[176:179], v[76:79]
	v_mfma_f32_16x16x32_bf16 v[80:83], v[168:171], v[176:179], v[80:83]
	v_mfma_f32_16x16x32_bf16 v[92:95], v[172:175], v[176:179], v[92:95]
	s_addk_i32 s1, 0x4000
	s_add_u32 s7, s7, 64
	s_addc_u32 s8, s8, 0
	s_add_i32 s6, s6, 1
	s_waitcnt vmcnt(4)
	s_barrier
	s_cmp_lt_u32 s6, s46
	s_cselect_b32 s11, s8, 0
	s_cselect_b32 s10, s7, s82
	s_lshl_b64 s[10:11], s[10:11], 9
	s_add_u32 s12, s67, s10
	s_addc_u32 s13, s4, s11
	s_add_u32 s10, s5, s10
	s_addc_u32 s11, s58, s11
	s_add_i32 s9, s40, s1
	s_mov_b32 s15, m0
	s_mov_b32 m0, s9
	s_nop 0
	global_load_lds_dwordx4 v212, s[12:13]
	s_mov_b32 m0, s15
	s_add_i32 s14, s9, 0x2000
	s_mov_b32 s9, m0
	s_mov_b32 m0, s14
	s_nop 0
	global_load_lds_dwordx4 v213, s[10:11]
	s_mov_b32 m0, s9
	s_add_i32 s34, s1, 0x4000
	v_add_u32_e32 v100, s34, v191
	v_add3_u32 v135, s34, v203, v198
	v_add_u32_e32 v102, v100, v193
	v_add_u32_e32 v100, v100, v192
	ds_read_b128 v[160:163], v100
	ds_read_b128 v[164:167], v102
	ds_read_b128 v[168:171], v100 offset:2048
	ds_read_b128 v[172:175], v102 offset:2048
	ds_read_b128 v[104:107], v100 offset:4096
	ds_read_b128 v[108:111], v102 offset:4096
	ds_read_b128 v[112:115], v100 offset:6144
	ds_read_b128 v[116:119], v102 offset:6144
	v_add_u32_e32 v103, v135, v199
	v_add_u32_e32 v133, v135, v200
	v_add_u32_e32 v134, v135, v201
	v_add_u32_e32 v135, v135, v202
	s_waitcnt lgkmcnt(4)
	v_mfma_f32_16x16x32_bf16 v[136:139], v[160:163], v[4:7], v[0:3]
	v_mfma_f32_16x16x32_bf16 v[140:143], v[168:171], v[4:7], v[0:3]
	v_mfma_f32_16x16x32_bf16 v[136:139], v[164:167], v[12:15], v[136:139]
	v_mfma_f32_16x16x32_bf16 v[140:143], v[172:175], v[12:15], v[140:143]
	ds_read_b64_tr_b16 v[216:217], v103 offset:8192
	ds_read_b64_tr_b16 v[218:219], v103 offset:10240
	ds_read_b64_tr_b16 v[220:221], v133 offset:8192
	ds_read_b64_tr_b16 v[222:223], v133 offset:10240
	ds_read_b64_tr_b16 v[224:225], v134 offset:8192
	ds_read_b64_tr_b16 v[226:227], v134 offset:10240
	ds_read_b64_tr_b16 v[228:229], v135 offset:8192
	ds_read_b64_tr_b16 v[230:231], v135 offset:10240
	v_mfma_f32_16x16x32_bf16 v[176:179], v[160:163], v[8:11], v[0:3]
	v_exp_f32_e32 v136, v136
	v_exp_f32_e32 v137, v137
	v_exp_f32_e32 v138, v138
	v_mfma_f32_16x16x32_bf16 v[232:235], v[168:171], v[8:11], v[0:3]
	v_exp_f32_e32 v139, v139
	v_exp_f32_e32 v140, v140
	v_pk_add_f32 v[242:243], v[136:137], v[138:139]
	v_mfma_f32_16x16x32_bf16 v[176:179], v[164:167], v[16:19], v[176:179]
	v_exp_f32_e32 v141, v141
	v_exp_f32_e32 v142, v142
	v_pk_add_f32 v[242:243], v[242:243], v[140:141]
	v_cvt_pk_bf16_f32 v136, v136, v137
	v_mfma_f32_16x16x32_bf16 v[232:235], v[172:175], v[16:19], v[232:235]
	v_exp_f32_e32 v143, v143
	v_cvt_pk_bf16_f32 v137, v138, v139
	v_cvt_pk_bf16_f32 v138, v140, v141
	v_cvt_pk_bf16_f32 v139, v142, v143
	v_pk_add_f32 v[242:243], v[242:243], v[142:143]
	v_add_f32_e32 v131, v131, v242
	v_add_f32_e32 v131, v131, v243
	s_waitcnt lgkmcnt(0)
; #define LAS __attribute__((address_space(3)))
; template <int NB16> __device__ __forceinline__ float exp_step(f32x4 (&S)[NB16]) {
;     float sum = 0.f;
; #pragma unroll
;     for (int k = 0; k < NB16; ++k)
; #pragma unroll
;         for (int i = 0; i < 4; ++i) { S[k][i] = __builtin_amdgcn_exp2f(S[k][i]); sum += S[k][i]; }
;     return sum;
; }
;     const int l15 = lane & 15, g = lane >> 4, q4 = l15 >> 2;
;     const LAS unsigned char* kb0 = Kt + l15 * 128;
;     const int kx0 = ((g) ^ (l15 & 7)) << 4, kx1 = ((4 + g) ^ (l15 & 7)) << 4;
;     const LAS unsigned char* vrow = Vt + (4 * g + q4) * 128 + (lane & 3) * 8;
;     const int swz = (2 * (g & 1) + (q4 >> 1)) & 3;
;     const f32x4 cinit = (f32x4){negb, negb, negb, negb};
; #pragma unroll
;     for (int gh = 0; gh < 4 / GPB; ++gh) {
;         f32x4 S[GPB][4];
; #pragma unroll
;         for (int kb = 0; kb < 4; ++kb) {
;             const bf16x8 kf0 = *(const LAS bf16x8*)(kb0 + (16 * kb) * 128 + kx0), kf1 = *(const LAS bf16x8*)(kb0 + (16 * kb) * 128 + kx1);
; #pragma unroll
;             for (int gi = 0; gi < GPB; ++gi) { S[gi][kb] = __builtin_amdgcn_mfma_f32_16x16x32_bf16(kf0, qf[GPB * gh + gi][0], cinit, 0, 0, 0);
;                 S[gi][kb] = __builtin_amdgcn_mfma_f32_16x16x32_bf16(kf1, qf[GPB * gh + gi][1], S[gi][kb], 0, 0, 0); } }
;         bf16x8 pf[GPB][2];
; #pragma unroll
;         for (int gi = 0; gi < GPB; ++gi) {
;             if (MASK) {
; #pragma unroll
;                 for (int kb = 0; kb < 4; ++kb)
; #pragma unroll
;                     for (int i = 0; i < 4; ++i) { const int rel = rel0 + 16 * kb + 4 * g + i; S[gi][kb][i] = ((unsigned)(rel + 128) > 256u) ? NEGBIG : S[gi][kb][i]; }
;             }
;             ls[GPB * gh + gi] += exp_step<4>(S[gi]);
;             pf[gi][0] = pack8(S[gi][0], S[gi][1]); pf[gi][1] = pack8(S[gi][2], S[gi][3]);
;         }
; #pragma unroll
;         for (int kc = 0; kc < 2; ++kc)
; #pragma unroll
;             for (int db = 0; db < 4; ++db) {
;                 const LAS unsigned char* va = vrow + ((db ^ swz) << 5) + (32 * kc) * 128;
;                 const bf16x8 vf = cat8(vtr(va), vtr(va + 16 * 128));
; #pragma unroll
;                 for (int gi = 0; gi < GPB; ++gi) O[GPB * gh + gi][db] = __builtin_amdgcn_mfma_f32_16x16x32_bf16(vf, pf[gi][kc], O[GPB * gh + gi][db], 0, 0, 0);
;             }
	v_mfma_f32_16x16x32_bf16 v[244:247], v[160:163], v[20:23], v[0:3]
	v_exp_f32_e32 v176, v176
	v_exp_f32_e32 v177, v177
	v_mfma_f32_16x16x32_bf16 v[248:251], v[168:171], v[20:23], v[0:3]
	v_exp_f32_e32 v178, v178
	v_mfma_f32_16x16x32_bf16 v[244:247], v[164:167], v[24:27], v[244:247]
	v_exp_f32_e32 v179, v179
	v_mfma_f32_16x16x32_bf16 v[248:251], v[172:175], v[24:27], v[248:251]
	v_exp_f32_e32 v232, v232
	v_pk_add_f32 v[242:243], v[176:177], v[178:179]
	v_mfma_f32_16x16x32_bf16 v[64:67], v[216:219], v[136:139], v[64:67]
	v_exp_f32_e32 v233, v233
	v_mfma_f32_16x16x32_bf16 v[60:63], v[220:223], v[136:139], v[60:63]
	v_exp_f32_e32 v234, v234
	v_pk_add_f32 v[242:243], v[242:243], v[232:233]
	v_cvt_pk_bf16_f32 v176, v176, v177
	v_mfma_f32_16x16x32_bf16 v[56:59], v[224:227], v[136:139], v[56:59]
	v_exp_f32_e32 v235, v235
	v_cvt_pk_bf16_f32 v177, v178, v179
	v_mfma_f32_16x16x32_bf16 v[52:55], v[228:231], v[136:139], v[52:55]
	v_cvt_pk_bf16_f32 v178, v232, v233
	v_cvt_pk_bf16_f32 v179, v234, v235
	v_pk_add_f32 v[242:243], v[242:243], v[234:235]
	v_add_f32_e32 v130, v130, v242
	v_add_f32_e32 v130, v130, v243
	v_mfma_f32_16x16x32_bf16 v[136:139], v[160:163], v[28:31], v[0:3]
	v_exp_f32_e32 v244, v244
	v_exp_f32_e32 v245, v245
	v_mfma_f32_16x16x32_bf16 v[140:143], v[168:171], v[28:31], v[0:3]
	v_exp_f32_e32 v246, v246
	v_mfma_f32_16x16x32_bf16 v[136:139], v[164:167], v[32:35], v[136:139]
	v_exp_f32_e32 v247, v247
	v_mfma_f32_16x16x32_bf16 v[140:143], v[172:175], v[32:35], v[140:143]
	v_exp_f32_e32 v248, v248
	v_pk_add_f32 v[242:243], v[244:245], v[246:247]
	v_mfma_f32_16x16x32_bf16 v[48:51], v[216:219], v[176:179], v[48:51]
	v_exp_f32_e32 v249, v249
	v_mfma_f32_16x16x32_bf16 v[44:47], v[220:223], v[176:179], v[44:47]
	v_exp_f32_e32 v250, v250
	v_pk_add_f32 v[242:243], v[242:243], v[248:249]
	v_cvt_pk_bf16_f32 v244, v244, v245
	v_mfma_f32_16x16x32_bf16 v[40:43], v[224:227], v[176:179], v[40:43]
	v_exp_f32_e32 v251, v251
	v_cvt_pk_bf16_f32 v245, v246, v247
	v_mfma_f32_16x16x32_bf16 v[36:39], v[228:231], v[176:179], v[36:39]
	v_cvt_pk_bf16_f32 v246, v248, v249
	v_cvt_pk_bf16_f32 v247, v250, v251
	v_pk_add_f32 v[242:243], v[242:243], v[250:251]
	v_add_f32_e32 v129, v129, v242
	v_add_f32_e32 v129, v129, v243
	ds_read_b64_tr_b16 v[160:161], v103 offset:12288
	ds_read_b64_tr_b16 v[162:163], v103 offset:14336
	ds_read_b64_tr_b16 v[164:165], v133 offset:12288
	ds_read_b64_tr_b16 v[166:167], v133 offset:14336
	ds_read_b64_tr_b16 v[168:169], v134 offset:12288
	ds_read_b64_tr_b16 v[170:171], v134 offset:14336
	ds_read_b64_tr_b16 v[172:173], v135 offset:12288
	ds_read_b64_tr_b16 v[174:175], v135 offset:14336
	v_mfma_f32_16x16x32_bf16 v[176:179], v[104:107], v[4:7], v[0:3]
	v_exp_f32_e32 v136, v136
	v_exp_f32_e32 v137, v137
	v_mfma_f32_16x16x32_bf16 v[232:235], v[112:115], v[4:7], v[0:3]
	v_exp_f32_e32 v138, v138
	v_mfma_f32_16x16x32_bf16 v[176:179], v[108:111], v[12:15], v[176:179]
	v_exp_f32_e32 v139, v139
	v_mfma_f32_16x16x32_bf16 v[232:235], v[116:119], v[12:15], v[232:235]
	v_exp_f32_e32 v140, v140
	v_pk_add_f32 v[242:243], v[136:137], v[138:139]
	v_mfma_f32_16x16x32_bf16 v[72:75], v[216:219], v[244:247], v[72:75]
	v_exp_f32_e32 v141, v141
	v_mfma_f32_16x16x32_bf16 v[84:87], v[220:223], v[244:247], v[84:87]
	v_exp_f32_e32 v142, v142
	v_pk_add_f32 v[242:243], v[242:243], v[140:141]
	v_cvt_pk_bf16_f32 v136, v136, v137
	v_mfma_f32_16x16x32_bf16 v[88:91], v[224:227], v[244:247], v[88:91]
	v_exp_f32_e32 v143, v143
	v_cvt_pk_bf16_f32 v137, v138, v139
	v_mfma_f32_16x16x32_bf16 v[96:99], v[228:231], v[244:247], v[96:99]
	v_cvt_pk_bf16_f32 v138, v140, v141
	v_cvt_pk_bf16_f32 v139, v142, v143
	v_pk_add_f32 v[242:243], v[242:243], v[142:143]
	v_add_f32_e32 v128, v128, v242
	v_add_f32_e32 v128, v128, v243
	v_mfma_f32_16x16x32_bf16 v[244:247], v[104:107], v[8:11], v[0:3]
	v_exp_f32_e32 v176, v176
	v_exp_f32_e32 v177, v177
	v_mfma_f32_16x16x32_bf16 v[248:251], v[112:115], v[8:11], v[0:3]
	v_exp_f32_e32 v178, v178
	v_mfma_f32_16x16x32_bf16 v[244:247], v[108:111], v[16:19], v[244:247]
	v_exp_f32_e32 v179, v179
	v_mfma_f32_16x16x32_bf16 v[248:251], v[116:119], v[16:19], v[248:251]
	v_exp_f32_e32 v232, v232
	v_pk_add_f32 v[242:243], v[176:177], v[178:179]
	v_mfma_f32_16x16x32_bf16 v[68:71], v[216:219], v[136:139], v[68:71]
	v_exp_f32_e32 v233, v233
	v_mfma_f32_16x16x32_bf16 v[76:79], v[220:223], v[136:139], v[76:79]
	v_exp_f32_e32 v234, v234
	v_pk_add_f32 v[242:243], v[242:243], v[232:233]
	v_cvt_pk_bf16_f32 v176, v176, v177
	v_mfma_f32_16x16x32_bf16 v[80:83], v[224:227], v[136:139], v[80:83]
	v_exp_f32_e32 v235, v235
	v_cvt_pk_bf16_f32 v177, v178, v179
	v_mfma_f32_16x16x32_bf16 v[92:95], v[228:231], v[136:139], v[92:95]
	v_cvt_pk_bf16_f32 v178, v232, v233
	v_cvt_pk_bf16_f32 v179, v234, v235
	v_pk_add_f32 v[242:243], v[242:243], v[234:235]
	v_add_f32_e32 v131, v131, v242
	v_add_f32_e32 v131, v131, v243
	s_waitcnt lgkmcnt(0)
; #define LAS __attribute__((address_space(3)))
;     const int l15 = lane & 15, g = lane >> 4, q4 = l15 >> 2;
;     const LAS unsigned char* kb0 = Kt + l15 * 128;
;     const int kx0 = ((g) ^ (l15 & 7)) << 4, kx1 = ((4 + g) ^ (l15 & 7)) << 4;
;     const LAS unsigned char* vrow = Vt + (4 * g + q4) * 128 + (lane & 3) * 8;
;     const int swz = (2 * (g & 1) + (q4 >> 1)) & 3;
;     const f32x4 cinit = (f32x4){negb, negb, negb, negb};
; #pragma unroll
;     for (int gh = 0; gh < 4 / GPB; ++gh) {
;         f32x4 S[GPB][4];
; #pragma unroll
;         for (int kb = 0; kb < 4; ++kb) {
;             const bf16x8 kf0 = *(const LAS bf16x8*)(kb0 + (16 * kb) * 128 + kx0), kf1 = *(const LAS bf16x8*)(kb0 + (16 * kb) * 128 + kx1);
; #pragma unroll
;             for (int gi = 0; gi < GPB; ++gi) { S[gi][kb] = __builtin_amdgcn_mfma_f32_16x16x32_bf16(kf0, qf[GPB * gh + gi][0], cinit, 0, 0, 0);
;                 S[gi][kb] = __builtin_amdgcn_mfma_f32_16x16x32_bf16(kf1, qf[GPB * gh + gi][1], S[gi][kb], 0, 0, 0); } }
;         bf16x8 pf[GPB][2];
; #pragma unroll
;         for (int gi = 0; gi < GPB; ++gi) {
;             if (MASK) {
; #pragma unroll
;                 for (int kb = 0; kb < 4; ++kb)
; #pragma unroll
;                     for (int i = 0; i < 4; ++i) { const int rel = rel0 + 16 * kb + 4 * g + i; S[gi][kb][i] = ((unsigned)(rel + 128) > 256u) ? NEGBIG : S[gi][kb][i]; }
;             }
;             ls[GPB * gh + gi] += exp_step<4>(S[gi]);
;             pf[gi][0] = pack8(S[gi][0], S[gi][1]); pf[gi][1] = pack8(S[gi][2], S[gi][3]);
;         }
; #pragma unroll
;         for (int kc = 0; kc < 2; ++kc)
; #pragma unroll
;             for (int db = 0; db < 4; ++db) {
;                 const LAS unsigned char* va = vrow + ((db ^ swz) << 5) + (32 * kc) * 128;
;                 const bf16x8 vf = cat8(vtr(va), vtr(va + 16 * 128));
; #pragma unroll
;                 for (int gi = 0; gi < GPB; ++gi) O[GPB * gh + gi][db] = __builtin_amdgcn_mfma_f32_16x16x32_bf16(vf, pf[gi][kc], O[GPB * gh + gi][db], 0, 0, 0);
;             }
;         if (SB == 1) __builtin_amdgcn_sched_barrier(0); else if (SB == 2) __builtin_amdgcn_sched_barrier(0x108);
;     }
; }
; __device__ __forceinline__ void swa_phase(LAS unsigned char* lds, const bf16_t* Q, const bf16_t* K, const bf16_t* V, bf16_t* Ob, const float* sink, float negb) {
;     ...
;         for (int t = 0; t < 4; ++t) {
	v_mfma_f32_16x16x32_bf16 v[136:139], v[104:107], v[20:23], v[0:3]
	v_exp_f32_e32 v244, v244
	v_exp_f32_e32 v245, v245
	v_mfma_f32_16x16x32_bf16 v[140:143], v[112:115], v[20:23], v[0:3]
	v_exp_f32_e32 v246, v246
	v_mfma_f32_16x16x32_bf16 v[136:139], v[108:111], v[24:27], v[136:139]
	v_exp_f32_e32 v247, v247
	v_mfma_f32_16x16x32_bf16 v[140:143], v[116:119], v[24:27], v[140:143]
	v_exp_f32_e32 v248, v248
	v_pk_add_f32 v[242:243], v[244:245], v[246:247]
	v_mfma_f32_16x16x32_bf16 v[64:67], v[160:163], v[176:179], v[64:67]
	v_exp_f32_e32 v249, v249
	v_mfma_f32_16x16x32_bf16 v[60:63], v[164:167], v[176:179], v[60:63]
	v_exp_f32_e32 v250, v250
	v_pk_add_f32 v[242:243], v[242:243], v[248:249]
	v_cvt_pk_bf16_f32 v244, v244, v245
	v_mfma_f32_16x16x32_bf16 v[56:59], v[168:171], v[176:179], v[56:59]
	v_exp_f32_e32 v251, v251
	v_cvt_pk_bf16_f32 v245, v246, v247
	v_mfma_f32_16x16x32_bf16 v[52:55], v[172:175], v[176:179], v[52:55]
	v_cvt_pk_bf16_f32 v246, v248, v249
	v_cvt_pk_bf16_f32 v247, v250, v251
	v_pk_add_f32 v[242:243], v[242:243], v[250:251]
	v_add_f32_e32 v130, v130, v242
	v_add_f32_e32 v130, v130, v243
	v_mfma_f32_16x16x32_bf16 v[176:179], v[104:107], v[28:31], v[0:3]
	v_exp_f32_e32 v136, v136
	v_exp_f32_e32 v137, v137
	v_mfma_f32_16x16x32_bf16 v[232:235], v[112:115], v[28:31], v[0:3]
	v_exp_f32_e32 v138, v138
	v_mfma_f32_16x16x32_bf16 v[176:179], v[108:111], v[32:35], v[176:179]
	v_exp_f32_e32 v139, v139
	v_mfma_f32_16x16x32_bf16 v[232:235], v[116:119], v[32:35], v[232:235]
	v_exp_f32_e32 v140, v140
	v_pk_add_f32 v[242:243], v[136:137], v[138:139]
	v_mfma_f32_16x16x32_bf16 v[48:51], v[160:163], v[244:247], v[48:51]
	v_exp_f32_e32 v141, v141
	v_mfma_f32_16x16x32_bf16 v[44:47], v[164:167], v[244:247], v[44:47]
	v_exp_f32_e32 v142, v142
	v_pk_add_f32 v[242:243], v[242:243], v[140:141]
	v_cvt_pk_bf16_f32 v136, v136, v137
	v_mfma_f32_16x16x32_bf16 v[40:43], v[168:171], v[244:247], v[40:43]
	v_exp_f32_e32 v143, v143
	v_cvt_pk_bf16_f32 v137, v138, v139
	v_mfma_f32_16x16x32_bf16 v[36:39], v[172:175], v[244:247], v[36:39]
	v_cvt_pk_bf16_f32 v138, v140, v141
	v_cvt_pk_bf16_f32 v139, v142, v143
	v_pk_add_f32 v[242:243], v[242:243], v[142:143]
	v_add_f32_e32 v129, v129, v242
	v_add_f32_e32 v129, v129, v243
	v_mfma_f32_16x16x32_bf16 v[72:75], v[160:163], v[136:139], v[72:75]
	v_exp_f32_e32 v176, v176
	v_exp_f32_e32 v177, v177
	v_exp_f32_e32 v178, v178
	v_mfma_f32_16x16x32_bf16 v[84:87], v[164:167], v[136:139], v[84:87]
	v_exp_f32_e32 v179, v179
	v_exp_f32_e32 v232, v232
	v_pk_add_f32 v[242:243], v[176:177], v[178:179]
	v_mfma_f32_16x16x32_bf16 v[88:91], v[168:171], v[136:139], v[88:91]
	v_exp_f32_e32 v233, v233
	v_exp_f32_e32 v234, v234
	v_pk_add_f32 v[242:243], v[242:243], v[232:233]
	v_cvt_pk_bf16_f32 v176, v176, v177
	v_mfma_f32_16x16x32_bf16 v[96:99], v[172:175], v[136:139], v[96:99]
	v_exp_f32_e32 v235, v235
	v_cvt_pk_bf16_f32 v177, v178, v179
	v_cvt_pk_bf16_f32 v178, v232, v233
	v_cvt_pk_bf16_f32 v179, v234, v235
	v_pk_add_f32 v[242:243], v[242:243], v[234:235]
	v_add_f32_e32 v128, v128, v242
	v_add_f32_e32 v128, v128, v243
	v_mfma_f32_16x16x32_bf16 v[68:71], v[160:163], v[176:179], v[68:71]
	v_mfma_f32_16x16x32_bf16 v[76:79], v[164:167], v[176:179], v[76:79]
	v_mfma_f32_16x16x32_bf16 v[80:83], v[168:171], v[176:179], v[80:83]
	v_mfma_f32_16x16x32_bf16 v[92:95], v[172:175], v[176:179], v[92:95]
	s_addk_i32 s1, 0x4000
	s_add_u32 s7, s7, 64
	s_addc_u32 s8, s8, 0
	s_add_i32 s6, s6, 1
	s_waitcnt vmcnt(4)
	s_barrier
	s_add_i32 s48, s0, 0xffffff80
	s_add_i32 s49, s0, 0x8f
	s_add_i32 s50, s45, 0xffffffbf
	s_mov_b32 s51, 0
	s_mov_b32 s52, 0x10000
	v_mov_b32_e32 v132, v211
	s_branch .LBB0_355

; #define LAS __attribute__((address_space(3)))
; __device__ __forceinline__ bf16x8 pack8(const f32x4& a, const f32x4& b) { u32x4 w; w.x = pkbf(a[0], a[1]); w.y = pkbf(a[2], a[3]); w.z = pkbf(b[0], b[1]); w.w = pkbf(b[2], b[3]); return __builtin_bit_cast(bf16x8, w); }
;     const int l15 = lane & 15, g = lane >> 4, q4 = l15 >> 2;
;     const LAS unsigned char* kb0 = Kt + l15 * 128;
;     const int kx0 = ((g) ^ (l15 & 7)) << 4, kx1 = ((4 + g) ^ (l15 & 7)) << 4;
;     const LAS unsigned char* vrow = Vt + (4 * g + q4) * 128 + (lane & 3) * 8;
;     const int swz = (2 * (g & 1) + (q4 >> 1)) & 3;
;     const f32x4 cinit = (f32x4){negb, negb, negb, negb};
; #pragma unroll
;     for (int gh = 0; gh < 4 / GPB; ++gh) {
;         f32x4 S[GPB][4];
; #pragma unroll
;         for (int kb = 0; kb < 4; ++kb) {
;             const bf16x8 kf0 = *(const LAS bf16x8*)(kb0 + (16 * kb) * 128 + kx0), kf1 = *(const LAS bf16x8*)(kb0 + (16 * kb) * 128 + kx1);
; #pragma unroll
;             for (int gi = 0; gi < GPB; ++gi) { S[gi][kb] = __builtin_amdgcn_mfma_f32_16x16x32_bf16(kf0, qf[GPB * gh + gi][0], cinit, 0, 0, 0);
;                 S[gi][kb] = __builtin_amdgcn_mfma_f32_16x16x32_bf16(kf1, qf[GPB * gh + gi][1], S[gi][kb], 0, 0, 0); } }
;         bf16x8 pf[GPB][2];
; #pragma unroll
;         for (int gi = 0; gi < GPB; ++gi) {
;             if (MASK) {
; #pragma unroll
;                 for (int kb = 0; kb < 4; ++kb)
; #pragma unroll
;                     for (int i = 0; i < 4; ++i) { const int rel = rel0 + 16 * kb + 4 * g + i; S[gi][kb][i] = ((unsigned)(rel + 128) > 256u) ? NEGBIG : S[gi][kb][i]; }
;             }
;             ls[GPB * gh + gi] += exp_step<4>(S[gi]);
;             pf[gi][0] = pack8(S[gi][0], S[gi][1]); pf[gi][1] = pack8(S[gi][2], S[gi][3]);
; __device__ __forceinline__ void swa_phase(LAS unsigned char* lds, const bf16_t* Q, const bf16_t* K, const bf16_t* V, bf16_t* Ob, const float* sink, float negb) {
;     ...
;         for (int t = 4; t < NT; ++t) {
;             dma_tile<1>(lds + ((t + 3) & 3) * SW_BUF, K, V, SW_ROW0(t + 3), 256, dl, w);
;             const LAS unsigned char* buf = lds + (t & 3) * SW_BUF;
;             const int start = 128 * tb - 128 + 64 * (i_lo + t - 4);
;             if (start + 63 >= tq - 128 && start <= tq + 15 + 128)
;                 full_tile<1, 2, 2>(O, ls, qf, negb, buf, buf + 8192, lane, start - (tq + l15));
.LBB0_355:
	s_add_i32 s1, s52, 0xc000
	s_and_b32 s1, s1, 0xc000
	s_add_i32 s9, s47, s45
	s_add_i32 s8, s1, 0
	s_add_i32 s1, s9, 64
	s_add_i32 s0, s51, 7
	s_ashr_i32 s6, s1, 31
	s_add_u32 s7, s1, s43
	s_addc_u32 s1, s6, 0
	s_cmp_lt_u32 s0, s46
	s_cselect_b32 s1, s1, 0
	s_cselect_b32 s0, s7, s82
	s_lshl_b64 s[0:1], s[0:1], 9
	s_add_u32 s6, s67, s0
	s_addc_u32 s7, s4, s1
	s_add_u32 s0, s5, s0
	s_addc_u32 s1, s58, s1
	s_add_i32 s8, s38, s8
	s_mov_b32 s11, m0
	s_mov_b32 m0, s8
	s_nop 0
	global_load_lds_dwordx4 v212, s[6:7]
	s_mov_b32 m0, s11
	s_add_i32 s10, s8, 0x2000
	s_mov_b32 s6, m0
	s_mov_b32 m0, s10
	s_nop 0
	global_load_lds_dwordx4 v213, s[0:1]
	s_mov_b32 m0, s6
	s_addk_i32 s9, 0xff80
	s_add_i32 s0, s47, s50
	s_cmp_lt_i32 s0, s48
	s_cselect_b64 s[0:1], -1, 0
	s_cmp_gt_i32 s9, s49
	s_cselect_b64 s[6:7], -1, 0
	s_or_b64 s[0:1], s[0:1], s[6:7]
	s_and_b64 vcc, exec, s[0:1]
	s_cbranch_vccnz .LBB0_354
	s_and_b32 s34, s52, 0xc000
	v_add_u32_e32 v145, s47, v132
	s_movk_i32 s20, 0x100
	v_readfirstlane_b32 s30, v145
	s_nop 0
	s_sub_i32 s30, s30, 15
	s_cmp_le_u32 s30, 0xb2
	s_cbranch_scc1 .Lswa_loc_nomask
	v_add_u32_e32 v100, s34, v191
	v_add3_u32 v135, s34, v203, v198
	v_add_u32_e32 v102, v100, v193
	v_add_u32_e32 v100, v100, v192
	ds_read_b128 v[160:163], v100
	ds_read_b128 v[164:167], v102
	ds_read_b128 v[168:171], v100 offset:2048
	ds_read_b128 v[172:175], v102 offset:2048
	ds_read_b128 v[104:107], v100 offset:4096
	ds_read_b128 v[108:111], v102 offset:4096
	ds_read_b128 v[112:115], v100 offset:6144
	ds_read_b128 v[116:119], v102 offset:6144
	v_add_u32_e32 v103, v135, v199
	v_add_u32_e32 v133, v135, v200
	v_add_u32_e32 v134, v135, v201
	v_add_u32_e32 v135, v135, v202
	v_add_u32_e32 v244, 0, v145
	v_add_u32_e32 v245, 1, v145
	v_add_u32_e32 v246, 2, v145
	v_add_u32_e32 v247, 3, v145
	v_add_u32_e32 v248, 16, v145
	v_add_u32_e32 v249, 17, v145
	v_add_u32_e32 v250, 18, v145
	v_add_u32_e32 v251, 19, v145
	v_cmp_gt_u32_e64 s[0:1], v244, s20
	v_cmp_gt_u32_e64 s[6:7], v245, s20
	v_cmp_gt_u32_e64 s[8:9], v246, s20
	v_cmp_gt_u32_e64 s[10:11], v247, s20
	v_cmp_gt_u32_e64 s[12:13], v248, s20
	v_cmp_gt_u32_e64 s[24:25], v249, s20
	v_cmp_gt_u32_e64 s[26:27], v250, s20
	v_cmp_gt_u32_e64 s[28:29], v251, s20
	v_cndmask_b32_e64 v180, v0, v197, s[0:1]
	v_cndmask_b32_e64 v181, v0, v197, s[6:7]
	v_cndmask_b32_e64 v182, v0, v197, s[8:9]
	v_cndmask_b32_e64 v183, v0, v197, s[10:11]
	v_cndmask_b32_e64 v236, v0, v197, s[12:13]
	v_cndmask_b32_e64 v237, v0, v197, s[24:25]
	v_cndmask_b32_e64 v238, v0, v197, s[26:27]
	v_cndmask_b32_e64 v239, v0, v197, s[28:29]
	v_add_u32_e32 v244, 32, v145
	v_add_u32_e32 v245, 33, v145
	v_add_u32_e32 v246, 34, v145
	v_add_u32_e32 v247, 35, v145
	v_add_u32_e32 v248, 48, v145
	v_add_u32_e32 v249, 49, v145
	v_add_u32_e32 v250, 50, v145
	v_add_u32_e32 v251, 51, v145
	v_cmp_gt_u32_e64 s[0:1], v244, s20
	v_cmp_gt_u32_e64 s[6:7], v245, s20
	v_cmp_gt_u32_e64 s[8:9], v246, s20
	v_cmp_gt_u32_e64 s[10:11], v247, s20
	v_cmp_gt_u32_e64 s[12:13], v248, s20
	v_cmp_gt_u32_e64 s[24:25], v249, s20
	v_cmp_gt_u32_e64 s[26:27], v250, s20
	v_cmp_gt_u32_e64 s[28:29], v251, s20
	v_cndmask_b32_e64 v252, v0, v197, s[0:1]
	v_cndmask_b32_e64 v253, v0, v197, s[6:7]
	v_cndmask_b32_e64 v254, v0, v197, s[8:9]
	v_cndmask_b32_e64 v255, v0, v197, s[10:11]
	v_cndmask_b32_e64 v204, v0, v197, s[12:13]
	v_cndmask_b32_e64 v205, v0, v197, s[24:25]
	v_cndmask_b32_e64 v206, v0, v197, s[26:27]
	v_cndmask_b32_e64 v207, v0, v197, s[28:29]
	s_waitcnt lgkmcnt(4)
	v_mfma_f32_16x16x32_bf16 v[136:139], v[160:163], v[4:7], v[180:183]
	v_mfma_f32_16x16x32_bf16 v[140:143], v[168:171], v[4:7], v[236:239]
	v_mfma_f32_16x16x32_bf16 v[136:139], v[164:167], v[12:15], v[136:139]
	v_mfma_f32_16x16x32_bf16 v[140:143], v[172:175], v[12:15], v[140:143]
	ds_read_b64_tr_b16 v[216:217], v103 offset:8192
	ds_read_b64_tr_b16 v[218:219], v103 offset:10240
	ds_read_b64_tr_b16 v[220:221], v133 offset:8192
	ds_read_b64_tr_b16 v[222:223], v133 offset:10240
	ds_read_b64_tr_b16 v[224:225], v134 offset:8192
	ds_read_b64_tr_b16 v[226:227], v134 offset:10240
	ds_read_b64_tr_b16 v[228:229], v135 offset:8192
	ds_read_b64_tr_b16 v[230:231], v135 offset:10240
	v_mfma_f32_16x16x32_bf16 v[176:179], v[160:163], v[8:11], v[180:183]
	v_exp_f32_e32 v136, v136
	v_exp_f32_e32 v137, v137
	v_exp_f32_e32 v138, v138
	v_mfma_f32_16x16x32_bf16 v[232:235], v[168:171], v[8:11], v[236:239]
	v_exp_f32_e32 v139, v139
	v_exp_f32_e32 v140, v140
	v_pk_add_f32 v[242:243], v[136:137], v[138:139]
	v_mfma_f32_16x16x32_bf16 v[176:179], v[164:167], v[16:19], v[176:179]
	v_exp_f32_e32 v141, v141
	v_exp_f32_e32 v142, v142
	v_pk_add_f32 v[242:243], v[242:243], v[140:141]
	v_cvt_pk_bf16_f32 v136, v136, v137
	v_mfma_f32_16x16x32_bf16 v[232:235], v[172:175], v[16:19], v[232:235]
	v_exp_f32_e32 v143, v143
	v_cvt_pk_bf16_f32 v137, v138, v139
	v_cvt_pk_bf16_f32 v138, v140, v141
	v_cvt_pk_bf16_f32 v139, v142, v143
	v_pk_add_f32 v[242:243], v[242:243], v[142:143]
	v_add_f32_e32 v131, v131, v242
	v_add_f32_e32 v131, v131, v243
	s_waitcnt lgkmcnt(0)
; #define LAS __attribute__((address_space(3)))
; template <int NB16> __device__ __forceinline__ float exp_step(f32x4 (&S)[NB16]) {
;     float sum = 0.f;
; #pragma unroll
;     for (int k = 0; k < NB16; ++k)
; #pragma unroll
;         for (int i = 0; i < 4; ++i) { S[k][i] = __builtin_amdgcn_exp2f(S[k][i]); sum += S[k][i]; }
;     return sum;
; }
;     const int l15 = lane & 15, g = lane >> 4, q4 = l15 >> 2;
;     const LAS unsigned char* kb0 = Kt + l15 * 128;
;     const int kx0 = ((g) ^ (l15 & 7)) << 4, kx1 = ((4 + g) ^ (l15 & 7)) << 4;
;     const LAS unsigned char* vrow = Vt + (4 * g + q4) * 128 + (lane & 3) * 8;
;     const int swz = (2 * (g & 1) + (q4 >> 1)) & 3;
;     const f32x4 cinit = (f32x4){negb, negb, negb, negb};
; #pragma unroll
;     for (int gh = 0; gh < 4 / GPB; ++gh) {
;         f32x4 S[GPB][4];
; #pragma unroll
;         for (int kb = 0; kb < 4; ++kb) {
;             const bf16x8 kf0 = *(const LAS bf16x8*)(kb0 + (16 * kb) * 128 + kx0), kf1 = *(const LAS bf16x8*)(kb0 + (16 * kb) * 128 + kx1);
; #pragma unroll
;             for (int gi = 0; gi < GPB; ++gi) { S[gi][kb] = __builtin_amdgcn_mfma_f32_16x16x32_bf16(kf0, qf[GPB * gh + gi][0], cinit, 0, 0, 0);
;                 S[gi][kb] = __builtin_amdgcn_mfma_f32_16x16x32_bf16(kf1, qf[GPB * gh + gi][1], S[gi][kb], 0, 0, 0); } }
;         bf16x8 pf[GPB][2];
; #pragma unroll
;         for (int gi = 0; gi < GPB; ++gi) {
;             if (MASK) {
; #pragma unroll
;                 for (int kb = 0; kb < 4; ++kb)
; #pragma unroll
;                     for (int i = 0; i < 4; ++i) { const int rel = rel0 + 16 * kb + 4 * g + i; S[gi][kb][i] = ((unsigned)(rel + 128) > 256u) ? NEGBIG : S[gi][kb][i]; }
;             }
;             ls[GPB * gh + gi] += exp_step<4>(S[gi]);
;             pf[gi][0] = pack8(S[gi][0], S[gi][1]); pf[gi][1] = pack8(S[gi][2], S[gi][3]);
;         }
; #pragma unroll
;         for (int kc = 0; kc < 2; ++kc)
; #pragma unroll
;             for (int db = 0; db < 4; ++db) {
;                 const LAS unsigned char* va = vrow + ((db ^ swz) << 5) + (32 * kc) * 128;
;                 const bf16x8 vf = cat8(vtr(va), vtr(va + 16 * 128));
; #pragma unroll
;                 for (int gi = 0; gi < GPB; ++gi) O[GPB * gh + gi][db] = __builtin_amdgcn_mfma_f32_16x16x32_bf16(vf, pf[gi][kc], O[GPB * gh + gi][db], 0, 0, 0);
;             }
	v_mfma_f32_16x16x32_bf16 v[244:247], v[160:163], v[20:23], v[180:183]
	v_exp_f32_e32 v176, v176
	v_exp_f32_e32 v177, v177
	v_mfma_f32_16x16x32_bf16 v[248:251], v[168:171], v[20:23], v[236:239]
	v_exp_f32_e32 v178, v178
	v_mfma_f32_16x16x32_bf16 v[244:247], v[164:167], v[24:27], v[244:247]
	v_exp_f32_e32 v179, v179
	v_mfma_f32_16x16x32_bf16 v[248:251], v[172:175], v[24:27], v[248:251]
	v_exp_f32_e32 v232, v232
	v_pk_add_f32 v[242:243], v[176:177], v[178:179]
	v_mfma_f32_16x16x32_bf16 v[64:67], v[216:219], v[136:139], v[64:67]
	v_exp_f32_e32 v233, v233
	v_mfma_f32_16x16x32_bf16 v[60:63], v[220:223], v[136:139], v[60:63]
	v_exp_f32_e32 v234, v234
	v_pk_add_f32 v[242:243], v[242:243], v[232:233]
	v_cvt_pk_bf16_f32 v176, v176, v177
	v_mfma_f32_16x16x32_bf16 v[56:59], v[224:227], v[136:139], v[56:59]
	v_exp_f32_e32 v235, v235
	v_cvt_pk_bf16_f32 v177, v178, v179
	v_mfma_f32_16x16x32_bf16 v[52:55], v[228:231], v[136:139], v[52:55]
	v_cvt_pk_bf16_f32 v178, v232, v233
	v_cvt_pk_bf16_f32 v179, v234, v235
	v_pk_add_f32 v[242:243], v[242:243], v[234:235]
	v_add_f32_e32 v130, v130, v242
	v_add_f32_e32 v130, v130, v243
	v_mfma_f32_16x16x32_bf16 v[136:139], v[160:163], v[28:31], v[180:183]
	v_exp_f32_e32 v244, v244
	v_exp_f32_e32 v245, v245
	v_mfma_f32_16x16x32_bf16 v[140:143], v[168:171], v[28:31], v[236:239]
	v_exp_f32_e32 v246, v246
	v_mfma_f32_16x16x32_bf16 v[136:139], v[164:167], v[32:35], v[136:139]
	v_exp_f32_e32 v247, v247
	v_mfma_f32_16x16x32_bf16 v[140:143], v[172:175], v[32:35], v[140:143]
	v_exp_f32_e32 v248, v248
	v_pk_add_f32 v[242:243], v[244:245], v[246:247]
	v_mfma_f32_16x16x32_bf16 v[48:51], v[216:219], v[176:179], v[48:51]
	v_exp_f32_e32 v249, v249
	v_mfma_f32_16x16x32_bf16 v[44:47], v[220:223], v[176:179], v[44:47]
	v_exp_f32_e32 v250, v250
	v_pk_add_f32 v[242:243], v[242:243], v[248:249]
	v_cvt_pk_bf16_f32 v244, v244, v245
	v_mfma_f32_16x16x32_bf16 v[40:43], v[224:227], v[176:179], v[40:43]
	v_exp_f32_e32 v251, v251
	v_cvt_pk_bf16_f32 v245, v246, v247
	v_mfma_f32_16x16x32_bf16 v[36:39], v[228:231], v[176:179], v[36:39]
	v_cvt_pk_bf16_f32 v246, v248, v249
	v_cvt_pk_bf16_f32 v247, v250, v251
	v_pk_add_f32 v[242:243], v[242:243], v[250:251]
	v_add_f32_e32 v129, v129, v242
	v_add_f32_e32 v129, v129, v243
	ds_read_b64_tr_b16 v[160:161], v103 offset:12288
	ds_read_b64_tr_b16 v[162:163], v103 offset:14336
	ds_read_b64_tr_b16 v[164:165], v133 offset:12288
	ds_read_b64_tr_b16 v[166:167], v133 offset:14336
	ds_read_b64_tr_b16 v[168:169], v134 offset:12288
	ds_read_b64_tr_b16 v[170:171], v134 offset:14336
	ds_read_b64_tr_b16 v[172:173], v135 offset:12288
	ds_read_b64_tr_b16 v[174:175], v135 offset:14336
	v_mfma_f32_16x16x32_bf16 v[176:179], v[104:107], v[4:7], v[252:255]
	v_exp_f32_e32 v136, v136
	v_exp_f32_e32 v137, v137
	v_mfma_f32_16x16x32_bf16 v[232:235], v[112:115], v[4:7], v[204:207]
	v_exp_f32_e32 v138, v138
	v_mfma_f32_16x16x32_bf16 v[176:179], v[108:111], v[12:15], v[176:179]
	v_exp_f32_e32 v139, v139
	v_mfma_f32_16x16x32_bf16 v[232:235], v[116:119], v[12:15], v[232:235]
	v_exp_f32_e32 v140, v140
	v_pk_add_f32 v[242:243], v[136:137], v[138:139]
	v_mfma_f32_16x16x32_bf16 v[72:75], v[216:219], v[244:247], v[72:75]
	v_exp_f32_e32 v141, v141
	v_mfma_f32_16x16x32_bf16 v[84:87], v[220:223], v[244:247], v[84:87]
	v_exp_f32_e32 v142, v142
	v_pk_add_f32 v[242:243], v[242:243], v[140:141]
	v_cvt_pk_bf16_f32 v136, v136, v137
	v_mfma_f32_16x16x32_bf16 v[88:91], v[224:227], v[244:247], v[88:91]
	v_exp_f32_e32 v143, v143
	v_cvt_pk_bf16_f32 v137, v138, v139
	v_mfma_f32_16x16x32_bf16 v[96:99], v[228:231], v[244:247], v[96:99]
	v_cvt_pk_bf16_f32 v138, v140, v141
	v_cvt_pk_bf16_f32 v139, v142, v143
	v_pk_add_f32 v[242:243], v[242:243], v[142:143]
	v_add_f32_e32 v128, v128, v242
	v_add_f32_e32 v128, v128, v243
	v_mfma_f32_16x16x32_bf16 v[244:247], v[104:107], v[8:11], v[252:255]
	v_exp_f32_e32 v176, v176
	v_exp_f32_e32 v177, v177
	v_mfma_f32_16x16x32_bf16 v[248:251], v[112:115], v[8:11], v[204:207]
	v_exp_f32_e32 v178, v178
	v_mfma_f32_16x16x32_bf16 v[244:247], v[108:111], v[16:19], v[244:247]
	v_exp_f32_e32 v179, v179
	v_mfma_f32_16x16x32_bf16 v[248:251], v[116:119], v[16:19], v[248:251]
	v_exp_f32_e32 v232, v232
	v_pk_add_f32 v[242:243], v[176:177], v[178:179]
	v_mfma_f32_16x16x32_bf16 v[68:71], v[216:219], v[136:139], v[68:71]
	v_exp_f32_e32 v233, v233
	v_mfma_f32_16x16x32_bf16 v[76:79], v[220:223], v[136:139], v[76:79]
	v_exp_f32_e32 v234, v234
	v_pk_add_f32 v[242:243], v[242:243], v[232:233]
	v_cvt_pk_bf16_f32 v176, v176, v177
	v_mfma_f32_16x16x32_bf16 v[80:83], v[224:227], v[136:139], v[80:83]
	v_exp_f32_e32 v235, v235
	v_cvt_pk_bf16_f32 v177, v178, v179
	v_mfma_f32_16x16x32_bf16 v[92:95], v[228:231], v[136:139], v[92:95]
	v_cvt_pk_bf16_f32 v178, v232, v233
	v_cvt_pk_bf16_f32 v179, v234, v235
	v_pk_add_f32 v[242:243], v[242:243], v[234:235]
	v_add_f32_e32 v131, v131, v242
	v_add_f32_e32 v131, v131, v243
	s_waitcnt lgkmcnt(0)
; #define LAS __attribute__((address_space(3)))
; __device__ __forceinline__ s16x4 vtr(const LAS unsigned char* p) { return __builtin_bit_cast(s16x4, __builtin_amdgcn_ds_read_tr16_b64_v4i16((LAS v4i16_t*)p)); }
; __device__ __forceinline__ bf16x8 cat8(s16x4 a, s16x4 b) { return (bf16x8){a[0], a[1], a[2], a[3], b[0], b[1], b[2], b[3]}; }
; __device__ __forceinline__ bf16x8 pack8(const f32x4& a, const f32x4& b) { u32x4 w; w.x = pkbf(a[0], a[1]); w.y = pkbf(a[2], a[3]); w.z = pkbf(b[0], b[1]); w.w = pkbf(b[2], b[3]); return __builtin_bit_cast(bf16x8, w); }
;     ...
;     for (int gh = 0; gh < 4 / GPB; ++gh) {
;         f32x4 S[GPB][4];
; #pragma unroll
;         for (int kb = 0; kb < 4; ++kb) {
;             const bf16x8 kf0 = *(const LAS bf16x8*)(kb0 + (16 * kb) * 128 + kx0), kf1 = *(const LAS bf16x8*)(kb0 + (16 * kb) * 128 + kx1);
; #pragma unroll
;             for (int gi = 0; gi < GPB; ++gi) { S[gi][kb] = __builtin_amdgcn_mfma_f32_16x16x32_bf16(kf0, qf[GPB * gh + gi][0], cinit, 0, 0, 0);
;                 S[gi][kb] = __builtin_amdgcn_mfma_f32_16x16x32_bf16(kf1, qf[GPB * gh + gi][1], S[gi][kb], 0, 0, 0); } }
;         bf16x8 pf[GPB][2];
; #pragma unroll
;         for (int gi = 0; gi < GPB; ++gi) {
;             if (MASK) {
; #pragma unroll
;                 for (int kb = 0; kb < 4; ++kb)
; #pragma unroll
;                     for (int i = 0; i < 4; ++i) { const int rel = rel0 + 16 * kb + 4 * g + i; S[gi][kb][i] = ((unsigned)(rel + 128) > 256u) ? NEGBIG : S[gi][kb][i]; }
;             }
;             ls[GPB * gh + gi] += exp_step<4>(S[gi]);
;             pf[gi][0] = pack8(S[gi][0], S[gi][1]); pf[gi][1] = pack8(S[gi][2], S[gi][3]);
;         }
; #pragma unroll
;         for (int kc = 0; kc < 2; ++kc)
; #pragma unroll
;             for (int db = 0; db < 4; ++db) {
;                 const LAS unsigned char* va = vrow + ((db ^ swz) << 5) + (32 * kc) * 128;
;                 const bf16x8 vf = cat8(vtr(va), vtr(va + 16 * 128));
; #pragma unroll
;                 for (int gi = 0; gi < GPB; ++gi) O[GPB * gh + gi][db] = __builtin_amdgcn_mfma_f32_16x16x32_bf16(vf, pf[gi][kc], O[GPB * gh + gi][db], 0, 0, 0);
;             }
	v_mfma_f32_16x16x32_bf16 v[136:139], v[104:107], v[20:23], v[252:255]
	v_exp_f32_e32 v244, v244
	v_exp_f32_e32 v245, v245
	v_mfma_f32_16x16x32_bf16 v[140:143], v[112:115], v[20:23], v[204:207]
	v_exp_f32_e32 v246, v246
	v_mfma_f32_16x16x32_bf16 v[136:139], v[108:111], v[24:27], v[136:139]
	v_exp_f32_e32 v247, v247
	v_mfma_f32_16x16x32_bf16 v[140:143], v[116:119], v[24:27], v[140:143]
	v_exp_f32_e32 v248, v248
	v_pk_add_f32 v[242:243], v[244:245], v[246:247]
	v_mfma_f32_16x16x32_bf16 v[64:67], v[160:163], v[176:179], v[64:67]
	v_exp_f32_e32 v249, v249
	v_mfma_f32_16x16x32_bf16 v[60:63], v[164:167], v[176:179], v[60:63]
	v_exp_f32_e32 v250, v250
	v_pk_add_f32 v[242:243], v[242:243], v[248:249]
	v_cvt_pk_bf16_f32 v244, v244, v245
	v_mfma_f32_16x16x32_bf16 v[56:59], v[168:171], v[176:179], v[56:59]
	v_exp_f32_e32 v251, v251
	v_cvt_pk_bf16_f32 v245, v246, v247
	v_mfma_f32_16x16x32_bf16 v[52:55], v[172:175], v[176:179], v[52:55]
	v_cvt_pk_bf16_f32 v246, v248, v249
	v_cvt_pk_bf16_f32 v247, v250, v251
	v_pk_add_f32 v[242:243], v[242:243], v[250:251]
	v_add_f32_e32 v130, v130, v242
	v_add_f32_e32 v130, v130, v243
	v_mfma_f32_16x16x32_bf16 v[176:179], v[104:107], v[28:31], v[252:255]
	v_exp_f32_e32 v136, v136
	v_exp_f32_e32 v137, v137
	v_mfma_f32_16x16x32_bf16 v[232:235], v[112:115], v[28:31], v[204:207]
	v_exp_f32_e32 v138, v138
	v_mfma_f32_16x16x32_bf16 v[176:179], v[108:111], v[32:35], v[176:179]
	v_exp_f32_e32 v139, v139
	v_mfma_f32_16x16x32_bf16 v[232:235], v[116:119], v[32:35], v[232:235]
	v_exp_f32_e32 v140, v140
	v_pk_add_f32 v[242:243], v[136:137], v[138:139]
	v_mfma_f32_16x16x32_bf16 v[48:51], v[160:163], v[244:247], v[48:51]
	v_exp_f32_e32 v141, v141
	v_mfma_f32_16x16x32_bf16 v[44:47], v[164:167], v[244:247], v[44:47]
	v_exp_f32_e32 v142, v142
	v_pk_add_f32 v[242:243], v[242:243], v[140:141]
	v_cvt_pk_bf16_f32 v136, v136, v137
	v_mfma_f32_16x16x32_bf16 v[40:43], v[168:171], v[244:247], v[40:43]
	v_exp_f32_e32 v143, v143
	v_cvt_pk_bf16_f32 v137, v138, v139
	v_mfma_f32_16x16x32_bf16 v[36:39], v[172:175], v[244:247], v[36:39]
	v_cvt_pk_bf16_f32 v138, v140, v141
	v_cvt_pk_bf16_f32 v139, v142, v143
	v_pk_add_f32 v[242:243], v[242:243], v[142:143]
	v_add_f32_e32 v129, v129, v242
	v_add_f32_e32 v129, v129, v243
	v_mfma_f32_16x16x32_bf16 v[72:75], v[160:163], v[136:139], v[72:75]
	v_exp_f32_e32 v176, v176
	v_exp_f32_e32 v177, v177
	v_exp_f32_e32 v178, v178
	v_mfma_f32_16x16x32_bf16 v[84:87], v[164:167], v[136:139], v[84:87]
	v_exp_f32_e32 v179, v179
	v_exp_f32_e32 v232, v232
	v_pk_add_f32 v[242:243], v[176:177], v[178:179]
	v_mfma_f32_16x16x32_bf16 v[88:91], v[168:171], v[136:139], v[88:91]
	v_exp_f32_e32 v233, v233
	v_exp_f32_e32 v234, v234
	v_pk_add_f32 v[242:243], v[242:243], v[232:233]
	v_cvt_pk_bf16_f32 v176, v176, v177
	v_mfma_f32_16x16x32_bf16 v[96:99], v[172:175], v[136:139], v[96:99]
	v_exp_f32_e32 v235, v235
	v_cvt_pk_bf16_f32 v177, v178, v179
	v_cvt_pk_bf16_f32 v178, v232, v233
	v_cvt_pk_bf16_f32 v179, v234, v235
	v_pk_add_f32 v[242:243], v[242:243], v[234:235]
	v_add_f32_e32 v128, v128, v242
	v_add_f32_e32 v128, v128, v243
	v_mfma_f32_16x16x32_bf16 v[68:71], v[160:163], v[176:179], v[68:71]
	v_mfma_f32_16x16x32_bf16 v[76:79], v[164:167], v[176:179], v[76:79]
	v_mfma_f32_16x16x32_bf16 v[80:83], v[168:171], v[176:179], v[80:83]
	v_mfma_f32_16x16x32_bf16 v[92:95], v[172:175], v[176:179], v[92:95]
	s_branch .LBB0_354
.Lswa_loc_nomask:
	v_add_u32_e32 v100, s34, v191
	v_add3_u32 v135, s34, v203, v198
	v_add_u32_e32 v102, v100, v193
	v_add_u32_e32 v100, v100, v192
	ds_read_b128 v[160:163], v100
	ds_read_b128 v[164:167], v102
	ds_read_b128 v[168:171], v100 offset:2048
	ds_read_b128 v[172:175], v102 offset:2048
	ds_read_b128 v[104:107], v100 offset:4096
	ds_read_b128 v[108:111], v102 offset:4096
	ds_read_b128 v[112:115], v100 offset:6144
	ds_read_b128 v[116:119], v102 offset:6144
	v_add_u32_e32 v103, v135, v199
	v_add_u32_e32 v133, v135, v200
	v_add_u32_e32 v134, v135, v201
	v_add_u32_e32 v135, v135, v202
	s_waitcnt lgkmcnt(4)
	v_mfma_f32_16x16x32_bf16 v[136:139], v[160:163], v[4:7], v[0:3]
	v_mfma_f32_16x16x32_bf16 v[140:143], v[168:171], v[4:7], v[0:3]
	v_mfma_f32_16x16x32_bf16 v[136:139], v[164:167], v[12:15], v[136:139]
	v_mfma_f32_16x16x32_bf16 v[140:143], v[172:175], v[12:15], v[140:143]
	ds_read_b64_tr_b16 v[216:217], v103 offset:8192
	ds_read_b64_tr_b16 v[218:219], v103 offset:10240
	ds_read_b64_tr_b16 v[220:221], v133 offset:8192
	ds_read_b64_tr_b16 v[222:223], v133 offset:10240
	ds_read_b64_tr_b16 v[224:225], v134 offset:8192
	ds_read_b64_tr_b16 v[226:227], v134 offset:10240
	ds_read_b64_tr_b16 v[228:229], v135 offset:8192
	ds_read_b64_tr_b16 v[230:231], v135 offset:10240
	v_mfma_f32_16x16x32_bf16 v[176:179], v[160:163], v[8:11], v[0:3]
	v_exp_f32_e32 v136, v136
	v_exp_f32_e32 v137, v137
	v_exp_f32_e32 v138, v138
	v_mfma_f32_16x16x32_bf16 v[232:235], v[168:171], v[8:11], v[0:3]
	v_exp_f32_e32 v139, v139
	v_exp_f32_e32 v140, v140
	v_pk_add_f32 v[242:243], v[136:137], v[138:139]
	v_mfma_f32_16x16x32_bf16 v[176:179], v[164:167], v[16:19], v[176:179]
	v_exp_f32_e32 v141, v141
	v_exp_f32_e32 v142, v142
	v_pk_add_f32 v[242:243], v[242:243], v[140:141]
	v_cvt_pk_bf16_f32 v136, v136, v137
	v_mfma_f32_16x16x32_bf16 v[232:235], v[172:175], v[16:19], v[232:235]
	v_exp_f32_e32 v143, v143
	v_cvt_pk_bf16_f32 v137, v138, v139
	v_cvt_pk_bf16_f32 v138, v140, v141
	v_cvt_pk_bf16_f32 v139, v142, v143
	v_pk_add_f32 v[242:243], v[242:243], v[142:143]
	v_add_f32_e32 v131, v131, v242
	v_add_f32_e32 v131, v131, v243
	s_waitcnt lgkmcnt(0)
; #define LAS __attribute__((address_space(3)))
; __device__ __forceinline__ s16x4 vtr(const LAS unsigned char* p) { return __builtin_bit_cast(s16x4, __builtin_amdgcn_ds_read_tr16_b64_v4i16((LAS v4i16_t*)p)); }
; __device__ __forceinline__ bf16x8 cat8(s16x4 a, s16x4 b) { return (bf16x8){a[0], a[1], a[2], a[3], b[0], b[1], b[2], b[3]}; }
; __device__ __forceinline__ bf16x8 pack8(const f32x4& a, const f32x4& b) { u32x4 w; w.x = pkbf(a[0], a[1]); w.y = pkbf(a[2], a[3]); w.z = pkbf(b[0], b[1]); w.w = pkbf(b[2], b[3]); return __builtin_bit_cast(bf16x8, w); }
;     ...
;     for (int gh = 0; gh < 4 / GPB; ++gh) {
;         f32x4 S[GPB][4];
; #pragma unroll
;         for (int kb = 0; kb < 4; ++kb) {
;             const bf16x8 kf0 = *(const LAS bf16x8*)(kb0 + (16 * kb) * 128 + kx0), kf1 = *(const LAS bf16x8*)(kb0 + (16 * kb) * 128 + kx1);
; #pragma unroll
;             for (int gi = 0; gi < GPB; ++gi) { S[gi][kb] = __builtin_amdgcn_mfma_f32_16x16x32_bf16(kf0, qf[GPB * gh + gi][0], cinit, 0, 0, 0);
;                 S[gi][kb] = __builtin_amdgcn_mfma_f32_16x16x32_bf16(kf1, qf[GPB * gh + gi][1], S[gi][kb], 0, 0, 0); } }
;         bf16x8 pf[GPB][2];
; #pragma unroll
;         for (int gi = 0; gi < GPB; ++gi) {
;             if (MASK) {
; #pragma unroll
;                 for (int kb = 0; kb < 4; ++kb)
; #pragma unroll
;                     for (int i = 0; i < 4; ++i) { const int rel = rel0 + 16 * kb + 4 * g + i; S[gi][kb][i] = ((unsigned)(rel + 128) > 256u) ? NEGBIG : S[gi][kb][i]; }
;             }
;             ls[GPB * gh + gi] += exp_step<4>(S[gi]);
;             pf[gi][0] = pack8(S[gi][0], S[gi][1]); pf[gi][1] = pack8(S[gi][2], S[gi][3]);
;         }
; #pragma unroll
;         for (int kc = 0; kc < 2; ++kc)
; #pragma unroll
;             for (int db = 0; db < 4; ++db) {
;                 const LAS unsigned char* va = vrow + ((db ^ swz) << 5) + (32 * kc) * 128;
;                 const bf16x8 vf = cat8(vtr(va), vtr(va + 16 * 128));
; #pragma unroll
;                 for (int gi = 0; gi < GPB; ++gi) O[GPB * gh + gi][db] = __builtin_amdgcn_mfma_f32_16x16x32_bf16(vf, pf[gi][kc], O[GPB * gh + gi][db], 0, 0, 0);
;             }
	v_mfma_f32_16x16x32_bf16 v[244:247], v[160:163], v[20:23], v[0:3]
	v_exp_f32_e32 v176, v176
	v_exp_f32_e32 v177, v177
	v_mfma_f32_16x16x32_bf16 v[248:251], v[168:171], v[20:23], v[0:3]
	v_exp_f32_e32 v178, v178
	v_mfma_f32_16x16x32_bf16 v[244:247], v[164:167], v[24:27], v[244:247]
	v_exp_f32_e32 v179, v179
	v_mfma_f32_16x16x32_bf16 v[248:251], v[172:175], v[24:27], v[248:251]
	v_exp_f32_e32 v232, v232
	v_pk_add_f32 v[242:243], v[176:177], v[178:179]
	v_mfma_f32_16x16x32_bf16 v[64:67], v[216:219], v[136:139], v[64:67]
	v_exp_f32_e32 v233, v233
	v_mfma_f32_16x16x32_bf16 v[60:63], v[220:223], v[136:139], v[60:63]
	v_exp_f32_e32 v234, v234
	v_pk_add_f32 v[242:243], v[242:243], v[232:233]
	v_cvt_pk_bf16_f32 v176, v176, v177
	v_mfma_f32_16x16x32_bf16 v[56:59], v[224:227], v[136:139], v[56:59]
	v_exp_f32_e32 v235, v235
	v_cvt_pk_bf16_f32 v177, v178, v179
	v_mfma_f32_16x16x32_bf16 v[52:55], v[228:231], v[136:139], v[52:55]
	v_cvt_pk_bf16_f32 v178, v232, v233
	v_cvt_pk_bf16_f32 v179, v234, v235
	v_pk_add_f32 v[242:243], v[242:243], v[234:235]
	v_add_f32_e32 v130, v130, v242
	v_add_f32_e32 v130, v130, v243
	v_mfma_f32_16x16x32_bf16 v[136:139], v[160:163], v[28:31], v[0:3]
	v_exp_f32_e32 v244, v244
	v_exp_f32_e32 v245, v245
	v_mfma_f32_16x16x32_bf16 v[140:143], v[168:171], v[28:31], v[0:3]
	v_exp_f32_e32 v246, v246
	v_mfma_f32_16x16x32_bf16 v[136:139], v[164:167], v[32:35], v[136:139]
	v_exp_f32_e32 v247, v247
	v_mfma_f32_16x16x32_bf16 v[140:143], v[172:175], v[32:35], v[140:143]
	v_exp_f32_e32 v248, v248
	v_pk_add_f32 v[242:243], v[244:245], v[246:247]
	v_mfma_f32_16x16x32_bf16 v[48:51], v[216:219], v[176:179], v[48:51]
	v_exp_f32_e32 v249, v249
	v_mfma_f32_16x16x32_bf16 v[44:47], v[220:223], v[176:179], v[44:47]
	v_exp_f32_e32 v250, v250
	v_pk_add_f32 v[242:243], v[242:243], v[248:249]
	v_cvt_pk_bf16_f32 v244, v244, v245
	v_mfma_f32_16x16x32_bf16 v[40:43], v[224:227], v[176:179], v[40:43]
	v_exp_f32_e32 v251, v251
	v_cvt_pk_bf16_f32 v245, v246, v247
	v_mfma_f32_16x16x32_bf16 v[36:39], v[228:231], v[176:179], v[36:39]
	v_cvt_pk_bf16_f32 v246, v248, v249
	v_cvt_pk_bf16_f32 v247, v250, v251
	v_pk_add_f32 v[242:243], v[242:243], v[250:251]
	v_add_f32_e32 v129, v129, v242
	v_add_f32_e32 v129, v129, v243
	ds_read_b64_tr_b16 v[160:161], v103 offset:12288
	ds_read_b64_tr_b16 v[162:163], v103 offset:14336
	ds_read_b64_tr_b16 v[164:165], v133 offset:12288
	ds_read_b64_tr_b16 v[166:167], v133 offset:14336
	ds_read_b64_tr_b16 v[168:169], v134 offset:12288
	ds_read_b64_tr_b16 v[170:171], v134 offset:14336
	ds_read_b64_tr_b16 v[172:173], v135 offset:12288
	ds_read_b64_tr_b16 v[174:175], v135 offset:14336
	v_mfma_f32_16x16x32_bf16 v[176:179], v[104:107], v[4:7], v[0:3]
	v_exp_f32_e32 v136, v136
	v_exp_f32_e32 v137, v137
	v_mfma_f32_16x16x32_bf16 v[232:235], v[112:115], v[4:7], v[0:3]
	v_exp_f32_e32 v138, v138
	v_mfma_f32_16x16x32_bf16 v[176:179], v[108:111], v[12:15], v[176:179]
	v_exp_f32_e32 v139, v139
	v_mfma_f32_16x16x32_bf16 v[232:235], v[116:119], v[12:15], v[232:235]
	v_exp_f32_e32 v140, v140
	v_pk_add_f32 v[242:243], v[136:137], v[138:139]
	v_mfma_f32_16x16x32_bf16 v[72:75], v[216:219], v[244:247], v[72:75]
	v_exp_f32_e32 v141, v141
	v_mfma_f32_16x16x32_bf16 v[84:87], v[220:223], v[244:247], v[84:87]
	v_exp_f32_e32 v142, v142
	v_pk_add_f32 v[242:243], v[242:243], v[140:141]
	v_cvt_pk_bf16_f32 v136, v136, v137
	v_mfma_f32_16x16x32_bf16 v[88:91], v[224:227], v[244:247], v[88:91]
	v_exp_f32_e32 v143, v143
	v_cvt_pk_bf16_f32 v137, v138, v139
	v_mfma_f32_16x16x32_bf16 v[96:99], v[228:231], v[244:247], v[96:99]
	v_cvt_pk_bf16_f32 v138, v140, v141
	v_cvt_pk_bf16_f32 v139, v142, v143
	v_pk_add_f32 v[242:243], v[242:243], v[142:143]
	v_add_f32_e32 v128, v128, v242
	v_add_f32_e32 v128, v128, v243
	v_mfma_f32_16x16x32_bf16 v[244:247], v[104:107], v[8:11], v[0:3]
	v_exp_f32_e32 v176, v176
	v_exp_f32_e32 v177, v177
	v_mfma_f32_16x16x32_bf16 v[248:251], v[112:115], v[8:11], v[0:3]
	v_exp_f32_e32 v178, v178
	v_mfma_f32_16x16x32_bf16 v[244:247], v[108:111], v[16:19], v[244:247]
	v_exp_f32_e32 v179, v179
	v_mfma_f32_16x16x32_bf16 v[248:251], v[116:119], v[16:19], v[248:251]
	v_exp_f32_e32 v232, v232
	v_pk_add_f32 v[242:243], v[176:177], v[178:179]
	v_mfma_f32_16x16x32_bf16 v[68:71], v[216:219], v[136:139], v[68:71]
	v_exp_f32_e32 v233, v233
	v_mfma_f32_16x16x32_bf16 v[76:79], v[220:223], v[136:139], v[76:79]
	v_exp_f32_e32 v234, v234
	v_pk_add_f32 v[242:243], v[242:243], v[232:233]
	v_cvt_pk_bf16_f32 v176, v176, v177
	v_mfma_f32_16x16x32_bf16 v[80:83], v[224:227], v[136:139], v[80:83]
	v_exp_f32_e32 v235, v235
	v_cvt_pk_bf16_f32 v177, v178, v179
	v_mfma_f32_16x16x32_bf16 v[92:95], v[228:231], v[136:139], v[92:95]
	v_cvt_pk_bf16_f32 v178, v232, v233
	v_cvt_pk_bf16_f32 v179, v234, v235
	v_pk_add_f32 v[242:243], v[242:243], v[234:235]
	v_add_f32_e32 v131, v131, v242
	v_add_f32_e32 v131, v131, v243
	s_waitcnt lgkmcnt(0)
; #define LAS __attribute__((address_space(3)))
; __device__ __forceinline__ s16x4 vtr(const LAS unsigned char* p) { return __builtin_bit_cast(s16x4, __builtin_amdgcn_ds_read_tr16_b64_v4i16((LAS v4i16_t*)p)); }
; __device__ __forceinline__ bf16x8 cat8(s16x4 a, s16x4 b) { return (bf16x8){a[0], a[1], a[2], a[3], b[0], b[1], b[2], b[3]}; }
; __device__ __forceinline__ bf16x8 pack8(const f32x4& a, const f32x4& b) { u32x4 w; w.x = pkbf(a[0], a[1]); w.y = pkbf(a[2], a[3]); w.z = pkbf(b[0], b[1]); w.w = pkbf(b[2], b[3]); return __builtin_bit_cast(bf16x8, w); }
;     ...
;     for (int gh = 0; gh < 4 / GPB; ++gh) {
;         f32x4 S[GPB][4];
; #pragma unroll
;         for (int kb = 0; kb < 4; ++kb) {
;             const bf16x8 kf0 = *(const LAS bf16x8*)(kb0 + (16 * kb) * 128 + kx0), kf1 = *(const LAS bf16x8*)(kb0 + (16 * kb) * 128 + kx1);
; #pragma unroll
;             for (int gi = 0; gi < GPB; ++gi) { S[gi][kb] = __builtin_amdgcn_mfma_f32_16x16x32_bf16(kf0, qf[GPB * gh + gi][0], cinit, 0, 0, 0);
;                 S[gi][kb] = __builtin_amdgcn_mfma_f32_16x16x32_bf16(kf1, qf[GPB * gh + gi][1], S[gi][kb], 0, 0, 0); } }
;         bf16x8 pf[GPB][2];
; #pragma unroll
;         for (int gi = 0; gi < GPB; ++gi) {
;             if (MASK) {
; #pragma unroll
;                 for (int kb = 0; kb < 4; ++kb)
; #pragma unroll
;                     for (int i = 0; i < 4; ++i) { const int rel = rel0 + 16 * kb + 4 * g + i; S[gi][kb][i] = ((unsigned)(rel + 128) > 256u) ? NEGBIG : S[gi][kb][i]; }
;             }
;             ls[GPB * gh + gi] += exp_step<4>(S[gi]);
;             pf[gi][0] = pack8(S[gi][0], S[gi][1]); pf[gi][1] = pack8(S[gi][2], S[gi][3]);
;         }
; #pragma unroll
;         for (int kc = 0; kc < 2; ++kc)
; #pragma unroll
;             for (int db = 0; db < 4; ++db) {
;                 const LAS unsigned char* va = vrow + ((db ^ swz) << 5) + (32 * kc) * 128;
;                 const bf16x8 vf = cat8(vtr(va), vtr(va + 16 * 128));
; #pragma unroll
;                 for (int gi = 0; gi < GPB; ++gi) O[GPB * gh + gi][db] = __builtin_amdgcn_mfma_f32_16x16x32_bf16(vf, pf[gi][kc], O[GPB * gh + gi][db], 0, 0, 0);
;             }
	v_mfma_f32_16x16x32_bf16 v[136:139], v[104:107], v[20:23], v[0:3]
	v_exp_f32_e32 v244, v244
	v_exp_f32_e32 v245, v245
	v_mfma_f32_16x16x32_bf16 v[140:143], v[112:115], v[20:23], v[0:3]
	v_exp_f32_e32 v246, v246
	v_mfma_f32_16x16x32_bf16 v[136:139], v[108:111], v[24:27], v[136:139]
	v_exp_f32_e32 v247, v247
	v_mfma_f32_16x16x32_bf16 v[140:143], v[116:119], v[24:27], v[140:143]
	v_exp_f32_e32 v248, v248
	v_pk_add_f32 v[242:243], v[244:245], v[246:247]
	v_mfma_f32_16x16x32_bf16 v[64:67], v[160:163], v[176:179], v[64:67]
	v_exp_f32_e32 v249, v249
	v_mfma_f32_16x16x32_bf16 v[60:63], v[164:167], v[176:179], v[60:63]
	v_exp_f32_e32 v250, v250
	v_pk_add_f32 v[242:243], v[242:243], v[248:249]
	v_cvt_pk_bf16_f32 v244, v244, v245
	v_mfma_f32_16x16x32_bf16 v[56:59], v[168:171], v[176:179], v[56:59]
	v_exp_f32_e32 v251, v251
	v_cvt_pk_bf16_f32 v245, v246, v247
	v_mfma_f32_16x16x32_bf16 v[52:55], v[172:175], v[176:179], v[52:55]
	v_cvt_pk_bf16_f32 v246, v248, v249
	v_cvt_pk_bf16_f32 v247, v250, v251
	v_pk_add_f32 v[242:243], v[242:243], v[250:251]
	v_add_f32_e32 v130, v130, v242
	v_add_f32_e32 v130, v130, v243
	v_mfma_f32_16x16x32_bf16 v[176:179], v[104:107], v[28:31], v[0:3]
	v_exp_f32_e32 v136, v136
	v_exp_f32_e32 v137, v137
	v_mfma_f32_16x16x32_bf16 v[232:235], v[112:115], v[28:31], v[0:3]
	v_exp_f32_e32 v138, v138
	v_mfma_f32_16x16x32_bf16 v[176:179], v[108:111], v[32:35], v[176:179]
	v_exp_f32_e32 v139, v139
	v_mfma_f32_16x16x32_bf16 v[232:235], v[116:119], v[32:35], v[232:235]
	v_exp_f32_e32 v140, v140
	v_pk_add_f32 v[242:243], v[136:137], v[138:139]
	v_mfma_f32_16x16x32_bf16 v[48:51], v[160:163], v[244:247], v[48:51]
	v_exp_f32_e32 v141, v141
	v_mfma_f32_16x16x32_bf16 v[44:47], v[164:167], v[244:247], v[44:47]
	v_exp_f32_e32 v142, v142
	v_pk_add_f32 v[242:243], v[242:243], v[140:141]
	v_cvt_pk_bf16_f32 v136, v136, v137
	v_mfma_f32_16x16x32_bf16 v[40:43], v[168:171], v[244:247], v[40:43]
	v_exp_f32_e32 v143, v143
	v_cvt_pk_bf16_f32 v137, v138, v139
	v_mfma_f32_16x16x32_bf16 v[36:39], v[172:175], v[244:247], v[36:39]
	v_cvt_pk_bf16_f32 v138, v140, v141
	v_cvt_pk_bf16_f32 v139, v142, v143
	v_pk_add_f32 v[242:243], v[242:243], v[142:143]
	v_add_f32_e32 v129, v129, v242
	v_add_f32_e32 v129, v129, v243
	v_mfma_f32_16x16x32_bf16 v[72:75], v[160:163], v[136:139], v[72:75]
	v_exp_f32_e32 v176, v176
	v_exp_f32_e32 v177, v177
	v_exp_f32_e32 v178, v178
	v_mfma_f32_16x16x32_bf16 v[84:87], v[164:167], v[136:139], v[84:87]
	v_exp_f32_e32 v179, v179
	v_exp_f32_e32 v232, v232
	v_pk_add_f32 v[242:243], v[176:177], v[178:179]
	v_mfma_f32_16x16x32_bf16 v[88:91], v[168:171], v[136:139], v[88:91]
	v_exp_f32_e32 v233, v233
	v_exp_f32_e32 v234, v234
	v_pk_add_f32 v[242:243], v[242:243], v[232:233]
	v_cvt_pk_bf16_f32 v176, v176, v177
	v_mfma_f32_16x16x32_bf16 v[96:99], v[172:175], v[136:139], v[96:99]
	v_exp_f32_e32 v235, v235
	v_cvt_pk_bf16_f32 v177, v178, v179
	v_cvt_pk_bf16_f32 v178, v232, v233
	v_cvt_pk_bf16_f32 v179, v234, v235
	v_pk_add_f32 v[242:243], v[242:243], v[234:235]
	v_add_f32_e32 v128, v128, v242
	v_add_f32_e32 v128, v128, v243
	v_mfma_f32_16x16x32_bf16 v[68:71], v[160:163], v[176:179], v[68:71]
	v_mfma_f32_16x16x32_bf16 v[76:79], v[164:167], v[176:179], v[76:79]
	v_mfma_f32_16x16x32_bf16 v[80:83], v[168:171], v[176:179], v[80:83]
	v_mfma_f32_16x16x32_bf16 v[92:95], v[172:175], v[176:179], v[92:95]
	s_branch .LBB0_354

;     ...
;     for (int gh = 0; gh < 4 / GPB; ++gh) {
;         f32x4 S[GPB][4];
; #pragma unroll
;         for (int kb = 0; kb < 4; ++kb) {
;             const bf16x8 kf0 = *(const LAS bf16x8*)(kb0 + (16 * kb) * 128 + kx0), kf1 = *(const LAS bf16x8*)(kb0 + (16 * kb) * 128 + kx1);
; #pragma unroll
;             for (int gi = 0; gi < GPB; ++gi) { S[gi][kb] = __builtin_amdgcn_mfma_f32_16x16x32_bf16(kf0, qf[GPB * gh + gi][0], cinit, 0, 0, 0);
;                 S[gi][kb] = __builtin_amdgcn_mfma_f32_16x16x32_bf16(kf1, qf[GPB * gh + gi][1], S[gi][kb], 0, 0, 0); } }
;         bf16x8 pf[GPB][2];
; #pragma unroll
;         for (int gi = 0; gi < GPB; ++gi) {
; __device__ __forceinline__ void na_phase(LAS unsigned char* lds, const bf16_t* Q, const bf16_t* K, const bf16_t* V, bf16_t* Ob, const float* rpb, float negb) {
;     ...
;         const int kr_lo = min(max(4 * rq - 4, 0), 120), kr_hi = min(max(4 * rq - 1, 0), 120) + 8;
;         const int NT = 4 + (isctx ? 0 : kr_hi - kr_lo);
;         const DmaLane dl = dma_lane(DM, hp * 128, w, lane);
;     ...
;         dma_tile<2>(lds, K, V, NA_ROW0(0), DM, dl, w);
;         dma_tile<2>(lds + NA_BUF, K, V, NA_ROW0(1), DM, dl, w);
;         dma_tile<2>(lds + 2 * NA_BUF, K, V, NA_ROW0(2), DM, dl, w);
;         for (int i = tid; i < 2 * 465; i += 512) { const int h2 = i / 465, e = i - h2 * 465; tab[h2 * 512 + e] = rpb[(2 * hp + h2) * 465 + e] * LOG2E; }
;         const int r = 4 * rq + (w & 3);
;         const size_t qrow0 = isctx ? (size_t)(MLAT + b * NCTX + (w & 3) * 64) : (size_t)(b * SEQ + r * 64);
;         bf16x8 qf[4][2];
; #pragma unroll
;         for (int grp = 0; grp < 4; ++grp)
; #pragma unroll
;             for (int ds = 0; ds < 2; ++ds) qf[grp][ds] = *(const bf16x8*)(Q + (qrow0 + 16 * grp + l15) * DM + head * 64 + 32 * ds + 8 * g);
;         f32x4 O[4][4]; float ls[4];
; #pragma unroll
;         for (int grp = 0; grp < 4; ++grp) { ls[grp] = 0.f;
; #pragma unroll
;             for (int db = 0; db < 4; ++db) O[grp][db] = (f32x4){0.f, 0.f, 0.f, 0.f}; }
;         const int r0w = min(max(r - 4, 0), 120);
;         drain_wait();
;         for (int t = 0; t < 4; ++t) {
;             dma_tile<2>(lds + ((t + 3) & 3) * NA_BUF, K, V, NA_ROW0(t + 3), DM, dl, w);
;             const LAS unsigned char* buf = lds + (t & 3) * NA_BUF;
;             full_tile<0, 1, 2>(O, ls, qf, negb, buf + hh * 8192, buf + 2 * 8192 + hh * 8192, lane, 0);
.LBB0_377:
	s_or_b64 exec, exec, s[96:97]
	v_sub_u32_e64 v4, s68, 1 clamp
	s_lshl_b32 s61, s6, 13
	v_readfirstlane_b32 s6, v4
	s_max_u32 s60, s68, 4
	s_min_u32 s6, s6, 0x78
	s_lshl_b32 s7, s7, 1
	v_readlane_b32 s59, v240, 49
	s_sub_i32 s6, s6, s60
	s_add_i32 s59, s7, s59
	s_add_i32 s66, s6, 16
	s_and_b64 s[6:7], exec, s[0:1]
	s_mov_b32 s33, s93
	s_cselect_b32 s93, 4, s66
	s_or_b32 s6, s68, s2
	v_readlane_b32 s7, v240, 48
	s_lshl_b32 s66, s6, 6
	s_or_b32 s7, s82, s7
	s_or_b32 s66, s61, s66
	s_and_b64 s[0:1], exec, s[0:1]
	s_cselect_b32 s0, s7, s66
	v_or_b32_e32 v154, s0, v199
	s_lshl_b32 s0, s59, 6
	s_ashr_i32 s1, s0, 31
	v_lshl_add_u64 v[28:29], s[0:1], 1, v[112:113]
	v_lshlrev_b64 v[122:123], 11, v[154:155]
	v_lshl_add_u64 v[8:9], v[28:29], 0, v[122:123]
	global_load_dwordx4 v[4:7], v[8:9], off
	s_nop 0
	global_load_dwordx4 v[8:11], v[8:9], off offset:64
	s_max_i32 s97, s6, 4
	s_or_b32 s59, s94, 0x60000
	v_or_b32_e32 v12, 16, v154
	v_mov_b32_e32 v13, v155
	v_or_b32_e32 v20, 32, v154
	v_mov_b32_e32 v21, v155
	v_or_b32_e32 v154, 48, v154
	s_add_u32 s6, s67, s59
	v_lshlrev_b64 v[120:121], 11, v[12:13]
	v_lshlrev_b64 v[118:119], 11, v[20:21]
	v_lshlrev_b64 v[116:117], 11, v[154:155]
	s_addc_u32 s7, s4, s95
	v_lshl_add_u64 v[16:17], v[28:29], 0, v[120:121]
	v_lshl_add_u64 v[24:25], v[28:29], 0, v[118:119]
	v_lshl_add_u64 v[32:33], v[28:29], 0, v[116:117]
	s_add_u32 s94, s5, s59
	global_load_dwordx4 v[12:15], v[16:17], off
	s_nop 0
	global_load_dwordx4 v[16:19], v[16:17], off offset:64
	s_nop 0
	global_load_dwordx4 v[20:23], v[24:25], off
	s_nop 0
	global_load_dwordx4 v[24:27], v[24:25], off offset:64
	s_nop 0
	global_load_dwordx4 v[28:31], v[32:33], off
	s_nop 0
	global_load_dwordx4 v[32:35], v[32:33], off offset:64
	s_waitcnt vmcnt(0)
	s_waitcnt lgkmcnt(0)
	s_barrier
	s_addc_u32 s95, s58, s95
	s_add_i32 s59, s69, 0x18000
	s_mov_b32 s76, m0
	s_mov_b32 m0, s59
	s_nop 0
	global_load_lds_dwordx4 v221, s[6:7]
	s_mov_b32 m0, s76
	s_add_i32 s66, s69, 0x1c000
	s_mov_b32 s59, m0
	s_mov_b32 m0, s66
	s_nop 0
	global_load_lds_dwordx4 v222, s[94:95]
	s_mov_b32 m0, s59
	s_add_i32 s59, s69, 0x1a000
	s_mov_b32 s66, m0
	s_mov_b32 m0, s59
	s_nop 0
	global_load_lds_dwordx4 v223, s[6:7]
	s_mov_b32 m0, s66
	s_add_i32 s6, s69, 0x1e000
	s_mov_b32 s7, m0
	s_mov_b32 m0, s6
	s_nop 0
	global_load_lds_dwordx4 v224, s[94:95]
	s_mov_b32 m0, s7
	v_mov_b32_e32 v48, 0
	v_mov_b32_e32 v49, 0
	v_mov_b32_e32 v50, 0
	v_mov_b32_e32 v51, 0
	v_mov_b32_e32 v44, 0
	v_mov_b32_e32 v45, 0
	v_mov_b32_e32 v46, 0
	v_mov_b32_e32 v47, 0
	v_mov_b32_e32 v40, 0
	v_mov_b32_e32 v41, 0
	v_mov_b32_e32 v42, 0
	v_mov_b32_e32 v43, 0
	v_mov_b32_e32 v36, 0
	v_mov_b32_e32 v37, 0
	v_mov_b32_e32 v38, 0
	v_mov_b32_e32 v39, 0
	v_mov_b32_e32 v126, 0
	v_mov_b32_e32 v64, 0
	v_mov_b32_e32 v65, 0
	v_mov_b32_e32 v66, 0
	v_mov_b32_e32 v67, 0
	v_mov_b32_e32 v60, 0
	v_mov_b32_e32 v61, 0
	v_mov_b32_e32 v62, 0
	v_mov_b32_e32 v63, 0
	v_mov_b32_e32 v56, 0
	v_mov_b32_e32 v57, 0
	v_mov_b32_e32 v58, 0
	v_mov_b32_e32 v59, 0
	v_mov_b32_e32 v52, 0
	v_mov_b32_e32 v53, 0
	v_mov_b32_e32 v54, 0
	v_mov_b32_e32 v55, 0
	v_mov_b32_e32 v127, 0
	v_mov_b32_e32 v80, 0
	v_mov_b32_e32 v81, 0
	v_mov_b32_e32 v82, 0
	v_mov_b32_e32 v83, 0
	v_mov_b32_e32 v76, 0
	v_mov_b32_e32 v77, 0
	v_mov_b32_e32 v78, 0
	v_mov_b32_e32 v79, 0
	v_mov_b32_e32 v72, 0
	v_mov_b32_e32 v73, 0
	v_mov_b32_e32 v74, 0
	v_mov_b32_e32 v75, 0
	v_mov_b32_e32 v68, 0
	v_mov_b32_e32 v69, 0
	v_mov_b32_e32 v70, 0
	v_mov_b32_e32 v71, 0
	v_mov_b32_e32 v124, 0
	v_mov_b32_e32 v84, 0
	v_mov_b32_e32 v85, 0
	v_mov_b32_e32 v86, 0
	v_mov_b32_e32 v87, 0
	v_mov_b32_e32 v92, 0
	v_mov_b32_e32 v93, 0
	v_mov_b32_e32 v94, 0
	v_mov_b32_e32 v95, 0
	v_mov_b32_e32 v88, 0
	v_mov_b32_e32 v89, 0
	v_mov_b32_e32 v90, 0
	v_mov_b32_e32 v91, 0
	v_mov_b32_e32 v96, 0
	v_mov_b32_e32 v97, 0
	v_mov_b32_e32 v98, 0
	v_mov_b32_e32 v99, 0
	v_mov_b32_e32 v125, 0
	s_mov_b32 s96, 4
	s_lshl_b32 s6, s60, 6
	s_addk_i32 s6, 0xff00
	s_add_u32 s94, s61, s6
	s_addc_u32 s95, 0, 0
	s_mov_b32 vcc_lo, 0
	s_add_i32 s76, s65, 0
	v_add_u32_e32 v144, s76, v111
	v_add3_u32 v193, s76, v210, v205
	v_add_u32_e32 v145, v144, v204
	v_add_u32_e32 v144, v144, v203
	ds_read_b128 v[160:163], v144
	ds_read_b128 v[164:167], v145
	ds_read_b128 v[168:171], v144 offset:2048
	ds_read_b128 v[172:175], v145 offset:2048
	ds_read_b128 v[128:131], v144 offset:4096
	ds_read_b128 v[132:135], v145 offset:4096
	ds_read_b128 v[136:139], v144 offset:6144
	ds_read_b128 v[140:143], v145 offset:6144
	v_add_u32_e32 v158, v193, v206
	v_add_u32_e32 v159, v193, v207
	v_add_u32_e32 v192, v193, v208
	v_add_u32_e32 v193, v193, v209
	s_waitcnt lgkmcnt(4)
	v_mfma_f32_16x16x32_bf16 v[228:231], v[160:163], v[4:7], v[0:3]
	v_mfma_f32_16x16x32_bf16 v[232:235], v[168:171], v[4:7], v[0:3]
	v_mfma_f32_16x16x32_bf16 v[228:231], v[164:167], v[8:11], v[228:231]
	v_mfma_f32_16x16x32_bf16 v[232:235], v[172:175], v[8:11], v[232:235]
	ds_read_b64_tr_b16 v[176:177], v158 offset:16384
	ds_read_b64_tr_b16 v[178:179], v158 offset:18432
	ds_read_b64_tr_b16 v[180:181], v159 offset:16384
	ds_read_b64_tr_b16 v[182:183], v159 offset:18432
	ds_read_b64_tr_b16 v[184:185], v192 offset:16384
	ds_read_b64_tr_b16 v[186:187], v192 offset:18432
	ds_read_b64_tr_b16 v[188:189], v193 offset:16384
	ds_read_b64_tr_b16 v[190:191], v193 offset:18432
	v_mfma_f32_16x16x32_bf16 v[236:239], v[160:163], v[12:15], v[0:3]
	v_exp_f32_e32 v228, v228
	v_exp_f32_e32 v229, v229
	v_exp_f32_e32 v230, v230
	v_mfma_f32_16x16x32_bf16 v[104:107], v[168:171], v[12:15], v[0:3]
	v_exp_f32_e32 v231, v231
	v_exp_f32_e32 v232, v232
	v_pk_add_f32 v[242:243], v[228:229], v[230:231]
	v_mfma_f32_16x16x32_bf16 v[236:239], v[164:167], v[16:19], v[236:239]
	v_exp_f32_e32 v233, v233
	v_exp_f32_e32 v234, v234
	v_pk_add_f32 v[242:243], v[242:243], v[232:233]
	v_cvt_pk_bf16_f32 v228, v228, v229
	v_mfma_f32_16x16x32_bf16 v[104:107], v[172:175], v[16:19], v[104:107]
	v_exp_f32_e32 v235, v235
	v_cvt_pk_bf16_f32 v229, v230, v231
	v_cvt_pk_bf16_f32 v230, v232, v233
	v_cvt_pk_bf16_f32 v231, v234, v235
	v_pk_add_f32 v[242:243], v[242:243], v[234:235]
	v_add_f32_e32 v126, v126, v242
	v_add_f32_e32 v126, v126, v243
	s_waitcnt lgkmcnt(0)
; #define LAS __attribute__((address_space(3)))
; __device__ __forceinline__ s16x4 vtr(const LAS unsigned char* p) { return __builtin_bit_cast(s16x4, __builtin_amdgcn_ds_read_tr16_b64_v4i16((LAS v4i16_t*)p)); }
; __device__ __forceinline__ bf16x8 cat8(s16x4 a, s16x4 b) { return (bf16x8){a[0], a[1], a[2], a[3], b[0], b[1], b[2], b[3]}; }
; __device__ __forceinline__ bf16x8 pack8(const f32x4& a, const f32x4& b) { u32x4 w; w.x = pkbf(a[0], a[1]); w.y = pkbf(a[2], a[3]); w.z = pkbf(b[0], b[1]); w.w = pkbf(b[2], b[3]); return __builtin_bit_cast(bf16x8, w); }
;     ...
;     for (int gh = 0; gh < 4 / GPB; ++gh) {
;         f32x4 S[GPB][4];
; #pragma unroll
;         for (int kb = 0; kb < 4; ++kb) {
;             const bf16x8 kf0 = *(const LAS bf16x8*)(kb0 + (16 * kb) * 128 + kx0), kf1 = *(const LAS bf16x8*)(kb0 + (16 * kb) * 128 + kx1);
; #pragma unroll
;             for (int gi = 0; gi < GPB; ++gi) { S[gi][kb] = __builtin_amdgcn_mfma_f32_16x16x32_bf16(kf0, qf[GPB * gh + gi][0], cinit, 0, 0, 0);
;                 S[gi][kb] = __builtin_amdgcn_mfma_f32_16x16x32_bf16(kf1, qf[GPB * gh + gi][1], S[gi][kb], 0, 0, 0); } }
;         bf16x8 pf[GPB][2];
; #pragma unroll
;         for (int gi = 0; gi < GPB; ++gi) {
;             if (MASK) {
; #pragma unroll
;                 for (int kb = 0; kb < 4; ++kb)
; #pragma unroll
;                     for (int i = 0; i < 4; ++i) { const int rel = rel0 + 16 * kb + 4 * g + i; S[gi][kb][i] = ((unsigned)(rel + 128) > 256u) ? NEGBIG : S[gi][kb][i]; }
;             }
;             ls[GPB * gh + gi] += exp_step<4>(S[gi]);
;             pf[gi][0] = pack8(S[gi][0], S[gi][1]); pf[gi][1] = pack8(S[gi][2], S[gi][3]);
;         }
; #pragma unroll
;         for (int kc = 0; kc < 2; ++kc)
; #pragma unroll
;             for (int db = 0; db < 4; ++db) {
;                 const LAS unsigned char* va = vrow + ((db ^ swz) << 5) + (32 * kc) * 128;
;                 const bf16x8 vf = cat8(vtr(va), vtr(va + 16 * 128));
; #pragma unroll
;                 for (int gi = 0; gi < GPB; ++gi) O[GPB * gh + gi][db] = __builtin_amdgcn_mfma_f32_16x16x32_bf16(vf, pf[gi][kc], O[GPB * gh + gi][db], 0, 0, 0);
;             }
	v_mfma_f32_16x16x32_bf16 v[244:247], v[160:163], v[20:23], v[0:3]
	v_exp_f32_e32 v236, v236
	v_exp_f32_e32 v237, v237
	v_mfma_f32_16x16x32_bf16 v[248:251], v[168:171], v[20:23], v[0:3]
	v_exp_f32_e32 v238, v238
	v_mfma_f32_16x16x32_bf16 v[244:247], v[164:167], v[24:27], v[244:247]
	v_exp_f32_e32 v239, v239
	v_mfma_f32_16x16x32_bf16 v[248:251], v[172:175], v[24:27], v[248:251]
	v_exp_f32_e32 v104, v104
	v_pk_add_f32 v[242:243], v[236:237], v[238:239]
	v_mfma_f32_16x16x32_bf16 v[48:51], v[176:179], v[228:231], v[48:51]
	v_exp_f32_e32 v105, v105
	v_mfma_f32_16x16x32_bf16 v[44:47], v[180:183], v[228:231], v[44:47]
	v_exp_f32_e32 v106, v106
	v_pk_add_f32 v[242:243], v[242:243], v[104:105]
	v_cvt_pk_bf16_f32 v236, v236, v237
	v_mfma_f32_16x16x32_bf16 v[40:43], v[184:187], v[228:231], v[40:43]
	v_exp_f32_e32 v107, v107
	v_cvt_pk_bf16_f32 v237, v238, v239
	v_mfma_f32_16x16x32_bf16 v[36:39], v[188:191], v[228:231], v[36:39]
	v_cvt_pk_bf16_f32 v238, v104, v105
	v_cvt_pk_bf16_f32 v239, v106, v107
	v_pk_add_f32 v[242:243], v[242:243], v[106:107]
	v_add_f32_e32 v127, v127, v242
	v_add_f32_e32 v127, v127, v243
	v_mfma_f32_16x16x32_bf16 v[228:231], v[160:163], v[28:31], v[0:3]
	v_exp_f32_e32 v244, v244
	v_exp_f32_e32 v245, v245
	v_mfma_f32_16x16x32_bf16 v[232:235], v[168:171], v[28:31], v[0:3]
	v_exp_f32_e32 v246, v246
	v_mfma_f32_16x16x32_bf16 v[228:231], v[164:167], v[32:35], v[228:231]
	v_exp_f32_e32 v247, v247
	v_mfma_f32_16x16x32_bf16 v[232:235], v[172:175], v[32:35], v[232:235]
	v_exp_f32_e32 v248, v248
	v_pk_add_f32 v[242:243], v[244:245], v[246:247]
	v_mfma_f32_16x16x32_bf16 v[64:67], v[176:179], v[236:239], v[64:67]
	v_exp_f32_e32 v249, v249
	v_mfma_f32_16x16x32_bf16 v[60:63], v[180:183], v[236:239], v[60:63]
	v_exp_f32_e32 v250, v250
	v_pk_add_f32 v[242:243], v[242:243], v[248:249]
	v_cvt_pk_bf16_f32 v244, v244, v245
	v_mfma_f32_16x16x32_bf16 v[56:59], v[184:187], v[236:239], v[56:59]
	v_exp_f32_e32 v251, v251
	v_cvt_pk_bf16_f32 v245, v246, v247
	v_mfma_f32_16x16x32_bf16 v[52:55], v[188:191], v[236:239], v[52:55]
	v_cvt_pk_bf16_f32 v246, v248, v249
	v_cvt_pk_bf16_f32 v247, v250, v251
	v_pk_add_f32 v[242:243], v[242:243], v[250:251]
	v_add_f32_e32 v124, v124, v242
	v_add_f32_e32 v124, v124, v243
	ds_read_b64_tr_b16 v[160:161], v158 offset:20480
	ds_read_b64_tr_b16 v[162:163], v158 offset:22528
	ds_read_b64_tr_b16 v[164:165], v159 offset:20480
	ds_read_b64_tr_b16 v[166:167], v159 offset:22528
	ds_read_b64_tr_b16 v[168:169], v192 offset:20480
	ds_read_b64_tr_b16 v[170:171], v192 offset:22528
	ds_read_b64_tr_b16 v[172:173], v193 offset:20480
	ds_read_b64_tr_b16 v[174:175], v193 offset:22528
	v_mfma_f32_16x16x32_bf16 v[236:239], v[128:131], v[4:7], v[0:3]
	v_exp_f32_e32 v228, v228
	v_exp_f32_e32 v229, v229
	v_mfma_f32_16x16x32_bf16 v[104:107], v[136:139], v[4:7], v[0:3]
	v_exp_f32_e32 v230, v230
	v_mfma_f32_16x16x32_bf16 v[236:239], v[132:135], v[8:11], v[236:239]
	v_exp_f32_e32 v231, v231
	v_mfma_f32_16x16x32_bf16 v[104:107], v[140:143], v[8:11], v[104:107]
	v_exp_f32_e32 v232, v232
	v_pk_add_f32 v[242:243], v[228:229], v[230:231]
	v_mfma_f32_16x16x32_bf16 v[80:83], v[176:179], v[244:247], v[80:83]
	v_exp_f32_e32 v233, v233
	v_mfma_f32_16x16x32_bf16 v[76:79], v[180:183], v[244:247], v[76:79]
	v_exp_f32_e32 v234, v234
	v_pk_add_f32 v[242:243], v[242:243], v[232:233]
	v_cvt_pk_bf16_f32 v228, v228, v229
	v_mfma_f32_16x16x32_bf16 v[72:75], v[184:187], v[244:247], v[72:75]
	v_exp_f32_e32 v235, v235
	v_cvt_pk_bf16_f32 v229, v230, v231
	v_mfma_f32_16x16x32_bf16 v[68:71], v[188:191], v[244:247], v[68:71]
	v_cvt_pk_bf16_f32 v230, v232, v233
	v_cvt_pk_bf16_f32 v231, v234, v235
	v_pk_add_f32 v[242:243], v[242:243], v[234:235]
	v_add_f32_e32 v125, v125, v242
	v_add_f32_e32 v125, v125, v243
	v_mfma_f32_16x16x32_bf16 v[244:247], v[128:131], v[12:15], v[0:3]
	v_exp_f32_e32 v236, v236
	v_exp_f32_e32 v237, v237
	v_mfma_f32_16x16x32_bf16 v[248:251], v[136:139], v[12:15], v[0:3]
	v_exp_f32_e32 v238, v238
	v_mfma_f32_16x16x32_bf16 v[244:247], v[132:135], v[16:19], v[244:247]
	v_exp_f32_e32 v239, v239
	v_mfma_f32_16x16x32_bf16 v[248:251], v[140:143], v[16:19], v[248:251]
	v_exp_f32_e32 v104, v104
	v_pk_add_f32 v[242:243], v[236:237], v[238:239]
	v_mfma_f32_16x16x32_bf16 v[84:87], v[176:179], v[228:231], v[84:87]
	v_exp_f32_e32 v105, v105
	v_mfma_f32_16x16x32_bf16 v[92:95], v[180:183], v[228:231], v[92:95]
	v_exp_f32_e32 v106, v106
	v_pk_add_f32 v[242:243], v[242:243], v[104:105]
	v_cvt_pk_bf16_f32 v236, v236, v237
	v_mfma_f32_16x16x32_bf16 v[88:91], v[184:187], v[228:231], v[88:91]
	v_exp_f32_e32 v107, v107
	v_cvt_pk_bf16_f32 v237, v238, v239
	v_mfma_f32_16x16x32_bf16 v[96:99], v[188:191], v[228:231], v[96:99]
	v_cvt_pk_bf16_f32 v238, v104, v105
	v_cvt_pk_bf16_f32 v239, v106, v107
	v_pk_add_f32 v[242:243], v[242:243], v[106:107]
	v_add_f32_e32 v126, v126, v242
	v_add_f32_e32 v126, v126, v243
	s_waitcnt lgkmcnt(0)
; #define LAS __attribute__((address_space(3)))
; __device__ __forceinline__ s16x4 vtr(const LAS unsigned char* p) { return __builtin_bit_cast(s16x4, __builtin_amdgcn_ds_read_tr16_b64_v4i16((LAS v4i16_t*)p)); }
;     ...
;     for (int gh = 0; gh < 4 / GPB; ++gh) {
;         f32x4 S[GPB][4];
; #pragma unroll
;         for (int kb = 0; kb < 4; ++kb) {
;             const bf16x8 kf0 = *(const LAS bf16x8*)(kb0 + (16 * kb) * 128 + kx0), kf1 = *(const LAS bf16x8*)(kb0 + (16 * kb) * 128 + kx1);
; #pragma unroll
;             for (int gi = 0; gi < GPB; ++gi) { S[gi][kb] = __builtin_amdgcn_mfma_f32_16x16x32_bf16(kf0, qf[GPB * gh + gi][0], cinit, 0, 0, 0);
;                 S[gi][kb] = __builtin_amdgcn_mfma_f32_16x16x32_bf16(kf1, qf[GPB * gh + gi][1], S[gi][kb], 0, 0, 0); } }
;         bf16x8 pf[GPB][2];
; #pragma unroll
;         for (int gi = 0; gi < GPB; ++gi) {
;             if (MASK) {
; #pragma unroll
;                 for (int kb = 0; kb < 4; ++kb)
; #pragma unroll
;                     for (int i = 0; i < 4; ++i) { const int rel = rel0 + 16 * kb + 4 * g + i; S[gi][kb][i] = ((unsigned)(rel + 128) > 256u) ? NEGBIG : S[gi][kb][i]; }
;             }
;             ls[GPB * gh + gi] += exp_step<4>(S[gi]);
;             pf[gi][0] = pack8(S[gi][0], S[gi][1]); pf[gi][1] = pack8(S[gi][2], S[gi][3]);
;         }
; #pragma unroll
;         for (int kc = 0; kc < 2; ++kc)
; #pragma unroll
;             for (int db = 0; db < 4; ++db) {
;                 const LAS unsigned char* va = vrow + ((db ^ swz) << 5) + (32 * kc) * 128;
;                 const bf16x8 vf = cat8(vtr(va), vtr(va + 16 * 128));
; #pragma unroll
;                 for (int gi = 0; gi < GPB; ++gi) O[GPB * gh + gi][db] = __builtin_amdgcn_mfma_f32_16x16x32_bf16(vf, pf[gi][kc], O[GPB * gh + gi][db], 0, 0, 0);
;             }
; __device__ __forceinline__ void na_phase(LAS unsigned char* lds, const bf16_t* Q, const bf16_t* K, const bf16_t* V, bf16_t* Ob, const float* rpb, float negb) {
;     ...
;         for (int t = 0; t < 4; ++t) {
;             dma_tile<2>(lds + ((t + 3) & 3) * NA_BUF, K, V, NA_ROW0(t + 3), DM, dl, w);
;             const LAS unsigned char* buf = lds + (t & 3) * NA_BUF;
;             full_tile<0, 1, 2>(O, ls, qf, negb, buf + hh * 8192, buf + 2 * 8192 + hh * 8192, lane, 0);
;             ring_wait<4>();
	v_mfma_f32_16x16x32_bf16 v[228:231], v[128:131], v[20:23], v[0:3]
	v_exp_f32_e32 v244, v244
	v_exp_f32_e32 v245, v245
	v_mfma_f32_16x16x32_bf16 v[232:235], v[136:139], v[20:23], v[0:3]
	v_exp_f32_e32 v246, v246
	v_mfma_f32_16x16x32_bf16 v[228:231], v[132:135], v[24:27], v[228:231]
	v_exp_f32_e32 v247, v247
	v_mfma_f32_16x16x32_bf16 v[232:235], v[140:143], v[24:27], v[232:235]
	v_exp_f32_e32 v248, v248
	v_pk_add_f32 v[242:243], v[244:245], v[246:247]
	v_mfma_f32_16x16x32_bf16 v[48:51], v[160:163], v[236:239], v[48:51]
	v_exp_f32_e32 v249, v249
	v_mfma_f32_16x16x32_bf16 v[44:47], v[164:167], v[236:239], v[44:47]
	v_exp_f32_e32 v250, v250
	v_pk_add_f32 v[242:243], v[242:243], v[248:249]
	v_cvt_pk_bf16_f32 v244, v244, v245
	v_mfma_f32_16x16x32_bf16 v[40:43], v[168:171], v[236:239], v[40:43]
	v_exp_f32_e32 v251, v251
	v_cvt_pk_bf16_f32 v245, v246, v247
	v_mfma_f32_16x16x32_bf16 v[36:39], v[172:175], v[236:239], v[36:39]
	v_cvt_pk_bf16_f32 v246, v248, v249
	v_cvt_pk_bf16_f32 v247, v250, v251
	v_pk_add_f32 v[242:243], v[242:243], v[250:251]
	v_add_f32_e32 v127, v127, v242
	v_add_f32_e32 v127, v127, v243
	v_mfma_f32_16x16x32_bf16 v[236:239], v[128:131], v[28:31], v[0:3]
	v_exp_f32_e32 v228, v228
	v_exp_f32_e32 v229, v229
	v_mfma_f32_16x16x32_bf16 v[104:107], v[136:139], v[28:31], v[0:3]
	v_exp_f32_e32 v230, v230
	v_mfma_f32_16x16x32_bf16 v[236:239], v[132:135], v[32:35], v[236:239]
	v_exp_f32_e32 v231, v231
	v_mfma_f32_16x16x32_bf16 v[104:107], v[140:143], v[32:35], v[104:107]
	v_exp_f32_e32 v232, v232
	v_pk_add_f32 v[242:243], v[228:229], v[230:231]
	v_mfma_f32_16x16x32_bf16 v[64:67], v[160:163], v[244:247], v[64:67]
	v_exp_f32_e32 v233, v233
	v_mfma_f32_16x16x32_bf16 v[60:63], v[164:167], v[244:247], v[60:63]
	v_exp_f32_e32 v234, v234
	v_pk_add_f32 v[242:243], v[242:243], v[232:233]
	v_cvt_pk_bf16_f32 v228, v228, v229
	v_mfma_f32_16x16x32_bf16 v[56:59], v[168:171], v[244:247], v[56:59]
	v_exp_f32_e32 v235, v235
	v_cvt_pk_bf16_f32 v229, v230, v231
	v_mfma_f32_16x16x32_bf16 v[52:55], v[172:175], v[244:247], v[52:55]
	v_cvt_pk_bf16_f32 v230, v232, v233
	v_cvt_pk_bf16_f32 v231, v234, v235
	v_pk_add_f32 v[242:243], v[242:243], v[234:235]
	v_add_f32_e32 v124, v124, v242
	v_add_f32_e32 v124, v124, v243
	v_mfma_f32_16x16x32_bf16 v[80:83], v[160:163], v[228:231], v[80:83]
	v_exp_f32_e32 v236, v236
	v_exp_f32_e32 v237, v237
	v_exp_f32_e32 v238, v238
	v_mfma_f32_16x16x32_bf16 v[76:79], v[164:167], v[228:231], v[76:79]
	v_exp_f32_e32 v239, v239
	v_exp_f32_e32 v104, v104
	v_pk_add_f32 v[242:243], v[236:237], v[238:239]
	v_mfma_f32_16x16x32_bf16 v[72:75], v[168:171], v[228:231], v[72:75]
	v_exp_f32_e32 v105, v105
	v_exp_f32_e32 v106, v106
	v_pk_add_f32 v[242:243], v[242:243], v[104:105]
	v_cvt_pk_bf16_f32 v236, v236, v237
	v_mfma_f32_16x16x32_bf16 v[68:71], v[172:175], v[228:231], v[68:71]
	v_exp_f32_e32 v107, v107
	v_cvt_pk_bf16_f32 v237, v238, v239
	v_cvt_pk_bf16_f32 v238, v104, v105
	v_cvt_pk_bf16_f32 v239, v106, v107
	v_pk_add_f32 v[242:243], v[242:243], v[106:107]
	v_add_f32_e32 v125, v125, v242
	v_add_f32_e32 v125, v125, v243
	v_mfma_f32_16x16x32_bf16 v[84:87], v[160:163], v[236:239], v[84:87]
	v_mfma_f32_16x16x32_bf16 v[92:95], v[164:167], v[236:239], v[92:95]
	v_mfma_f32_16x16x32_bf16 v[88:91], v[168:171], v[236:239], v[88:91]
	v_mfma_f32_16x16x32_bf16 v[96:99], v[172:175], v[236:239], v[96:99]
	s_waitcnt vmcnt(8)
	s_barrier
	s_cmp_lt_i32 s96, s93
	s_cselect_b32 s7, s95, 0
	s_cselect_b32 s6, s94, s82
	s_lshl_b64 s[6:7], s[6:7], 11
	s_add_u32 s76, s67, s6
	s_addc_u32 s77, s4, s7
	s_add_u32 s6, s5, s6
	s_addc_u32 s7, s58, s7
	s_add_i32 s59, s69, vcc_lo
	s_mov_b32 vcc_hi, m0
	s_mov_b32 m0, s59
	s_nop 0
	global_load_lds_dwordx4 v221, s[76:77]
	s_mov_b32 m0, vcc_hi
	s_add_i32 s66, s59, 0x4000
	s_mov_b32 vcc_hi, m0
	s_mov_b32 m0, s66
	s_nop 0
	global_load_lds_dwordx4 v222, s[6:7]
	s_mov_b32 m0, vcc_hi
	s_add_i32 s66, s59, 0x2000
	s_mov_b32 vcc_hi, m0
	s_mov_b32 m0, s66
	s_nop 0
	global_load_lds_dwordx4 v223, s[76:77]
	s_mov_b32 m0, vcc_hi
	s_addk_i32 s59, 0x6000
	s_mov_b32 s66, m0
	s_mov_b32 m0, s59
	s_nop 0
	global_load_lds_dwordx4 v224, s[6:7]
	s_mov_b32 m0, s66
	s_add_i32 s76, s65, vcc_lo
	s_add_i32 s76, s76, 0x8000
	v_add_u32_e32 v144, s76, v111
	v_add3_u32 v193, s76, v210, v205
	v_add_u32_e32 v145, v144, v204
	v_add_u32_e32 v144, v144, v203
	ds_read_b128 v[160:163], v144
	ds_read_b128 v[164:167], v145
	ds_read_b128 v[168:171], v144 offset:2048
	ds_read_b128 v[172:175], v145 offset:2048
	ds_read_b128 v[128:131], v144 offset:4096
	ds_read_b128 v[132:135], v145 offset:4096
	ds_read_b128 v[136:139], v144 offset:6144
	ds_read_b128 v[140:143], v145 offset:6144
	v_add_u32_e32 v158, v193, v206
	v_add_u32_e32 v159, v193, v207
	v_add_u32_e32 v192, v193, v208
	v_add_u32_e32 v193, v193, v209
	s_waitcnt lgkmcnt(4)
	v_mfma_f32_16x16x32_bf16 v[228:231], v[160:163], v[4:7], v[0:3]
	v_mfma_f32_16x16x32_bf16 v[232:235], v[168:171], v[4:7], v[0:3]
	v_mfma_f32_16x16x32_bf16 v[228:231], v[164:167], v[8:11], v[228:231]
	v_mfma_f32_16x16x32_bf16 v[232:235], v[172:175], v[8:11], v[232:235]
	ds_read_b64_tr_b16 v[176:177], v158 offset:16384
	ds_read_b64_tr_b16 v[178:179], v158 offset:18432
	ds_read_b64_tr_b16 v[180:181], v159 offset:16384
	ds_read_b64_tr_b16 v[182:183], v159 offset:18432
	ds_read_b64_tr_b16 v[184:185], v192 offset:16384
	ds_read_b64_tr_b16 v[186:187], v192 offset:18432
	ds_read_b64_tr_b16 v[188:189], v193 offset:16384
	ds_read_b64_tr_b16 v[190:191], v193 offset:18432
	v_mfma_f32_16x16x32_bf16 v[236:239], v[160:163], v[12:15], v[0:3]
	v_exp_f32_e32 v228, v228
	v_exp_f32_e32 v229, v229
	v_exp_f32_e32 v230, v230
	v_mfma_f32_16x16x32_bf16 v[104:107], v[168:171], v[12:15], v[0:3]
	v_exp_f32_e32 v231, v231
	v_exp_f32_e32 v232, v232
	v_pk_add_f32 v[242:243], v[228:229], v[230:231]
	v_mfma_f32_16x16x32_bf16 v[236:239], v[164:167], v[16:19], v[236:239]
	v_exp_f32_e32 v233, v233
	v_exp_f32_e32 v234, v234
	v_pk_add_f32 v[242:243], v[242:243], v[232:233]
	v_cvt_pk_bf16_f32 v228, v228, v229
	v_mfma_f32_16x16x32_bf16 v[104:107], v[172:175], v[16:19], v[104:107]
	v_exp_f32_e32 v235, v235
	v_cvt_pk_bf16_f32 v229, v230, v231
	v_cvt_pk_bf16_f32 v230, v232, v233
	v_cvt_pk_bf16_f32 v231, v234, v235
	v_pk_add_f32 v[242:243], v[242:243], v[234:235]
	v_add_f32_e32 v126, v126, v242
	v_add_f32_e32 v126, v126, v243
	s_waitcnt lgkmcnt(0)
; #define LAS __attribute__((address_space(3)))
; __device__ __forceinline__ s16x4 vtr(const LAS unsigned char* p) { return __builtin_bit_cast(s16x4, __builtin_amdgcn_ds_read_tr16_b64_v4i16((LAS v4i16_t*)p)); }
; __device__ __forceinline__ bf16x8 cat8(s16x4 a, s16x4 b) { return (bf16x8){a[0], a[1], a[2], a[3], b[0], b[1], b[2], b[3]}; }
; __device__ __forceinline__ bf16x8 pack8(const f32x4& a, const f32x4& b) { u32x4 w; w.x = pkbf(a[0], a[1]); w.y = pkbf(a[2], a[3]); w.z = pkbf(b[0], b[1]); w.w = pkbf(b[2], b[3]); return __builtin_bit_cast(bf16x8, w); }
;     ...
;     for (int gh = 0; gh < 4 / GPB; ++gh) {
;         f32x4 S[GPB][4];
; #pragma unroll
;         for (int kb = 0; kb < 4; ++kb) {
;             const bf16x8 kf0 = *(const LAS bf16x8*)(kb0 + (16 * kb) * 128 + kx0), kf1 = *(const LAS bf16x8*)(kb0 + (16 * kb) * 128 + kx1);
; #pragma unroll
;             for (int gi = 0; gi < GPB; ++gi) { S[gi][kb] = __builtin_amdgcn_mfma_f32_16x16x32_bf16(kf0, qf[GPB * gh + gi][0], cinit, 0, 0, 0);
;                 S[gi][kb] = __builtin_amdgcn_mfma_f32_16x16x32_bf16(kf1, qf[GPB * gh + gi][1], S[gi][kb], 0, 0, 0); } }
;         bf16x8 pf[GPB][2];
; #pragma unroll
;         for (int gi = 0; gi < GPB; ++gi) {
;             if (MASK) {
; #pragma unroll
;                 for (int kb = 0; kb < 4; ++kb)
; #pragma unroll
;                     for (int i = 0; i < 4; ++i) { const int rel = rel0 + 16 * kb + 4 * g + i; S[gi][kb][i] = ((unsigned)(rel + 128) > 256u) ? NEGBIG : S[gi][kb][i]; }
;             }
;             ls[GPB * gh + gi] += exp_step<4>(S[gi]);
;             pf[gi][0] = pack8(S[gi][0], S[gi][1]); pf[gi][1] = pack8(S[gi][2], S[gi][3]);
;         }
; #pragma unroll
;         for (int kc = 0; kc < 2; ++kc)
; #pragma unroll
;             for (int db = 0; db < 4; ++db) {
;                 const LAS unsigned char* va = vrow + ((db ^ swz) << 5) + (32 * kc) * 128;
;                 const bf16x8 vf = cat8(vtr(va), vtr(va + 16 * 128));
; #pragma unroll
;                 for (int gi = 0; gi < GPB; ++gi) O[GPB * gh + gi][db] = __builtin_amdgcn_mfma_f32_16x16x32_bf16(vf, pf[gi][kc], O[GPB * gh + gi][db], 0, 0, 0);
;             }
	v_mfma_f32_16x16x32_bf16 v[244:247], v[160:163], v[20:23], v[0:3]
	v_exp_f32_e32 v236, v236
	v_exp_f32_e32 v237, v237
	v_mfma_f32_16x16x32_bf16 v[248:251], v[168:171], v[20:23], v[0:3]
	v_exp_f32_e32 v238, v238
	v_mfma_f32_16x16x32_bf16 v[244:247], v[164:167], v[24:27], v[244:247]
	v_exp_f32_e32 v239, v239
	v_mfma_f32_16x16x32_bf16 v[248:251], v[172:175], v[24:27], v[248:251]
	v_exp_f32_e32 v104, v104
	v_pk_add_f32 v[242:243], v[236:237], v[238:239]
	v_mfma_f32_16x16x32_bf16 v[48:51], v[176:179], v[228:231], v[48:51]
	v_exp_f32_e32 v105, v105
	v_mfma_f32_16x16x32_bf16 v[44:47], v[180:183], v[228:231], v[44:47]
	v_exp_f32_e32 v106, v106
	v_pk_add_f32 v[242:243], v[242:243], v[104:105]
	v_cvt_pk_bf16_f32 v236, v236, v237
	v_mfma_f32_16x16x32_bf16 v[40:43], v[184:187], v[228:231], v[40:43]
	v_exp_f32_e32 v107, v107
	v_cvt_pk_bf16_f32 v237, v238, v239
	v_mfma_f32_16x16x32_bf16 v[36:39], v[188:191], v[228:231], v[36:39]
	v_cvt_pk_bf16_f32 v238, v104, v105
	v_cvt_pk_bf16_f32 v239, v106, v107
	v_pk_add_f32 v[242:243], v[242:243], v[106:107]
	v_add_f32_e32 v127, v127, v242
	v_add_f32_e32 v127, v127, v243
	v_mfma_f32_16x16x32_bf16 v[228:231], v[160:163], v[28:31], v[0:3]
	v_exp_f32_e32 v244, v244
	v_exp_f32_e32 v245, v245
	v_mfma_f32_16x16x32_bf16 v[232:235], v[168:171], v[28:31], v[0:3]
	v_exp_f32_e32 v246, v246
	v_mfma_f32_16x16x32_bf16 v[228:231], v[164:167], v[32:35], v[228:231]
	v_exp_f32_e32 v247, v247
	v_mfma_f32_16x16x32_bf16 v[232:235], v[172:175], v[32:35], v[232:235]
	v_exp_f32_e32 v248, v248
	v_pk_add_f32 v[242:243], v[244:245], v[246:247]
	v_mfma_f32_16x16x32_bf16 v[64:67], v[176:179], v[236:239], v[64:67]
	v_exp_f32_e32 v249, v249
	v_mfma_f32_16x16x32_bf16 v[60:63], v[180:183], v[236:239], v[60:63]
	v_exp_f32_e32 v250, v250
	v_pk_add_f32 v[242:243], v[242:243], v[248:249]
	v_cvt_pk_bf16_f32 v244, v244, v245
	v_mfma_f32_16x16x32_bf16 v[56:59], v[184:187], v[236:239], v[56:59]
	v_exp_f32_e32 v251, v251
	v_cvt_pk_bf16_f32 v245, v246, v247
	v_mfma_f32_16x16x32_bf16 v[52:55], v[188:191], v[236:239], v[52:55]
	v_cvt_pk_bf16_f32 v246, v248, v249
	v_cvt_pk_bf16_f32 v247, v250, v251
	v_pk_add_f32 v[242:243], v[242:243], v[250:251]
	v_add_f32_e32 v124, v124, v242
	v_add_f32_e32 v124, v124, v243
	ds_read_b64_tr_b16 v[160:161], v158 offset:20480
	ds_read_b64_tr_b16 v[162:163], v158 offset:22528
	ds_read_b64_tr_b16 v[164:165], v159 offset:20480
	ds_read_b64_tr_b16 v[166:167], v159 offset:22528
	ds_read_b64_tr_b16 v[168:169], v192 offset:20480
	ds_read_b64_tr_b16 v[170:171], v192 offset:22528
	ds_read_b64_tr_b16 v[172:173], v193 offset:20480
	ds_read_b64_tr_b16 v[174:175], v193 offset:22528
	v_mfma_f32_16x16x32_bf16 v[236:239], v[128:131], v[4:7], v[0:3]
	v_exp_f32_e32 v228, v228
	v_exp_f32_e32 v229, v229
	v_mfma_f32_16x16x32_bf16 v[104:107], v[136:139], v[4:7], v[0:3]
	v_exp_f32_e32 v230, v230
	v_mfma_f32_16x16x32_bf16 v[236:239], v[132:135], v[8:11], v[236:239]
	v_exp_f32_e32 v231, v231
	v_mfma_f32_16x16x32_bf16 v[104:107], v[140:143], v[8:11], v[104:107]
	v_exp_f32_e32 v232, v232
	v_pk_add_f32 v[242:243], v[228:229], v[230:231]
	v_mfma_f32_16x16x32_bf16 v[80:83], v[176:179], v[244:247], v[80:83]
	v_exp_f32_e32 v233, v233
	v_mfma_f32_16x16x32_bf16 v[76:79], v[180:183], v[244:247], v[76:79]
	v_exp_f32_e32 v234, v234
	v_pk_add_f32 v[242:243], v[242:243], v[232:233]
	v_cvt_pk_bf16_f32 v228, v228, v229
	v_mfma_f32_16x16x32_bf16 v[72:75], v[184:187], v[244:247], v[72:75]
	v_exp_f32_e32 v235, v235
	v_cvt_pk_bf16_f32 v229, v230, v231
	v_mfma_f32_16x16x32_bf16 v[68:71], v[188:191], v[244:247], v[68:71]
	v_cvt_pk_bf16_f32 v230, v232, v233
	v_cvt_pk_bf16_f32 v231, v234, v235
	v_pk_add_f32 v[242:243], v[242:243], v[234:235]
	v_add_f32_e32 v125, v125, v242
	v_add_f32_e32 v125, v125, v243
	v_mfma_f32_16x16x32_bf16 v[244:247], v[128:131], v[12:15], v[0:3]
	v_exp_f32_e32 v236, v236
	v_exp_f32_e32 v237, v237
	v_mfma_f32_16x16x32_bf16 v[248:251], v[136:139], v[12:15], v[0:3]
	v_exp_f32_e32 v238, v238
	v_mfma_f32_16x16x32_bf16 v[244:247], v[132:135], v[16:19], v[244:247]
	v_exp_f32_e32 v239, v239
	v_mfma_f32_16x16x32_bf16 v[248:251], v[140:143], v[16:19], v[248:251]
	v_exp_f32_e32 v104, v104
	v_pk_add_f32 v[242:243], v[236:237], v[238:239]
	v_mfma_f32_16x16x32_bf16 v[84:87], v[176:179], v[228:231], v[84:87]
	v_exp_f32_e32 v105, v105
	v_mfma_f32_16x16x32_bf16 v[92:95], v[180:183], v[228:231], v[92:95]
	v_exp_f32_e32 v106, v106
	v_pk_add_f32 v[242:243], v[242:243], v[104:105]
	v_cvt_pk_bf16_f32 v236, v236, v237
	v_mfma_f32_16x16x32_bf16 v[88:91], v[184:187], v[228:231], v[88:91]
	v_exp_f32_e32 v107, v107
	v_cvt_pk_bf16_f32 v237, v238, v239
	v_mfma_f32_16x16x32_bf16 v[96:99], v[188:191], v[228:231], v[96:99]
	v_cvt_pk_bf16_f32 v238, v104, v105
	v_cvt_pk_bf16_f32 v239, v106, v107
	v_pk_add_f32 v[242:243], v[242:243], v[106:107]
	v_add_f32_e32 v126, v126, v242
	v_add_f32_e32 v126, v126, v243
	s_waitcnt lgkmcnt(0)
; #define LAS __attribute__((address_space(3)))
; __device__ __forceinline__ s16x4 vtr(const LAS unsigned char* p) { return __builtin_bit_cast(s16x4, __builtin_amdgcn_ds_read_tr16_b64_v4i16((LAS v4i16_t*)p)); }
;     ...
;     for (int gh = 0; gh < 4 / GPB; ++gh) {
;         f32x4 S[GPB][4];
; #pragma unroll
;         for (int kb = 0; kb < 4; ++kb) {
;             const bf16x8 kf0 = *(const LAS bf16x8*)(kb0 + (16 * kb) * 128 + kx0), kf1 = *(const LAS bf16x8*)(kb0 + (16 * kb) * 128 + kx1);
; #pragma unroll
;             for (int gi = 0; gi < GPB; ++gi) { S[gi][kb] = __builtin_amdgcn_mfma_f32_16x16x32_bf16(kf0, qf[GPB * gh + gi][0], cinit, 0, 0, 0);
;                 S[gi][kb] = __builtin_amdgcn_mfma_f32_16x16x32_bf16(kf1, qf[GPB * gh + gi][1], S[gi][kb], 0, 0, 0); } }
;         bf16x8 pf[GPB][2];
; #pragma unroll
;         for (int gi = 0; gi < GPB; ++gi) {
;             if (MASK) {
; #pragma unroll
;                 for (int kb = 0; kb < 4; ++kb)
; #pragma unroll
;                     for (int i = 0; i < 4; ++i) { const int rel = rel0 + 16 * kb + 4 * g + i; S[gi][kb][i] = ((unsigned)(rel + 128) > 256u) ? NEGBIG : S[gi][kb][i]; }
;             }
;             ls[GPB * gh + gi] += exp_step<4>(S[gi]);
;             pf[gi][0] = pack8(S[gi][0], S[gi][1]); pf[gi][1] = pack8(S[gi][2], S[gi][3]);
;         }
; #pragma unroll
;         for (int kc = 0; kc < 2; ++kc)
; #pragma unroll
;             for (int db = 0; db < 4; ++db) {
;                 const LAS unsigned char* va = vrow + ((db ^ swz) << 5) + (32 * kc) * 128;
;                 const bf16x8 vf = cat8(vtr(va), vtr(va + 16 * 128));
; #pragma unroll
;                 for (int gi = 0; gi < GPB; ++gi) O[GPB * gh + gi][db] = __builtin_amdgcn_mfma_f32_16x16x32_bf16(vf, pf[gi][kc], O[GPB * gh + gi][db], 0, 0, 0);
;             }
; __device__ __forceinline__ void na_phase(LAS unsigned char* lds, const bf16_t* Q, const bf16_t* K, const bf16_t* V, bf16_t* Ob, const float* rpb, float negb) {
;     ...
;         for (int t = 0; t < 4; ++t) {
;             dma_tile<2>(lds + ((t + 3) & 3) * NA_BUF, K, V, NA_ROW0(t + 3), DM, dl, w);
;             const LAS unsigned char* buf = lds + (t & 3) * NA_BUF;
;             full_tile<0, 1, 2>(O, ls, qf, negb, buf + hh * 8192, buf + 2 * 8192 + hh * 8192, lane, 0);
;             ring_wait<4>();
	v_mfma_f32_16x16x32_bf16 v[228:231], v[128:131], v[20:23], v[0:3]
	v_exp_f32_e32 v244, v244
	v_exp_f32_e32 v245, v245
	v_mfma_f32_16x16x32_bf16 v[232:235], v[136:139], v[20:23], v[0:3]
	v_exp_f32_e32 v246, v246
	v_mfma_f32_16x16x32_bf16 v[228:231], v[132:135], v[24:27], v[228:231]
	v_exp_f32_e32 v247, v247
	v_mfma_f32_16x16x32_bf16 v[232:235], v[140:143], v[24:27], v[232:235]
	v_exp_f32_e32 v248, v248
	v_pk_add_f32 v[242:243], v[244:245], v[246:247]
	v_mfma_f32_16x16x32_bf16 v[48:51], v[160:163], v[236:239], v[48:51]
	v_exp_f32_e32 v249, v249
	v_mfma_f32_16x16x32_bf16 v[44:47], v[164:167], v[236:239], v[44:47]
	v_exp_f32_e32 v250, v250
	v_pk_add_f32 v[242:243], v[242:243], v[248:249]
	v_cvt_pk_bf16_f32 v244, v244, v245
	v_mfma_f32_16x16x32_bf16 v[40:43], v[168:171], v[236:239], v[40:43]
	v_exp_f32_e32 v251, v251
	v_cvt_pk_bf16_f32 v245, v246, v247
	v_mfma_f32_16x16x32_bf16 v[36:39], v[172:175], v[236:239], v[36:39]
	v_cvt_pk_bf16_f32 v246, v248, v249
	v_cvt_pk_bf16_f32 v247, v250, v251
	v_pk_add_f32 v[242:243], v[242:243], v[250:251]
	v_add_f32_e32 v127, v127, v242
	v_add_f32_e32 v127, v127, v243
	v_mfma_f32_16x16x32_bf16 v[236:239], v[128:131], v[28:31], v[0:3]
	v_exp_f32_e32 v228, v228
	v_exp_f32_e32 v229, v229
	v_mfma_f32_16x16x32_bf16 v[104:107], v[136:139], v[28:31], v[0:3]
	v_exp_f32_e32 v230, v230
	v_mfma_f32_16x16x32_bf16 v[236:239], v[132:135], v[32:35], v[236:239]
	v_exp_f32_e32 v231, v231
	v_mfma_f32_16x16x32_bf16 v[104:107], v[140:143], v[32:35], v[104:107]
	v_exp_f32_e32 v232, v232
	v_pk_add_f32 v[242:243], v[228:229], v[230:231]
	v_mfma_f32_16x16x32_bf16 v[64:67], v[160:163], v[244:247], v[64:67]
	v_exp_f32_e32 v233, v233
	v_mfma_f32_16x16x32_bf16 v[60:63], v[164:167], v[244:247], v[60:63]
	v_exp_f32_e32 v234, v234
	v_pk_add_f32 v[242:243], v[242:243], v[232:233]
	v_cvt_pk_bf16_f32 v228, v228, v229
	v_mfma_f32_16x16x32_bf16 v[56:59], v[168:171], v[244:247], v[56:59]
	v_exp_f32_e32 v235, v235
	v_cvt_pk_bf16_f32 v229, v230, v231
	v_mfma_f32_16x16x32_bf16 v[52:55], v[172:175], v[244:247], v[52:55]
	v_cvt_pk_bf16_f32 v230, v232, v233
	v_cvt_pk_bf16_f32 v231, v234, v235
	v_pk_add_f32 v[242:243], v[242:243], v[234:235]
	v_add_f32_e32 v124, v124, v242
	v_add_f32_e32 v124, v124, v243
	v_mfma_f32_16x16x32_bf16 v[80:83], v[160:163], v[228:231], v[80:83]
	v_exp_f32_e32 v236, v236
	v_exp_f32_e32 v237, v237
	v_exp_f32_e32 v238, v238
	v_mfma_f32_16x16x32_bf16 v[76:79], v[164:167], v[228:231], v[76:79]
	v_exp_f32_e32 v239, v239
	v_exp_f32_e32 v104, v104
	v_pk_add_f32 v[242:243], v[236:237], v[238:239]
	v_mfma_f32_16x16x32_bf16 v[72:75], v[168:171], v[228:231], v[72:75]
	v_exp_f32_e32 v105, v105
	v_exp_f32_e32 v106, v106
	v_pk_add_f32 v[242:243], v[242:243], v[104:105]
	v_cvt_pk_bf16_f32 v236, v236, v237
	v_mfma_f32_16x16x32_bf16 v[68:71], v[172:175], v[228:231], v[68:71]
	v_exp_f32_e32 v107, v107
	v_cvt_pk_bf16_f32 v237, v238, v239
	v_cvt_pk_bf16_f32 v238, v104, v105
	v_cvt_pk_bf16_f32 v239, v106, v107
	v_pk_add_f32 v[242:243], v[242:243], v[106:107]
	v_add_f32_e32 v125, v125, v242
	v_add_f32_e32 v125, v125, v243
	v_mfma_f32_16x16x32_bf16 v[84:87], v[160:163], v[236:239], v[84:87]
	v_mfma_f32_16x16x32_bf16 v[92:95], v[164:167], v[236:239], v[92:95]
	v_mfma_f32_16x16x32_bf16 v[88:91], v[168:171], v[236:239], v[88:91]
	v_mfma_f32_16x16x32_bf16 v[96:99], v[172:175], v[236:239], v[96:99]
	s_add_i32 vcc_lo, vcc_lo, 0x8000
	s_add_u32 s94, s94, 64
	s_addc_u32 s95, s95, 0
	s_add_i32 s96, s96, 1
	s_waitcnt vmcnt(8)
	s_barrier
	s_cmp_lt_i32 s96, s93
	s_cselect_b32 s7, s95, 0
	s_cselect_b32 s6, s94, s82
	s_lshl_b64 s[6:7], s[6:7], 11
	s_add_u32 s76, s67, s6
	s_addc_u32 s77, s4, s7
	s_add_u32 s6, s5, s6
	s_addc_u32 s7, s58, s7
	s_add_i32 s59, s69, vcc_lo
	s_mov_b32 vcc_hi, m0
	s_mov_b32 m0, s59
	s_nop 0
	global_load_lds_dwordx4 v221, s[76:77]
	s_mov_b32 m0, vcc_hi
	s_add_i32 s66, s59, 0x4000
	s_mov_b32 vcc_hi, m0
	s_mov_b32 m0, s66
	s_nop 0
	global_load_lds_dwordx4 v222, s[6:7]
	s_mov_b32 m0, vcc_hi
	s_add_i32 s66, s59, 0x2000
	s_mov_b32 vcc_hi, m0
	s_mov_b32 m0, s66
	s_nop 0
	global_load_lds_dwordx4 v223, s[76:77]
	s_mov_b32 m0, vcc_hi
	s_addk_i32 s59, 0x6000
	s_mov_b32 s66, m0
	s_mov_b32 m0, s59
	s_nop 0
	global_load_lds_dwordx4 v224, s[6:7]
	s_mov_b32 m0, s66
	s_add_i32 s76, s65, vcc_lo
	s_add_i32 s76, s76, 0x8000
	v_add_u32_e32 v144, s76, v111
	v_add3_u32 v193, s76, v210, v205
	v_add_u32_e32 v145, v144, v204
	v_add_u32_e32 v144, v144, v203
	ds_read_b128 v[160:163], v144
	ds_read_b128 v[164:167], v145
	ds_read_b128 v[168:171], v144 offset:2048
	ds_read_b128 v[172:175], v145 offset:2048
	ds_read_b128 v[128:131], v144 offset:4096
	ds_read_b128 v[132:135], v145 offset:4096
	ds_read_b128 v[136:139], v144 offset:6144
	ds_read_b128 v[140:143], v145 offset:6144
	v_add_u32_e32 v158, v193, v206
	v_add_u32_e32 v159, v193, v207
	v_add_u32_e32 v192, v193, v208
	v_add_u32_e32 v193, v193, v209
	s_waitcnt lgkmcnt(4)
; #define LAS __attribute__((address_space(3)))
; __device__ __forceinline__ s16x4 vtr(const LAS unsigned char* p) { return __builtin_bit_cast(s16x4, __builtin_amdgcn_ds_read_tr16_b64_v4i16((LAS v4i16_t*)p)); }
; __device__ __forceinline__ bf16x8 cat8(s16x4 a, s16x4 b) { return (bf16x8){a[0], a[1], a[2], a[3], b[0], b[1], b[2], b[3]}; }
; __device__ __forceinline__ bf16x8 pack8(const f32x4& a, const f32x4& b) { u32x4 w; w.x = pkbf(a[0], a[1]); w.y = pkbf(a[2], a[3]); w.z = pkbf(b[0], b[1]); w.w = pkbf(b[2], b[3]); return __builtin_bit_cast(bf16x8, w); }
;     ...
;     for (int gh = 0; gh < 4 / GPB; ++gh) {
;         f32x4 S[GPB][4];
; #pragma unroll
;         for (int kb = 0; kb < 4; ++kb) {
;             const bf16x8 kf0 = *(const LAS bf16x8*)(kb0 + (16 * kb) * 128 + kx0), kf1 = *(const LAS bf16x8*)(kb0 + (16 * kb) * 128 + kx1);
; #pragma unroll
;             for (int gi = 0; gi < GPB; ++gi) { S[gi][kb] = __builtin_amdgcn_mfma_f32_16x16x32_bf16(kf0, qf[GPB * gh + gi][0], cinit, 0, 0, 0);
;                 S[gi][kb] = __builtin_amdgcn_mfma_f32_16x16x32_bf16(kf1, qf[GPB * gh + gi][1], S[gi][kb], 0, 0, 0); } }
;         bf16x8 pf[GPB][2];
; #pragma unroll
;         for (int gi = 0; gi < GPB; ++gi) {
;             if (MASK) {
; #pragma unroll
;                 for (int kb = 0; kb < 4; ++kb)
; #pragma unroll
;                     for (int i = 0; i < 4; ++i) { const int rel = rel0 + 16 * kb + 4 * g + i; S[gi][kb][i] = ((unsigned)(rel + 128) > 256u) ? NEGBIG : S[gi][kb][i]; }
;             }
;             ls[GPB * gh + gi] += exp_step<4>(S[gi]);
;             pf[gi][0] = pack8(S[gi][0], S[gi][1]); pf[gi][1] = pack8(S[gi][2], S[gi][3]);
;         }
; #pragma unroll
;         for (int kc = 0; kc < 2; ++kc)
; #pragma unroll
;             for (int db = 0; db < 4; ++db) {
;                 const LAS unsigned char* va = vrow + ((db ^ swz) << 5) + (32 * kc) * 128;
;                 const bf16x8 vf = cat8(vtr(va), vtr(va + 16 * 128));
; #pragma unroll
;                 for (int gi = 0; gi < GPB; ++gi) O[GPB * gh + gi][db] = __builtin_amdgcn_mfma_f32_16x16x32_bf16(vf, pf[gi][kc], O[GPB * gh + gi][db], 0, 0, 0);
;             }
	v_mfma_f32_16x16x32_bf16 v[228:231], v[160:163], v[4:7], v[0:3]
	v_mfma_f32_16x16x32_bf16 v[232:235], v[168:171], v[4:7], v[0:3]
	v_mfma_f32_16x16x32_bf16 v[228:231], v[164:167], v[8:11], v[228:231]
	v_mfma_f32_16x16x32_bf16 v[232:235], v[172:175], v[8:11], v[232:235]
	ds_read_b64_tr_b16 v[176:177], v158 offset:16384
	ds_read_b64_tr_b16 v[178:179], v158 offset:18432
	ds_read_b64_tr_b16 v[180:181], v159 offset:16384
	ds_read_b64_tr_b16 v[182:183], v159 offset:18432
	ds_read_b64_tr_b16 v[184:185], v192 offset:16384
	ds_read_b64_tr_b16 v[186:187], v192 offset:18432
	ds_read_b64_tr_b16 v[188:189], v193 offset:16384
	ds_read_b64_tr_b16 v[190:191], v193 offset:18432
	v_mfma_f32_16x16x32_bf16 v[236:239], v[160:163], v[12:15], v[0:3]
	v_exp_f32_e32 v228, v228
	v_exp_f32_e32 v229, v229
	v_exp_f32_e32 v230, v230
	v_mfma_f32_16x16x32_bf16 v[104:107], v[168:171], v[12:15], v[0:3]
	v_exp_f32_e32 v231, v231
	v_exp_f32_e32 v232, v232
	v_pk_add_f32 v[242:243], v[228:229], v[230:231]
	v_mfma_f32_16x16x32_bf16 v[236:239], v[164:167], v[16:19], v[236:239]
	v_exp_f32_e32 v233, v233
	v_exp_f32_e32 v234, v234
	v_pk_add_f32 v[242:243], v[242:243], v[232:233]
	v_cvt_pk_bf16_f32 v228, v228, v229
	v_mfma_f32_16x16x32_bf16 v[104:107], v[172:175], v[16:19], v[104:107]
	v_exp_f32_e32 v235, v235
	v_cvt_pk_bf16_f32 v229, v230, v231
	v_cvt_pk_bf16_f32 v230, v232, v233
	v_cvt_pk_bf16_f32 v231, v234, v235
	v_pk_add_f32 v[242:243], v[242:243], v[234:235]
	v_add_f32_e32 v126, v126, v242
	v_add_f32_e32 v126, v126, v243
	s_waitcnt lgkmcnt(0)
	v_mfma_f32_16x16x32_bf16 v[244:247], v[160:163], v[20:23], v[0:3]
	v_exp_f32_e32 v236, v236
	v_exp_f32_e32 v237, v237
	v_mfma_f32_16x16x32_bf16 v[248:251], v[168:171], v[20:23], v[0:3]
	v_exp_f32_e32 v238, v238
	v_mfma_f32_16x16x32_bf16 v[244:247], v[164:167], v[24:27], v[244:247]
	v_exp_f32_e32 v239, v239
	v_mfma_f32_16x16x32_bf16 v[248:251], v[172:175], v[24:27], v[248:251]
	v_exp_f32_e32 v104, v104
	v_pk_add_f32 v[242:243], v[236:237], v[238:239]
	v_mfma_f32_16x16x32_bf16 v[48:51], v[176:179], v[228:231], v[48:51]
	v_exp_f32_e32 v105, v105
	v_mfma_f32_16x16x32_bf16 v[44:47], v[180:183], v[228:231], v[44:47]
	v_exp_f32_e32 v106, v106
	v_pk_add_f32 v[242:243], v[242:243], v[104:105]
	v_cvt_pk_bf16_f32 v236, v236, v237
	v_mfma_f32_16x16x32_bf16 v[40:43], v[184:187], v[228:231], v[40:43]
	v_exp_f32_e32 v107, v107
	v_cvt_pk_bf16_f32 v237, v238, v239
	v_mfma_f32_16x16x32_bf16 v[36:39], v[188:191], v[228:231], v[36:39]
	v_cvt_pk_bf16_f32 v238, v104, v105
	v_cvt_pk_bf16_f32 v239, v106, v107
	v_pk_add_f32 v[242:243], v[242:243], v[106:107]
	v_add_f32_e32 v127, v127, v242
	v_add_f32_e32 v127, v127, v243
	v_mfma_f32_16x16x32_bf16 v[228:231], v[160:163], v[28:31], v[0:3]
	v_exp_f32_e32 v244, v244
	v_exp_f32_e32 v245, v245
	v_mfma_f32_16x16x32_bf16 v[232:235], v[168:171], v[28:31], v[0:3]
	v_exp_f32_e32 v246, v246
	v_mfma_f32_16x16x32_bf16 v[228:231], v[164:167], v[32:35], v[228:231]
	v_exp_f32_e32 v247, v247
	v_mfma_f32_16x16x32_bf16 v[232:235], v[172:175], v[32:35], v[232:235]
	v_exp_f32_e32 v248, v248
	v_pk_add_f32 v[242:243], v[244:245], v[246:247]
	v_mfma_f32_16x16x32_bf16 v[64:67], v[176:179], v[236:239], v[64:67]
	v_exp_f32_e32 v249, v249
	v_mfma_f32_16x16x32_bf16 v[60:63], v[180:183], v[236:239], v[60:63]
	v_exp_f32_e32 v250, v250
	v_pk_add_f32 v[242:243], v[242:243], v[248:249]
	v_cvt_pk_bf16_f32 v244, v244, v245
	v_mfma_f32_16x16x32_bf16 v[56:59], v[184:187], v[236:239], v[56:59]
	v_exp_f32_e32 v251, v251
	v_cvt_pk_bf16_f32 v245, v246, v247
	v_mfma_f32_16x16x32_bf16 v[52:55], v[188:191], v[236:239], v[52:55]
	v_cvt_pk_bf16_f32 v246, v248, v249
	v_cvt_pk_bf16_f32 v247, v250, v251
	v_pk_add_f32 v[242:243], v[242:243], v[250:251]
	v_add_f32_e32 v124, v124, v242
	v_add_f32_e32 v124, v124, v243
	ds_read_b64_tr_b16 v[160:161], v158 offset:20480
	ds_read_b64_tr_b16 v[162:163], v158 offset:22528
	ds_read_b64_tr_b16 v[164:165], v159 offset:20480
	ds_read_b64_tr_b16 v[166:167], v159 offset:22528
	ds_read_b64_tr_b16 v[168:169], v192 offset:20480
	ds_read_b64_tr_b16 v[170:171], v192 offset:22528
	ds_read_b64_tr_b16 v[172:173], v193 offset:20480
	ds_read_b64_tr_b16 v[174:175], v193 offset:22528
	v_mfma_f32_16x16x32_bf16 v[236:239], v[128:131], v[4:7], v[0:3]
	v_exp_f32_e32 v228, v228
	v_exp_f32_e32 v229, v229
	v_mfma_f32_16x16x32_bf16 v[104:107], v[136:139], v[4:7], v[0:3]
	v_exp_f32_e32 v230, v230
	v_mfma_f32_16x16x32_bf16 v[236:239], v[132:135], v[8:11], v[236:239]
	v_exp_f32_e32 v231, v231
	v_mfma_f32_16x16x32_bf16 v[104:107], v[140:143], v[8:11], v[104:107]
	v_exp_f32_e32 v232, v232
	v_pk_add_f32 v[242:243], v[228:229], v[230:231]
	v_mfma_f32_16x16x32_bf16 v[80:83], v[176:179], v[244:247], v[80:83]
	v_exp_f32_e32 v233, v233
	v_mfma_f32_16x16x32_bf16 v[76:79], v[180:183], v[244:247], v[76:79]
	v_exp_f32_e32 v234, v234
	v_pk_add_f32 v[242:243], v[242:243], v[232:233]
	v_cvt_pk_bf16_f32 v228, v228, v229
	v_mfma_f32_16x16x32_bf16 v[72:75], v[184:187], v[244:247], v[72:75]
	v_exp_f32_e32 v235, v235
	v_cvt_pk_bf16_f32 v229, v230, v231
	v_mfma_f32_16x16x32_bf16 v[68:71], v[188:191], v[244:247], v[68:71]
	v_cvt_pk_bf16_f32 v230, v232, v233
	v_cvt_pk_bf16_f32 v231, v234, v235
	v_pk_add_f32 v[242:243], v[242:243], v[234:235]
	v_add_f32_e32 v125, v125, v242
	v_add_f32_e32 v125, v125, v243
	v_mfma_f32_16x16x32_bf16 v[244:247], v[128:131], v[12:15], v[0:3]
	v_exp_f32_e32 v236, v236
	v_exp_f32_e32 v237, v237
	v_mfma_f32_16x16x32_bf16 v[248:251], v[136:139], v[12:15], v[0:3]
	v_exp_f32_e32 v238, v238
	v_mfma_f32_16x16x32_bf16 v[244:247], v[132:135], v[16:19], v[244:247]
	v_exp_f32_e32 v239, v239
	v_mfma_f32_16x16x32_bf16 v[248:251], v[140:143], v[16:19], v[248:251]
	v_exp_f32_e32 v104, v104
	v_pk_add_f32 v[242:243], v[236:237], v[238:239]
	v_mfma_f32_16x16x32_bf16 v[84:87], v[176:179], v[228:231], v[84:87]
	v_exp_f32_e32 v105, v105
	v_mfma_f32_16x16x32_bf16 v[92:95], v[180:183], v[228:231], v[92:95]
	v_exp_f32_e32 v106, v106
	v_pk_add_f32 v[242:243], v[242:243], v[104:105]
	v_cvt_pk_bf16_f32 v236, v236, v237
	v_mfma_f32_16x16x32_bf16 v[88:91], v[184:187], v[228:231], v[88:91]
	v_exp_f32_e32 v107, v107
	v_cvt_pk_bf16_f32 v237, v238, v239
	v_mfma_f32_16x16x32_bf16 v[96:99], v[188:191], v[228:231], v[96:99]
	v_cvt_pk_bf16_f32 v238, v104, v105
	v_cvt_pk_bf16_f32 v239, v106, v107
	v_pk_add_f32 v[242:243], v[242:243], v[106:107]
	v_add_f32_e32 v126, v126, v242
	v_add_f32_e32 v126, v126, v243
	s_waitcnt lgkmcnt(0)
; #define LAS __attribute__((address_space(3)))
; __device__ __forceinline__ s16x4 vtr(const LAS unsigned char* p) { return __builtin_bit_cast(s16x4, __builtin_amdgcn_ds_read_tr16_b64_v4i16((LAS v4i16_t*)p)); }
;     ...
;     for (int gh = 0; gh < 4 / GPB; ++gh) {
;         f32x4 S[GPB][4];
; #pragma unroll
;         for (int kb = 0; kb < 4; ++kb) {
;             const bf16x8 kf0 = *(const LAS bf16x8*)(kb0 + (16 * kb) * 128 + kx0), kf1 = *(const LAS bf16x8*)(kb0 + (16 * kb) * 128 + kx1);
; #pragma unroll
;             for (int gi = 0; gi < GPB; ++gi) { S[gi][kb] = __builtin_amdgcn_mfma_f32_16x16x32_bf16(kf0, qf[GPB * gh + gi][0], cinit, 0, 0, 0);
;                 S[gi][kb] = __builtin_amdgcn_mfma_f32_16x16x32_bf16(kf1, qf[GPB * gh + gi][1], S[gi][kb], 0, 0, 0); } }
;         bf16x8 pf[GPB][2];
; #pragma unroll
;         for (int gi = 0; gi < GPB; ++gi) {
;             if (MASK) {
; #pragma unroll
;                 for (int kb = 0; kb < 4; ++kb)
; #pragma unroll
;                     for (int i = 0; i < 4; ++i) { const int rel = rel0 + 16 * kb + 4 * g + i; S[gi][kb][i] = ((unsigned)(rel + 128) > 256u) ? NEGBIG : S[gi][kb][i]; }
;             }
;             ls[GPB * gh + gi] += exp_step<4>(S[gi]);
;             pf[gi][0] = pack8(S[gi][0], S[gi][1]); pf[gi][1] = pack8(S[gi][2], S[gi][3]);
;         }
; #pragma unroll
;         for (int kc = 0; kc < 2; ++kc)
; #pragma unroll
;             for (int db = 0; db < 4; ++db) {
;                 const LAS unsigned char* va = vrow + ((db ^ swz) << 5) + (32 * kc) * 128;
;                 const bf16x8 vf = cat8(vtr(va), vtr(va + 16 * 128));
; #pragma unroll
;                 for (int gi = 0; gi < GPB; ++gi) O[GPB * gh + gi][db] = __builtin_amdgcn_mfma_f32_16x16x32_bf16(vf, pf[gi][kc], O[GPB * gh + gi][db], 0, 0, 0);
;             }
; __device__ __forceinline__ void na_phase(LAS unsigned char* lds, const bf16_t* Q, const bf16_t* K, const bf16_t* V, bf16_t* Ob, const float* rpb, float negb) {
;     ...
;         for (int t = 0; t < 4; ++t) {
;             dma_tile<2>(lds + ((t + 3) & 3) * NA_BUF, K, V, NA_ROW0(t + 3), DM, dl, w);
;             const LAS unsigned char* buf = lds + (t & 3) * NA_BUF;
;             full_tile<0, 1, 2>(O, ls, qf, negb, buf + hh * 8192, buf + 2 * 8192 + hh * 8192, lane, 0);
;             ring_wait<4>();
	v_mfma_f32_16x16x32_bf16 v[228:231], v[128:131], v[20:23], v[0:3]
	v_exp_f32_e32 v244, v244
	v_exp_f32_e32 v245, v245
	v_mfma_f32_16x16x32_bf16 v[232:235], v[136:139], v[20:23], v[0:3]
	v_exp_f32_e32 v246, v246
	v_mfma_f32_16x16x32_bf16 v[228:231], v[132:135], v[24:27], v[228:231]
	v_exp_f32_e32 v247, v247
	v_mfma_f32_16x16x32_bf16 v[232:235], v[140:143], v[24:27], v[232:235]
	v_exp_f32_e32 v248, v248
	v_pk_add_f32 v[242:243], v[244:245], v[246:247]
	v_mfma_f32_16x16x32_bf16 v[48:51], v[160:163], v[236:239], v[48:51]
	v_exp_f32_e32 v249, v249
	v_mfma_f32_16x16x32_bf16 v[44:47], v[164:167], v[236:239], v[44:47]
	v_exp_f32_e32 v250, v250
	v_pk_add_f32 v[242:243], v[242:243], v[248:249]
	v_cvt_pk_bf16_f32 v244, v244, v245
	v_mfma_f32_16x16x32_bf16 v[40:43], v[168:171], v[236:239], v[40:43]
	v_exp_f32_e32 v251, v251
	v_cvt_pk_bf16_f32 v245, v246, v247
	v_mfma_f32_16x16x32_bf16 v[36:39], v[172:175], v[236:239], v[36:39]
	v_cvt_pk_bf16_f32 v246, v248, v249
	v_cvt_pk_bf16_f32 v247, v250, v251
	v_pk_add_f32 v[242:243], v[242:243], v[250:251]
	v_add_f32_e32 v127, v127, v242
	v_add_f32_e32 v127, v127, v243
	v_mfma_f32_16x16x32_bf16 v[236:239], v[128:131], v[28:31], v[0:3]
	v_exp_f32_e32 v228, v228
	v_exp_f32_e32 v229, v229
	v_mfma_f32_16x16x32_bf16 v[104:107], v[136:139], v[28:31], v[0:3]
	v_exp_f32_e32 v230, v230
	v_mfma_f32_16x16x32_bf16 v[236:239], v[132:135], v[32:35], v[236:239]
	v_exp_f32_e32 v231, v231
	v_mfma_f32_16x16x32_bf16 v[104:107], v[140:143], v[32:35], v[104:107]
	v_exp_f32_e32 v232, v232
	v_pk_add_f32 v[242:243], v[228:229], v[230:231]
	v_mfma_f32_16x16x32_bf16 v[64:67], v[160:163], v[244:247], v[64:67]
	v_exp_f32_e32 v233, v233
	v_mfma_f32_16x16x32_bf16 v[60:63], v[164:167], v[244:247], v[60:63]
	v_exp_f32_e32 v234, v234
	v_pk_add_f32 v[242:243], v[242:243], v[232:233]
	v_cvt_pk_bf16_f32 v228, v228, v229
	v_mfma_f32_16x16x32_bf16 v[56:59], v[168:171], v[244:247], v[56:59]
	v_exp_f32_e32 v235, v235
	v_cvt_pk_bf16_f32 v229, v230, v231
	v_mfma_f32_16x16x32_bf16 v[52:55], v[172:175], v[244:247], v[52:55]
	v_cvt_pk_bf16_f32 v230, v232, v233
	v_cvt_pk_bf16_f32 v231, v234, v235
	v_pk_add_f32 v[242:243], v[242:243], v[234:235]
	v_add_f32_e32 v124, v124, v242
	v_add_f32_e32 v124, v124, v243
	v_mfma_f32_16x16x32_bf16 v[80:83], v[160:163], v[228:231], v[80:83]
	v_exp_f32_e32 v236, v236
	v_exp_f32_e32 v237, v237
	v_exp_f32_e32 v238, v238
	v_mfma_f32_16x16x32_bf16 v[76:79], v[164:167], v[228:231], v[76:79]
	v_exp_f32_e32 v239, v239
	v_exp_f32_e32 v104, v104
	v_pk_add_f32 v[242:243], v[236:237], v[238:239]
	v_mfma_f32_16x16x32_bf16 v[72:75], v[168:171], v[228:231], v[72:75]
	v_exp_f32_e32 v105, v105
	v_exp_f32_e32 v106, v106
	v_pk_add_f32 v[242:243], v[242:243], v[104:105]
	v_cvt_pk_bf16_f32 v236, v236, v237
	v_mfma_f32_16x16x32_bf16 v[68:71], v[172:175], v[228:231], v[68:71]
	v_exp_f32_e32 v107, v107
	v_cvt_pk_bf16_f32 v237, v238, v239
	v_cvt_pk_bf16_f32 v238, v104, v105
	v_cvt_pk_bf16_f32 v239, v106, v107
	v_pk_add_f32 v[242:243], v[242:243], v[106:107]
	v_add_f32_e32 v125, v125, v242
	v_add_f32_e32 v125, v125, v243
	v_mfma_f32_16x16x32_bf16 v[84:87], v[160:163], v[236:239], v[84:87]
	v_mfma_f32_16x16x32_bf16 v[92:95], v[164:167], v[236:239], v[92:95]
	v_mfma_f32_16x16x32_bf16 v[88:91], v[168:171], v[236:239], v[88:91]
	v_mfma_f32_16x16x32_bf16 v[96:99], v[172:175], v[236:239], v[96:99]
	s_add_i32 vcc_lo, vcc_lo, 0x8000
	s_add_u32 s94, s94, 64
	s_addc_u32 s95, s95, 0
	s_add_i32 s96, s96, 1
	s_waitcnt vmcnt(8)
	s_barrier
	s_cmp_lt_i32 s96, s93
	s_cselect_b32 s7, s95, 0
	s_cselect_b32 s6, s94, s82
	s_lshl_b64 s[6:7], s[6:7], 11
	s_add_u32 s76, s67, s6
	s_addc_u32 s77, s4, s7
	s_add_u32 s6, s5, s6
	s_addc_u32 s7, s58, s7
	s_add_i32 s59, s69, vcc_lo
	s_mov_b32 vcc_hi, m0
	s_mov_b32 m0, s59
	s_nop 0
	global_load_lds_dwordx4 v221, s[76:77]
	s_mov_b32 m0, vcc_hi
	s_add_i32 s66, s59, 0x4000
	s_mov_b32 vcc_hi, m0
	s_mov_b32 m0, s66
	s_nop 0
	global_load_lds_dwordx4 v222, s[6:7]
	s_mov_b32 m0, vcc_hi
	s_add_i32 s66, s59, 0x2000
	s_mov_b32 vcc_hi, m0
	s_mov_b32 m0, s66
	s_nop 0
	global_load_lds_dwordx4 v223, s[76:77]
	s_mov_b32 m0, vcc_hi
	s_addk_i32 s59, 0x6000
	s_mov_b32 s66, m0
	s_mov_b32 m0, s59
	s_nop 0
	global_load_lds_dwordx4 v224, s[6:7]
	s_mov_b32 m0, s66
	s_add_i32 s76, s65, vcc_lo
	s_add_i32 s76, s76, 0x8000
	v_add_u32_e32 v144, s76, v111
	v_add3_u32 v193, s76, v210, v205
	v_add_u32_e32 v145, v144, v204
	v_add_u32_e32 v144, v144, v203
	ds_read_b128 v[160:163], v144
	ds_read_b128 v[164:167], v145
	ds_read_b128 v[168:171], v144 offset:2048
	ds_read_b128 v[172:175], v145 offset:2048
	ds_read_b128 v[128:131], v144 offset:4096
	ds_read_b128 v[132:135], v145 offset:4096
	ds_read_b128 v[136:139], v144 offset:6144
	ds_read_b128 v[140:143], v145 offset:6144
	v_add_u32_e32 v158, v193, v206
	v_add_u32_e32 v159, v193, v207
	v_add_u32_e32 v192, v193, v208
	v_add_u32_e32 v193, v193, v209
	s_waitcnt lgkmcnt(4)
; #define LAS __attribute__((address_space(3)))
; __device__ __forceinline__ s16x4 vtr(const LAS unsigned char* p) { return __builtin_bit_cast(s16x4, __builtin_amdgcn_ds_read_tr16_b64_v4i16((LAS v4i16_t*)p)); }
; __device__ __forceinline__ bf16x8 cat8(s16x4 a, s16x4 b) { return (bf16x8){a[0], a[1], a[2], a[3], b[0], b[1], b[2], b[3]}; }
; __device__ __forceinline__ bf16x8 pack8(const f32x4& a, const f32x4& b) { u32x4 w; w.x = pkbf(a[0], a[1]); w.y = pkbf(a[2], a[3]); w.z = pkbf(b[0], b[1]); w.w = pkbf(b[2], b[3]); return __builtin_bit_cast(bf16x8, w); }
;     ...
;     for (int gh = 0; gh < 4 / GPB; ++gh) {
;         f32x4 S[GPB][4];
; #pragma unroll
;         for (int kb = 0; kb < 4; ++kb) {
;             const bf16x8 kf0 = *(const LAS bf16x8*)(kb0 + (16 * kb) * 128 + kx0), kf1 = *(const LAS bf16x8*)(kb0 + (16 * kb) * 128 + kx1);
; #pragma unroll
;             for (int gi = 0; gi < GPB; ++gi) { S[gi][kb] = __builtin_amdgcn_mfma_f32_16x16x32_bf16(kf0, qf[GPB * gh + gi][0], cinit, 0, 0, 0);
;                 S[gi][kb] = __builtin_amdgcn_mfma_f32_16x16x32_bf16(kf1, qf[GPB * gh + gi][1], S[gi][kb], 0, 0, 0); } }
;         bf16x8 pf[GPB][2];
; #pragma unroll
;         for (int gi = 0; gi < GPB; ++gi) {
;             if (MASK) {
; #pragma unroll
;                 for (int kb = 0; kb < 4; ++kb)
; #pragma unroll
;                     for (int i = 0; i < 4; ++i) { const int rel = rel0 + 16 * kb + 4 * g + i; S[gi][kb][i] = ((unsigned)(rel + 128) > 256u) ? NEGBIG : S[gi][kb][i]; }
;             }
;             ls[GPB * gh + gi] += exp_step<4>(S[gi]);
;             pf[gi][0] = pack8(S[gi][0], S[gi][1]); pf[gi][1] = pack8(S[gi][2], S[gi][3]);
;         }
; #pragma unroll
;         for (int kc = 0; kc < 2; ++kc)
; #pragma unroll
;             for (int db = 0; db < 4; ++db) {
;                 const LAS unsigned char* va = vrow + ((db ^ swz) << 5) + (32 * kc) * 128;
;                 const bf16x8 vf = cat8(vtr(va), vtr(va + 16 * 128));
; #pragma unroll
;                 for (int gi = 0; gi < GPB; ++gi) O[GPB * gh + gi][db] = __builtin_amdgcn_mfma_f32_16x16x32_bf16(vf, pf[gi][kc], O[GPB * gh + gi][db], 0, 0, 0);
;             }
	v_mfma_f32_16x16x32_bf16 v[228:231], v[160:163], v[4:7], v[0:3]
	v_mfma_f32_16x16x32_bf16 v[232:235], v[168:171], v[4:7], v[0:3]
	v_mfma_f32_16x16x32_bf16 v[228:231], v[164:167], v[8:11], v[228:231]
	v_mfma_f32_16x16x32_bf16 v[232:235], v[172:175], v[8:11], v[232:235]
	ds_read_b64_tr_b16 v[176:177], v158 offset:16384
	ds_read_b64_tr_b16 v[178:179], v158 offset:18432
	ds_read_b64_tr_b16 v[180:181], v159 offset:16384
	ds_read_b64_tr_b16 v[182:183], v159 offset:18432
	ds_read_b64_tr_b16 v[184:185], v192 offset:16384
	ds_read_b64_tr_b16 v[186:187], v192 offset:18432
	ds_read_b64_tr_b16 v[188:189], v193 offset:16384
	ds_read_b64_tr_b16 v[190:191], v193 offset:18432
	v_mfma_f32_16x16x32_bf16 v[236:239], v[160:163], v[12:15], v[0:3]
	v_exp_f32_e32 v228, v228
	v_exp_f32_e32 v229, v229
	v_exp_f32_e32 v230, v230
	v_mfma_f32_16x16x32_bf16 v[104:107], v[168:171], v[12:15], v[0:3]
	v_exp_f32_e32 v231, v231
	v_exp_f32_e32 v232, v232
	v_pk_add_f32 v[242:243], v[228:229], v[230:231]
	v_mfma_f32_16x16x32_bf16 v[236:239], v[164:167], v[16:19], v[236:239]
	v_exp_f32_e32 v233, v233
	v_exp_f32_e32 v234, v234
	v_pk_add_f32 v[242:243], v[242:243], v[232:233]
	v_cvt_pk_bf16_f32 v228, v228, v229
	v_mfma_f32_16x16x32_bf16 v[104:107], v[172:175], v[16:19], v[104:107]
	v_exp_f32_e32 v235, v235
	v_cvt_pk_bf16_f32 v229, v230, v231
	v_cvt_pk_bf16_f32 v230, v232, v233
	v_cvt_pk_bf16_f32 v231, v234, v235
	v_pk_add_f32 v[242:243], v[242:243], v[234:235]
	v_add_f32_e32 v126, v126, v242
	v_add_f32_e32 v126, v126, v243
	s_waitcnt lgkmcnt(0)
	v_mfma_f32_16x16x32_bf16 v[244:247], v[160:163], v[20:23], v[0:3]
	v_exp_f32_e32 v236, v236
	v_exp_f32_e32 v237, v237
	v_mfma_f32_16x16x32_bf16 v[248:251], v[168:171], v[20:23], v[0:3]
	v_exp_f32_e32 v238, v238
	v_mfma_f32_16x16x32_bf16 v[244:247], v[164:167], v[24:27], v[244:247]
	v_exp_f32_e32 v239, v239
	v_mfma_f32_16x16x32_bf16 v[248:251], v[172:175], v[24:27], v[248:251]
	v_exp_f32_e32 v104, v104
	v_pk_add_f32 v[242:243], v[236:237], v[238:239]
	v_mfma_f32_16x16x32_bf16 v[48:51], v[176:179], v[228:231], v[48:51]
	v_exp_f32_e32 v105, v105
	v_mfma_f32_16x16x32_bf16 v[44:47], v[180:183], v[228:231], v[44:47]
	v_exp_f32_e32 v106, v106
	v_pk_add_f32 v[242:243], v[242:243], v[104:105]
	v_cvt_pk_bf16_f32 v236, v236, v237
	v_mfma_f32_16x16x32_bf16 v[40:43], v[184:187], v[228:231], v[40:43]
	v_exp_f32_e32 v107, v107
	v_cvt_pk_bf16_f32 v237, v238, v239
	v_mfma_f32_16x16x32_bf16 v[36:39], v[188:191], v[228:231], v[36:39]
	v_cvt_pk_bf16_f32 v238, v104, v105
	v_cvt_pk_bf16_f32 v239, v106, v107
	v_pk_add_f32 v[242:243], v[242:243], v[106:107]
	v_add_f32_e32 v127, v127, v242
	v_add_f32_e32 v127, v127, v243
	v_mfma_f32_16x16x32_bf16 v[228:231], v[160:163], v[28:31], v[0:3]
	v_exp_f32_e32 v244, v244
	v_exp_f32_e32 v245, v245
	v_mfma_f32_16x16x32_bf16 v[232:235], v[168:171], v[28:31], v[0:3]
	v_exp_f32_e32 v246, v246
	v_mfma_f32_16x16x32_bf16 v[228:231], v[164:167], v[32:35], v[228:231]
	v_exp_f32_e32 v247, v247
	v_mfma_f32_16x16x32_bf16 v[232:235], v[172:175], v[32:35], v[232:235]
	v_exp_f32_e32 v248, v248
	v_pk_add_f32 v[242:243], v[244:245], v[246:247]
	v_mfma_f32_16x16x32_bf16 v[64:67], v[176:179], v[236:239], v[64:67]
	v_exp_f32_e32 v249, v249
	v_mfma_f32_16x16x32_bf16 v[60:63], v[180:183], v[236:239], v[60:63]
	v_exp_f32_e32 v250, v250
	v_pk_add_f32 v[242:243], v[242:243], v[248:249]
	v_cvt_pk_bf16_f32 v244, v244, v245
	v_mfma_f32_16x16x32_bf16 v[56:59], v[184:187], v[236:239], v[56:59]
	v_exp_f32_e32 v251, v251
	v_cvt_pk_bf16_f32 v245, v246, v247
	v_mfma_f32_16x16x32_bf16 v[52:55], v[188:191], v[236:239], v[52:55]
	v_cvt_pk_bf16_f32 v246, v248, v249
	v_cvt_pk_bf16_f32 v247, v250, v251
	v_pk_add_f32 v[242:243], v[242:243], v[250:251]
	v_add_f32_e32 v124, v124, v242
	v_add_f32_e32 v124, v124, v243
	ds_read_b64_tr_b16 v[160:161], v158 offset:20480
	ds_read_b64_tr_b16 v[162:163], v158 offset:22528
	ds_read_b64_tr_b16 v[164:165], v159 offset:20480
	ds_read_b64_tr_b16 v[166:167], v159 offset:22528
	ds_read_b64_tr_b16 v[168:169], v192 offset:20480
	ds_read_b64_tr_b16 v[170:171], v192 offset:22528
	ds_read_b64_tr_b16 v[172:173], v193 offset:20480
	ds_read_b64_tr_b16 v[174:175], v193 offset:22528
	v_mfma_f32_16x16x32_bf16 v[236:239], v[128:131], v[4:7], v[0:3]
	v_exp_f32_e32 v228, v228
	v_exp_f32_e32 v229, v229
	v_mfma_f32_16x16x32_bf16 v[104:107], v[136:139], v[4:7], v[0:3]
	v_exp_f32_e32 v230, v230
	v_mfma_f32_16x16x32_bf16 v[236:239], v[132:135], v[8:11], v[236:239]
	v_exp_f32_e32 v231, v231
	v_mfma_f32_16x16x32_bf16 v[104:107], v[140:143], v[8:11], v[104:107]
	v_exp_f32_e32 v232, v232
	v_pk_add_f32 v[242:243], v[228:229], v[230:231]
	v_mfma_f32_16x16x32_bf16 v[80:83], v[176:179], v[244:247], v[80:83]
	v_exp_f32_e32 v233, v233
	v_mfma_f32_16x16x32_bf16 v[76:79], v[180:183], v[244:247], v[76:79]
	v_exp_f32_e32 v234, v234
	v_pk_add_f32 v[242:243], v[242:243], v[232:233]
	v_cvt_pk_bf16_f32 v228, v228, v229
	v_mfma_f32_16x16x32_bf16 v[72:75], v[184:187], v[244:247], v[72:75]
	v_exp_f32_e32 v235, v235
	v_cvt_pk_bf16_f32 v229, v230, v231
	v_mfma_f32_16x16x32_bf16 v[68:71], v[188:191], v[244:247], v[68:71]
	v_cvt_pk_bf16_f32 v230, v232, v233
	v_cvt_pk_bf16_f32 v231, v234, v235
	v_pk_add_f32 v[242:243], v[242:243], v[234:235]
	v_add_f32_e32 v125, v125, v242
	v_add_f32_e32 v125, v125, v243
	v_mfma_f32_16x16x32_bf16 v[244:247], v[128:131], v[12:15], v[0:3]
	v_exp_f32_e32 v236, v236
	v_exp_f32_e32 v237, v237
	v_mfma_f32_16x16x32_bf16 v[248:251], v[136:139], v[12:15], v[0:3]
	v_exp_f32_e32 v238, v238
	v_mfma_f32_16x16x32_bf16 v[244:247], v[132:135], v[16:19], v[244:247]
	v_exp_f32_e32 v239, v239
	v_mfma_f32_16x16x32_bf16 v[248:251], v[140:143], v[16:19], v[248:251]
	v_exp_f32_e32 v104, v104
	v_pk_add_f32 v[242:243], v[236:237], v[238:239]
	v_mfma_f32_16x16x32_bf16 v[84:87], v[176:179], v[228:231], v[84:87]
	v_exp_f32_e32 v105, v105
	v_mfma_f32_16x16x32_bf16 v[92:95], v[180:183], v[228:231], v[92:95]
	v_exp_f32_e32 v106, v106
	v_pk_add_f32 v[242:243], v[242:243], v[104:105]
	v_cvt_pk_bf16_f32 v236, v236, v237
	v_mfma_f32_16x16x32_bf16 v[88:91], v[184:187], v[228:231], v[88:91]
	v_exp_f32_e32 v107, v107
	v_cvt_pk_bf16_f32 v237, v238, v239
	v_mfma_f32_16x16x32_bf16 v[96:99], v[188:191], v[228:231], v[96:99]
	v_cvt_pk_bf16_f32 v238, v104, v105
	v_cvt_pk_bf16_f32 v239, v106, v107
	v_pk_add_f32 v[242:243], v[242:243], v[106:107]
	v_add_f32_e32 v126, v126, v242
	v_add_f32_e32 v126, v126, v243
	s_waitcnt lgkmcnt(0)
; #define LAS __attribute__((address_space(3)))
; __device__ __forceinline__ s16x4 vtr(const LAS unsigned char* p) { return __builtin_bit_cast(s16x4, __builtin_amdgcn_ds_read_tr16_b64_v4i16((LAS v4i16_t*)p)); }
;     ...
;     for (int gh = 0; gh < 4 / GPB; ++gh) {
;         f32x4 S[GPB][4];
; #pragma unroll
;         for (int kb = 0; kb < 4; ++kb) {
;             const bf16x8 kf0 = *(const LAS bf16x8*)(kb0 + (16 * kb) * 128 + kx0), kf1 = *(const LAS bf16x8*)(kb0 + (16 * kb) * 128 + kx1);
; #pragma unroll
;             for (int gi = 0; gi < GPB; ++gi) { S[gi][kb] = __builtin_amdgcn_mfma_f32_16x16x32_bf16(kf0, qf[GPB * gh + gi][0], cinit, 0, 0, 0);
;                 S[gi][kb] = __builtin_amdgcn_mfma_f32_16x16x32_bf16(kf1, qf[GPB * gh + gi][1], S[gi][kb], 0, 0, 0); } }
;         bf16x8 pf[GPB][2];
; #pragma unroll
;         for (int gi = 0; gi < GPB; ++gi) {
;             if (MASK) {
; #pragma unroll
;                 for (int kb = 0; kb < 4; ++kb)
; #pragma unroll
;                     for (int i = 0; i < 4; ++i) { const int rel = rel0 + 16 * kb + 4 * g + i; S[gi][kb][i] = ((unsigned)(rel + 128) > 256u) ? NEGBIG : S[gi][kb][i]; }
;             }
;             ls[GPB * gh + gi] += exp_step<4>(S[gi]);
;             pf[gi][0] = pack8(S[gi][0], S[gi][1]); pf[gi][1] = pack8(S[gi][2], S[gi][3]);
;         }
; #pragma unroll
;         for (int kc = 0; kc < 2; ++kc)
; #pragma unroll
;             for (int db = 0; db < 4; ++db) {
;                 const LAS unsigned char* va = vrow + ((db ^ swz) << 5) + (32 * kc) * 128;
;                 const bf16x8 vf = cat8(vtr(va), vtr(va + 16 * 128));
; #pragma unroll
;                 for (int gi = 0; gi < GPB; ++gi) O[GPB * gh + gi][db] = __builtin_amdgcn_mfma_f32_16x16x32_bf16(vf, pf[gi][kc], O[GPB * gh + gi][db], 0, 0, 0);
;             }
; __device__ __forceinline__ void na_phase(LAS unsigned char* lds, const bf16_t* Q, const bf16_t* K, const bf16_t* V, bf16_t* Ob, const float* rpb, float negb) {
;     ...
;         for (int t = 4; t < NT; ++t) {
;             dma_tile<2>(lds + ((t + 3) & 3) * NA_BUF, K, V, NA_ROW0(t + 3), DM, dl, w);
;             const LAS unsigned char* buf = lds + (t & 3) * NA_BUF;
;             const int kr = kr_lo + t - 4; const bool rv = kr >= r0w && kr < r0w + 8;
;             if (rv) na_local_tile(O, ls, qf, negb, buf + hh * 8192, buf + 2 * 8192 + hh * 8192, lane, tab + hh * 512 + (kr - r + 7) * 31, true);
	v_mfma_f32_16x16x32_bf16 v[228:231], v[128:131], v[20:23], v[0:3]
	v_exp_f32_e32 v244, v244
	v_exp_f32_e32 v245, v245
	v_mfma_f32_16x16x32_bf16 v[232:235], v[136:139], v[20:23], v[0:3]
	v_exp_f32_e32 v246, v246
	v_mfma_f32_16x16x32_bf16 v[228:231], v[132:135], v[24:27], v[228:231]
	v_exp_f32_e32 v247, v247
	v_mfma_f32_16x16x32_bf16 v[232:235], v[140:143], v[24:27], v[232:235]
	v_exp_f32_e32 v248, v248
	v_pk_add_f32 v[242:243], v[244:245], v[246:247]
	v_mfma_f32_16x16x32_bf16 v[48:51], v[160:163], v[236:239], v[48:51]
	v_exp_f32_e32 v249, v249
	v_mfma_f32_16x16x32_bf16 v[44:47], v[164:167], v[236:239], v[44:47]
	v_exp_f32_e32 v250, v250
	v_pk_add_f32 v[242:243], v[242:243], v[248:249]
	v_cvt_pk_bf16_f32 v244, v244, v245
	v_mfma_f32_16x16x32_bf16 v[40:43], v[168:171], v[236:239], v[40:43]
	v_exp_f32_e32 v251, v251
	v_cvt_pk_bf16_f32 v245, v246, v247
	v_mfma_f32_16x16x32_bf16 v[36:39], v[172:175], v[236:239], v[36:39]
	v_cvt_pk_bf16_f32 v246, v248, v249
	v_cvt_pk_bf16_f32 v247, v250, v251
	v_pk_add_f32 v[242:243], v[242:243], v[250:251]
	v_add_f32_e32 v127, v127, v242
	v_add_f32_e32 v127, v127, v243
	v_mfma_f32_16x16x32_bf16 v[236:239], v[128:131], v[28:31], v[0:3]
	v_exp_f32_e32 v228, v228
	v_exp_f32_e32 v229, v229
	v_mfma_f32_16x16x32_bf16 v[104:107], v[136:139], v[28:31], v[0:3]
	v_exp_f32_e32 v230, v230
	v_mfma_f32_16x16x32_bf16 v[236:239], v[132:135], v[32:35], v[236:239]
	v_exp_f32_e32 v231, v231
	v_mfma_f32_16x16x32_bf16 v[104:107], v[140:143], v[32:35], v[104:107]
	v_exp_f32_e32 v232, v232
	v_pk_add_f32 v[242:243], v[228:229], v[230:231]
	v_mfma_f32_16x16x32_bf16 v[64:67], v[160:163], v[244:247], v[64:67]
	v_exp_f32_e32 v233, v233
	v_mfma_f32_16x16x32_bf16 v[60:63], v[164:167], v[244:247], v[60:63]
	v_exp_f32_e32 v234, v234
	v_pk_add_f32 v[242:243], v[242:243], v[232:233]
	v_cvt_pk_bf16_f32 v228, v228, v229
	v_mfma_f32_16x16x32_bf16 v[56:59], v[168:171], v[244:247], v[56:59]
	v_exp_f32_e32 v235, v235
	v_cvt_pk_bf16_f32 v229, v230, v231
	v_mfma_f32_16x16x32_bf16 v[52:55], v[172:175], v[244:247], v[52:55]
	v_cvt_pk_bf16_f32 v230, v232, v233
	v_cvt_pk_bf16_f32 v231, v234, v235
	v_pk_add_f32 v[242:243], v[242:243], v[234:235]
	v_add_f32_e32 v124, v124, v242
	v_add_f32_e32 v124, v124, v243
	v_mfma_f32_16x16x32_bf16 v[80:83], v[160:163], v[228:231], v[80:83]
	v_exp_f32_e32 v236, v236
	v_exp_f32_e32 v237, v237
	v_exp_f32_e32 v238, v238
	v_mfma_f32_16x16x32_bf16 v[76:79], v[164:167], v[228:231], v[76:79]
	v_exp_f32_e32 v239, v239
	v_exp_f32_e32 v104, v104
	v_pk_add_f32 v[242:243], v[236:237], v[238:239]
	v_mfma_f32_16x16x32_bf16 v[72:75], v[168:171], v[228:231], v[72:75]
	v_exp_f32_e32 v105, v105
	v_exp_f32_e32 v106, v106
	v_pk_add_f32 v[242:243], v[242:243], v[104:105]
	v_cvt_pk_bf16_f32 v236, v236, v237
	v_mfma_f32_16x16x32_bf16 v[68:71], v[172:175], v[228:231], v[68:71]
	v_exp_f32_e32 v107, v107
	v_cvt_pk_bf16_f32 v237, v238, v239
	v_cvt_pk_bf16_f32 v238, v104, v105
	v_cvt_pk_bf16_f32 v239, v106, v107
	v_pk_add_f32 v[242:243], v[242:243], v[106:107]
	v_add_f32_e32 v125, v125, v242
	v_add_f32_e32 v125, v125, v243
	v_mfma_f32_16x16x32_bf16 v[84:87], v[160:163], v[236:239], v[84:87]
	v_mfma_f32_16x16x32_bf16 v[92:95], v[164:167], v[236:239], v[92:95]
	v_mfma_f32_16x16x32_bf16 v[88:91], v[168:171], v[236:239], v[88:91]
	v_mfma_f32_16x16x32_bf16 v[96:99], v[172:175], v[236:239], v[96:99]
	s_add_i32 vcc_lo, vcc_lo, 0x8000
	s_add_u32 s94, s94, 64
	s_addc_u32 s95, s95, 0
	s_add_i32 s96, s96, 1
	s_waitcnt vmcnt(8)
	s_barrier
	s_cmp_lt_i32 s93, 5
	s_cbranch_scc1 .LBB0_361
	s_add_i32 s97, s97, -4
	s_min_u32 s94, s97, 0x78
	s_add_i32 s95, s94, 8
	s_add_i32 s96, s93, -4
	s_cmp_gt_u32 s68, 4
	s_cselect_b32 s7, 0, 0
	s_cselect_b32 s6, s68, 4
	s_lshl_b64 s[6:7], s[6:7], 6
	s_add_u32 s6, s6, s61
	s_addc_u32 s7, s7, 0
	s_add_u32 s59, s6, 0xffffffc0
	s_addc_u32 s66, s7, -1
	s_add_i32 s7, s2, s68
	s_mul_i32 s6, s60, 0x7c
	s_mulk_i32 s7, 0x7c
	s_sub_i32 s6, s6, s7
	s_mov_b32 s97, 0
	v_add_u32_e32 v128, s6, v219
	s_add_i32 s68, s60, -4
	v_add_u32_e32 v129, s6, v220
	s_mov_b32 s6, 0x20000
	s_branch .LBB0_383

; #define LAS __attribute__((address_space(3)))
; __device__ __forceinline__ void na_local_tile(f32x4 (&O)[4][4], float (&ls)[4], const bf16x8 (&qf)[4][2], float negb,
;                                               const LAS unsigned char* Kt, const LAS unsigned char* Vt, int lane, const LAS float* bias_row, bool rowvalid) {
;     const int l15 = lane & 15, g = lane >> 4, q4 = l15 >> 2;
;     const LAS unsigned char* kb0 = Kt + l15 * 128;
;     const int kx0 = ((g) ^ (l15 & 7)) << 4, kx1 = ((4 + g) ^ (l15 & 7)) << 4;
;     const LAS unsigned char* vrow = Vt + (4 * g + q4) * 128 + (lane & 3) * 8;
;     const int swz = (2 * (g & 1) + (q4 >> 1)) & 3;
; #pragma unroll
;     for (int grp = 0; grp < 4; ++grp) {
;         const int kwin = grp == 0 ? 0 : (grp == 1 ? 8 : (grp == 2 ? 24 : 32));
;         f32x4 S[2];
; #pragma unroll
;         for (int k2 = 0; k2 < 2; ++k2) {
;             const bf16x8 kf0 = *(const LAS bf16x8*)(kb0 + (kwin + 16 * k2) * 128 + kx0), kf1 = *(const LAS bf16x8*)(kb0 + (kwin + 16 * k2) * 128 + kx1);
;             S[k2] = __builtin_amdgcn_mfma_f32_16x16x32_bf16(kf0, qf[grp][0], (f32x4){negb, negb, negb, negb}, 0, 0, 0);
;             S[k2] = __builtin_amdgcn_mfma_f32_16x16x32_bf16(kf1, qf[grp][1], S[k2], 0, 0, 0); }
;         const int c = 16 * grp + l15; const int c0 = rowvalid ? min(max(c - 8, 0), 48) : 4096;
;         const LAS float* bl = bias_row + (15 - c + 4 * g);
; #pragma unroll
;         for (int k2 = 0; k2 < 2; ++k2)
; #pragma unroll
;             for (int i = 0; i < 4; ++i) { const int kc = kwin + 16 * k2 + 4 * g + i; const float bias = bl[kwin + 16 * k2 + i];
;                 S[k2][i] = ((unsigned)(kc - c0) < 16u) ? S[k2][i] + bias : NEGBIG; }
;         ls[grp] += exp_step<2>(S);
;         const bf16x8 pf = pack8(S[0], S[1]);
; #pragma unroll
;         for (int db = 0; db < 4; ++db) {
;             const LAS unsigned char* va = vrow + ((db ^ swz) << 5) + kwin * 128;
;             const bf16x8 vf = cat8(vtr(va), vtr(va + 16 * 128));
;             O[grp][db] = __builtin_amdgcn_mfma_f32_16x16x32_bf16(vf, pf, O[grp][db], 0, 0, 0);
;         }
;         __builtin_amdgcn_sched_barrier(0x108);
; __device__ __forceinline__ void na_phase(LAS unsigned char* lds, const bf16_t* Q, const bf16_t* K, const bf16_t* V, bf16_t* Ob, const float* rpb, float negb) {
;     ...
;         for (int t = 4; t < NT; ++t) {
.LBB0_383:
	s_add_i32 s60, s6, 0x18000
	s_and_b32 s60, s60, 0x18000
	s_add_i32 s7, s97, 7
	s_add_i32 vcc_lo, s60, 0
	s_cmp_lt_i32 s7, s93
	s_cselect_b32 s61, s66, 0
	s_cselect_b32 s60, s59, s82
	s_lshl_b64 s[60:61], s[60:61], 11
	s_add_u32 s76, s67, s60
	s_addc_u32 s77, s4, s61
	s_add_u32 s60, s5, s60
	s_addc_u32 s61, s58, s61
	s_add_i32 s7, s63, vcc_lo
	s_add_i32 vcc_lo, s7, 0x4000
	s_mov_b32 vcc_hi, m0
	s_mov_b32 m0, s7
	s_nop 0
	global_load_lds_dwordx4 v221, s[76:77]
	s_mov_b32 m0, vcc_hi
	s_nop 0
	s_mov_b32 vcc_hi, m0
	s_mov_b32 m0, vcc_lo
	s_nop 0
	global_load_lds_dwordx4 v222, s[60:61]
	s_mov_b32 m0, vcc_hi
	s_add_i32 vcc_lo, s7, 0x2000
	s_mov_b32 vcc_hi, m0
	s_mov_b32 m0, vcc_lo
	s_nop 0
	global_load_lds_dwordx4 v223, s[76:77]
	s_mov_b32 m0, vcc_hi
	s_addk_i32 s7, 0x6000
	s_mov_b32 s76, m0
	s_mov_b32 m0, s7
	s_nop 0
	global_load_lds_dwordx4 v224, s[60:61]
	s_mov_b32 m0, s76
	s_add_i32 s7, s68, s97
	s_cmp_ge_u32 s7, s94
	s_cselect_b64 s[60:61], -1, 0
	s_cmp_lt_u32 s7, s95
	s_cselect_b64 s[76:77], -1, 0
	s_and_b64 s[60:61], s[60:61], s[76:77]
	s_andn2_b64 vcc, exec, s[60:61]
	s_cbranch_vccnz .LBB0_382
	s_and_b32 s7, s6, 0x18000
	s_add_i32 s7, s65, s7
	s_mov_b32 s76, 0x20000
	v_add3_u32 v236, v129, v110, s76
	v_add_u32_e32 v130, s7, v111
	v_mov_b32_e32 v238, 0xf149f2ca
	v_add3_u32 v235, s7, v210, v205
	ds_read2_b32 v[228:229], v236 offset0:108 offset1:109
	ds_read2_b32 v[230:231], v236 offset0:110 offset1:111
	ds_read2_b32 v[104:105], v236 offset0:124 offset1:125
	ds_read2_b32 v[106:107], v236 offset0:126 offset1:127
	v_add_u32_e32 v131, v130, v204
	v_add_u32_e32 v130, v130, v203
	ds_read2_b32 v[140:141], v236 offset0:100 offset1:101
	ds_read2_b32 v[142:143], v236 offset0:102 offset1:103
	ds_read2_b32 v[144:145], v236 offset0:116 offset1:117
	ds_read2_b32 v[146:147], v236 offset0:118 offset1:119
	ds_read2_b32 v[148:149], v236 offset0:92 offset1:93
	ds_read2_b32 v[150:151], v236 offset0:94 offset1:95
	ds_read_b128 v[160:163], v130
	ds_read_b128 v[164:167], v131
	ds_read_b128 v[168:171], v130 offset:2048
	ds_read_b128 v[172:175], v131 offset:2048
	v_add_u32_e32 v232, v235, v206
	v_add_u32_e32 v233, v235, v207
	v_add_u32_e32 v234, v235, v208
	v_add_u32_e32 v235, v235, v209
	s_waitcnt lgkmcnt(4)
	v_cndmask_b32_e64 v100, v238, v228, s[8:9]
	v_cndmask_b32_e64 v101, v238, v229, s[10:11]
	v_cndmask_b32_e64 v102, v238, v230, s[12:13]
	v_cndmask_b32_e64 v103, v238, v231, s[14:15]
	v_cndmask_b32_e64 v104, v238, v104, s[16:17]
	v_cndmask_b32_e64 v105, v238, v105, s[18:19]
	v_cndmask_b32_e64 v106, v238, v106, s[20:21]
	v_cndmask_b32_e64 v107, v238, v107, s[22:23]
	ds_read_b128 v[176:179], v130 offset:1024
	ds_read_b128 v[180:183], v131 offset:1024
	ds_read_b128 v[184:187], v130 offset:3072
	ds_read_b128 v[188:191], v131 offset:3072
	s_waitcnt lgkmcnt(4)
	v_mfma_f32_16x16x32_bf16 v[100:103], v[160:163], v[4:7], v[100:103]
	v_mfma_f32_16x16x32_bf16 v[104:107], v[168:171], v[4:7], v[104:107]
	v_mfma_f32_16x16x32_bf16 v[100:103], v[164:167], v[8:11], v[100:103]
	v_mfma_f32_16x16x32_bf16 v[104:107], v[172:175], v[8:11], v[104:107]
	ds_read_b64_tr_b16 v[160:161], v232 offset:16384
	ds_read_b64_tr_b16 v[162:163], v232 offset:18432
	ds_read_b64_tr_b16 v[164:165], v233 offset:16384
	ds_read_b64_tr_b16 v[166:167], v233 offset:18432
	ds_read_b64_tr_b16 v[168:169], v234 offset:16384
	ds_read_b64_tr_b16 v[170:171], v234 offset:18432
	ds_read_b64_tr_b16 v[172:173], v235 offset:16384
	ds_read_b64_tr_b16 v[174:175], v235 offset:18432
	v_cndmask_b32_e64 v140, v238, v140, s[24:25]
	v_cndmask_b32_e64 v141, v238, v141, s[26:27]
	v_cndmask_b32_e64 v142, v238, v142, s[28:29]
	v_cndmask_b32_e64 v143, v238, v143, s[30:31]
	v_cndmask_b32_e64 v144, v238, v144, s[34:35]
	v_cndmask_b32_e64 v145, v238, v145, s[36:37]
	v_cndmask_b32_e64 v146, v238, v146, s[38:39]
	v_cndmask_b32_e64 v147, v238, v147, s[40:41]
	v_cndmask_b32_e64 v148, v238, v148, s[42:43]
	v_cndmask_b32_e64 v149, v238, v149, s[44:45]
	v_cndmask_b32_e64 v150, v238, v150, s[46:47]
	v_cndmask_b32_e64 v151, v238, v151, s[48:49]
	v_cndmask_b32_e64 v228, v238, v228, s[50:51]
	v_cndmask_b32_e64 v229, v238, v229, s[52:53]
	v_cndmask_b32_e64 v230, v238, v230, s[54:55]
	v_cndmask_b32_e64 v231, v238, v231, s[56:57]
	s_waitcnt lgkmcnt(8)
	v_mfma_f32_16x16x32_bf16 v[132:135], v[176:179], v[12:15], v[140:143]
	v_mfma_f32_16x16x32_bf16 v[136:139], v[184:187], v[12:15], v[144:147]
	v_mfma_f32_16x16x32_bf16 v[132:135], v[180:183], v[16:19], v[132:135]
	v_mfma_f32_16x16x32_bf16 v[136:139], v[188:191], v[16:19], v[136:139]
	v_exp_f32_e32 v100, v100
	v_exp_f32_e32 v101, v101
	v_exp_f32_e32 v102, v102
	v_exp_f32_e32 v103, v103
	v_exp_f32_e32 v104, v104
	v_exp_f32_e32 v105, v105
	v_pk_add_f32 v[242:243], v[100:101], v[102:103]
	v_exp_f32_e32 v106, v106
	v_exp_f32_e32 v107, v107
	v_pk_add_f32 v[242:243], v[242:243], v[104:105]
	v_cvt_pk_bf16_f32 v100, v100, v101
	v_cvt_pk_bf16_f32 v101, v102, v103
	v_cvt_pk_bf16_f32 v102, v104, v105
	v_cvt_pk_bf16_f32 v103, v106, v107
	v_pk_add_f32 v[242:243], v[242:243], v[106:107]
	v_add_f32_e32 v126, v126, v242
	v_add_f32_e32 v126, v126, v243
	s_waitcnt lgkmcnt(0)
; #define LAS __attribute__((address_space(3)))
; __device__ __forceinline__ s16x4 vtr(const LAS unsigned char* p) { return __builtin_bit_cast(s16x4, __builtin_amdgcn_ds_read_tr16_b64_v4i16((LAS v4i16_t*)p)); }
; __device__ __forceinline__ bf16x8 cat8(s16x4 a, s16x4 b) { return (bf16x8){a[0], a[1], a[2], a[3], b[0], b[1], b[2], b[3]}; }
; __device__ __forceinline__ bf16x8 pack8(const f32x4& a, const f32x4& b) { u32x4 w; w.x = pkbf(a[0], a[1]); w.y = pkbf(a[2], a[3]); w.z = pkbf(b[0], b[1]); w.w = pkbf(b[2], b[3]); return __builtin_bit_cast(bf16x8, w); }
; __device__ __forceinline__ void na_local_tile(f32x4 (&O)[4][4], float (&ls)[4], const bf16x8 (&qf)[4][2], float negb,
;                                               const LAS unsigned char* Kt, const LAS unsigned char* Vt, int lane, const LAS float* bias_row, bool rowvalid) {
;     ...
; #pragma unroll
;     for (int grp = 0; grp < 4; ++grp) {
;         const int kwin = grp == 0 ? 0 : (grp == 1 ? 8 : (grp == 2 ? 24 : 32));
;         f32x4 S[2];
; #pragma unroll
;         for (int k2 = 0; k2 < 2; ++k2) {
;             const bf16x8 kf0 = *(const LAS bf16x8*)(kb0 + (kwin + 16 * k2) * 128 + kx0), kf1 = *(const LAS bf16x8*)(kb0 + (kwin + 16 * k2) * 128 + kx1);
;             S[k2] = __builtin_amdgcn_mfma_f32_16x16x32_bf16(kf0, qf[grp][0], (f32x4){negb, negb, negb, negb}, 0, 0, 0);
;             S[k2] = __builtin_amdgcn_mfma_f32_16x16x32_bf16(kf1, qf[grp][1], S[k2], 0, 0, 0); }
;         const int c = 16 * grp + l15; const int c0 = rowvalid ? min(max(c - 8, 0), 48) : 4096;
;         const LAS float* bl = bias_row + (15 - c + 4 * g);
; #pragma unroll
;         for (int k2 = 0; k2 < 2; ++k2)
; #pragma unroll
;             for (int i = 0; i < 4; ++i) { const int kc = kwin + 16 * k2 + 4 * g + i; const float bias = bl[kwin + 16 * k2 + i];
;                 S[k2][i] = ((unsigned)(kc - c0) < 16u) ? S[k2][i] + bias : NEGBIG; }
;         ls[grp] += exp_step<2>(S);
;         const bf16x8 pf = pack8(S[0], S[1]);
; #pragma unroll
;         for (int db = 0; db < 4; ++db) {
;             const LAS unsigned char* va = vrow + ((db ^ swz) << 5) + kwin * 128;
;             const bf16x8 vf = cat8(vtr(va), vtr(va + 16 * 128));
;             O[grp][db] = __builtin_amdgcn_mfma_f32_16x16x32_bf16(vf, pf, O[grp][db], 0, 0, 0);
;         }
;         __builtin_amdgcn_sched_barrier(0x108);
	v_mfma_f32_16x16x32_bf16 v[48:51], v[160:163], v[100:103], v[48:51]
	v_mfma_f32_16x16x32_bf16 v[44:47], v[164:167], v[100:103], v[44:47]
	v_mfma_f32_16x16x32_bf16 v[40:43], v[168:171], v[100:103], v[40:43]
	v_mfma_f32_16x16x32_bf16 v[36:39], v[172:175], v[100:103], v[36:39]
	ds_read_b128 v[160:163], v130 offset:3072
	ds_read_b128 v[164:167], v131 offset:3072
	ds_read_b128 v[168:171], v130 offset:5120
	ds_read_b128 v[172:175], v131 offset:5120
	ds_read_b64_tr_b16 v[176:177], v232 offset:17408
	ds_read_b64_tr_b16 v[178:179], v232 offset:19456
	ds_read_b64_tr_b16 v[180:181], v233 offset:17408
	ds_read_b64_tr_b16 v[182:183], v233 offset:19456
	ds_read_b64_tr_b16 v[184:185], v234 offset:17408
	ds_read_b64_tr_b16 v[186:187], v234 offset:19456
	ds_read_b64_tr_b16 v[188:189], v235 offset:17408
	ds_read_b64_tr_b16 v[190:191], v235 offset:19456
	v_exp_f32_e32 v132, v132
	v_exp_f32_e32 v133, v133
	v_exp_f32_e32 v134, v134
	v_exp_f32_e32 v135, v135
	v_exp_f32_e32 v136, v136
	v_exp_f32_e32 v137, v137
	v_pk_add_f32 v[242:243], v[132:133], v[134:135]
	v_exp_f32_e32 v138, v138
	v_exp_f32_e32 v139, v139
	v_pk_add_f32 v[242:243], v[242:243], v[136:137]
	v_cvt_pk_bf16_f32 v132, v132, v133
	v_cvt_pk_bf16_f32 v133, v134, v135
	v_cvt_pk_bf16_f32 v134, v136, v137
	v_cvt_pk_bf16_f32 v135, v138, v139
	v_pk_add_f32 v[242:243], v[242:243], v[138:139]
	v_add_f32_e32 v127, v127, v242
	v_add_f32_e32 v127, v127, v243
	s_waitcnt lgkmcnt(0)
	v_mfma_f32_16x16x32_bf16 v[64:67], v[176:179], v[132:135], v[64:67]
	v_mfma_f32_16x16x32_bf16 v[60:63], v[180:183], v[132:135], v[60:63]
	v_mfma_f32_16x16x32_bf16 v[56:59], v[184:187], v[132:135], v[56:59]
	v_mfma_f32_16x16x32_bf16 v[52:55], v[188:191], v[132:135], v[52:55]
	v_mfma_f32_16x16x32_bf16 v[140:143], v[160:163], v[20:23], v[140:143]
	v_mfma_f32_16x16x32_bf16 v[144:147], v[168:171], v[20:23], v[144:147]
	v_mfma_f32_16x16x32_bf16 v[140:143], v[164:167], v[24:27], v[140:143]
	v_mfma_f32_16x16x32_bf16 v[144:147], v[172:175], v[24:27], v[144:147]
	ds_read_b128 v[176:179], v130 offset:4096
	ds_read_b128 v[180:183], v131 offset:4096
	ds_read_b128 v[184:187], v130 offset:6144
	ds_read_b128 v[188:191], v131 offset:6144
	ds_read_b64_tr_b16 v[160:161], v232 offset:19456
	ds_read_b64_tr_b16 v[162:163], v232 offset:21504
	ds_read_b64_tr_b16 v[164:165], v233 offset:19456
	ds_read_b64_tr_b16 v[166:167], v233 offset:21504
	ds_read_b64_tr_b16 v[168:169], v234 offset:19456
	ds_read_b64_tr_b16 v[170:171], v234 offset:21504
	ds_read_b64_tr_b16 v[172:173], v235 offset:19456
	ds_read_b64_tr_b16 v[174:175], v235 offset:21504
	v_exp_f32_e32 v140, v140
	v_exp_f32_e32 v141, v141
	v_exp_f32_e32 v142, v142
	v_exp_f32_e32 v143, v143
	v_exp_f32_e32 v144, v144
	v_exp_f32_e32 v145, v145
	v_pk_add_f32 v[242:243], v[140:141], v[142:143]
	v_exp_f32_e32 v146, v146
	v_exp_f32_e32 v147, v147
	v_pk_add_f32 v[242:243], v[242:243], v[144:145]
	v_cvt_pk_bf16_f32 v140, v140, v141
	v_cvt_pk_bf16_f32 v141, v142, v143
	v_cvt_pk_bf16_f32 v142, v144, v145
	v_cvt_pk_bf16_f32 v143, v146, v147
	v_pk_add_f32 v[242:243], v[242:243], v[146:147]
	v_add_f32_e32 v124, v124, v242
	v_add_f32_e32 v124, v124, v243
	s_waitcnt lgkmcnt(8)
	v_mfma_f32_16x16x32_bf16 v[148:151], v[176:179], v[28:31], v[148:151]
	v_mfma_f32_16x16x32_bf16 v[228:231], v[184:187], v[28:31], v[228:231]
	v_mfma_f32_16x16x32_bf16 v[148:151], v[180:183], v[32:35], v[148:151]
	v_mfma_f32_16x16x32_bf16 v[228:231], v[188:191], v[32:35], v[228:231]
	s_waitcnt lgkmcnt(0)
	v_mfma_f32_16x16x32_bf16 v[80:83], v[160:163], v[140:143], v[80:83]
	v_mfma_f32_16x16x32_bf16 v[76:79], v[164:167], v[140:143], v[76:79]
	v_mfma_f32_16x16x32_bf16 v[72:75], v[168:171], v[140:143], v[72:75]
	v_mfma_f32_16x16x32_bf16 v[68:71], v[172:175], v[140:143], v[68:71]
	ds_read_b64_tr_b16 v[176:177], v232 offset:20480
	ds_read_b64_tr_b16 v[178:179], v232 offset:22528
	ds_read_b64_tr_b16 v[180:181], v233 offset:20480
	ds_read_b64_tr_b16 v[182:183], v233 offset:22528
	ds_read_b64_tr_b16 v[184:185], v234 offset:20480
	ds_read_b64_tr_b16 v[186:187], v234 offset:22528
	ds_read_b64_tr_b16 v[188:189], v235 offset:20480
	ds_read_b64_tr_b16 v[190:191], v235 offset:22528
	v_exp_f32_e32 v148, v148
	v_exp_f32_e32 v149, v149
	v_exp_f32_e32 v150, v150
	v_exp_f32_e32 v151, v151
	v_exp_f32_e32 v228, v228
	v_exp_f32_e32 v229, v229
	v_pk_add_f32 v[242:243], v[148:149], v[150:151]
	v_exp_f32_e32 v230, v230
	v_exp_f32_e32 v231, v231
	v_pk_add_f32 v[242:243], v[242:243], v[228:229]
	v_cvt_pk_bf16_f32 v148, v148, v149
	v_cvt_pk_bf16_f32 v149, v150, v151
	v_cvt_pk_bf16_f32 v150, v228, v229
	v_cvt_pk_bf16_f32 v151, v230, v231
	v_pk_add_f32 v[242:243], v[242:243], v[230:231]
	v_add_f32_e32 v125, v125, v242
	v_add_f32_e32 v125, v125, v243
	s_waitcnt lgkmcnt(0)
	v_mfma_f32_16x16x32_bf16 v[84:87], v[176:179], v[148:151], v[84:87]
	v_mfma_f32_16x16x32_bf16 v[92:95], v[180:183], v[148:151], v[92:95]
	v_mfma_f32_16x16x32_bf16 v[88:91], v[184:187], v[148:151], v[88:91]
	v_mfma_f32_16x16x32_bf16 v[96:99], v[188:191], v[148:151], v[96:99]
	s_branch .LBB0_382
